# gemm8 k-loop: LDS-DMA of k-tile t+2 issued right after the mid-tile barrier (a full k-tile ahead), k-tile 1 staged in the prologue
# speedup vs baseline: 1.0068x; 1.0068x over previous
; DI int opaque_tid512() { int t = threadIdx.x; asm volatile("" : "+v"(t)); return t; }
; #define G8_STAGE(buf_, ap_, bp_) G8_STAGE_R(buf_, ap_, bp_, 0, 4)
; template <class Epi>
; DI void gemm8_tile(const bf16_t* __restrict__ Ab, int lda, const bf16_t* __restrict__ Bb, int ldb, int K, int brow, int bcol, const Epi epi,
;                    bool staged, bool has_next, const bf16_t* __restrict__ Abn, const bf16_t* __restrict__ Bbn) {
;   const int tid = opaque_tid512(), wid = tid >> 6, lane = tid & 63, wr = wid >> 2, wc = wid & 3, fr = lane & 15, fq = lane >> 4;
;   unsigned aoff[4], boff[4];
; #pragma unroll
;   for (int i = 0; i < 4; ++i) { int R, C; stage_rc2(wid * 1024 + i * 8192 + lane * 16, R, C); aoff[i] = (unsigned)R * (unsigned)lda + (unsigned)C; boff[i] = (unsigned)R * (unsigned)ldb + (unsigned)C; }
;     ...
;   f32x4 acc[8][4];
; #pragma unroll
;   for (int m = 0; m < 8; ++m)
; #pragma unroll
;     for (int n = 0; n < 4; ++n) acc[m][n] = (f32x4){0.f, 0.f, 0.f, 0.f};
;   const int nt = K / 64;
;   if (!staged) {
;     G8_STAGE(0, Ab, Bb);
;     asm volatile("s_waitcnt vmcnt(0)" ::: "memory");
;     __syncthreads();
;   }
;   for (int t = 0; t < nt; ++t) {
;     const int cur = t & 1;
;     const unsigned char* sa = smem + cur * G8_STAGE_B;
;     const unsigned char* sb = sa + G8_TILE_B;
; #pragma unroll
;     for (int ks = 0; ks < 2; ++ks) {
;       bf16x8 At[8], Bf[4];
;       Bf[0] = *(const bf16x8*)(sb + lds_byte2(wc * 64 + fr, ks * 32 + fq * 8));
;       At[0] = *(const bf16x8*)(sa + lds_byte2(wr * 128 + fr, ks * 32 + fq * 8));
; #pragma unroll
;       for (int n = 1; n < 4; ++n) Bf[n] = *(const bf16x8*)(sb + lds_byte2(wc * 64 + n * 16 + fr, ks * 32 + fq * 8));
; #pragma unroll
;       for (int m = 1; m < 8; ++m) At[m] = *(const bf16x8*)(sa + lds_byte2(wr * 128 + m * 16 + fr, ks * 32 + fq * 8));
.LBB0_461:
	v_readlane_b32 s0, v253, 4
	s_add_u32 s0, s0, s71
	v_readlane_b32 s1, v253, 5
	v_lshlrev_b64 v[212:213], 1, v[0:1]
	s_addc_u32 s1, s1, s78
	v_lshlrev_b64 v[214:215], 1, v[6:7]
	v_lshlrev_b64 v[146:147], 1, v[4:5]
	v_lshlrev_b64 v[148:149], 1, v[2:3]
	v_lshl_add_u64 v[130:131], s[0:1], 0, v[212:213]
	v_lshl_add_u64 v[132:133], s[0:1], 0, v[214:215]
	v_lshl_add_u64 v[134:135], s[0:1], 0, v[146:147]
	v_lshl_add_u64 v[136:137], s[0:1], 0, v[148:149]
	s_lshl_b32 s0, s59, 3
	s_add_i32 s0, s28, s0
	s_add_i32 s0, s0, s70
	s_lshl_b32 s1, s58, 3
	s_sub_i32 s0, s0, s1
	s_lshl_b32 s1, s0, 8
	s_mul_i32 s0, s0, 0x88000
	v_readlane_b32 s8, v253, 6
	v_and_b32_e32 v228, 63, v8
	v_and_b32_e32 v229, 3, v9
	v_ashrrev_i32_e32 v9, 8, v8
	v_and_b32_e32 v223, 15, v8
	v_and_b32_e32 v10, 48, v8
	v_lshlrev_b32_e32 v12, 2, v8
	v_lshlrev_b32_e32 v8, 6, v8
	s_mul_hi_i32 s1, s1, 0x880
	s_add_u32 s0, s8, s0
	v_readlane_b32 s8, v253, 7
	v_lshlrev_b32_e32 v11, 6, v223
	v_and_b32_e32 v12, 32, v12
	v_lshlrev_b32_e32 v153, 14, v9
	v_and_b32_e32 v8, 0x3c0, v8
	s_addc_u32 s1, s8, s1
	v_mov_b32_e32 v2, 0
	v_lshlrev_b32_e32 v151, 13, v229
	v_bitop3_b32 v152, v11, v12, v10 bitop3:0x36
	v_lshlrev_b32_e32 v230, 7, v9
	v_or_b32_e32 v150, 0x800, v153
	v_bitop3_b32 v158, v8, v12, v10 bitop3:0x36
	v_or_b32_e32 v167, 0x1000, v153
	v_or_b32_e32 v166, 0x1800, v153
	v_or_b32_e32 v165, 0x2000, v153
	v_or_b32_e32 v164, 0x2800, v153
	v_or_b32_e32 v163, 0x3000, v153
	v_or_b32_e32 v162, 0x3800, v153
	v_lshl_add_u64 v[138:139], s[0:1], 0, v[212:213]
	v_lshl_add_u64 v[140:141], s[0:1], 0, v[214:215]
	v_lshl_add_u64 v[142:143], s[0:1], 0, v[146:147]
	v_lshl_add_u64 v[144:145], s[0:1], 0, v[148:149]
	s_mov_b64 s[0:1], 0
	s_mov_b32 s14, 0
	v_mov_b32_e32 v3, v2
	v_mov_b32_e32 v4, v2
	v_mov_b32_e32 v5, v2
	v_mov_b32_e32 v6, v2
	v_mov_b32_e32 v7, v2
	v_mov_b32_e32 v8, v2
	v_mov_b32_e32 v9, v2
	v_mov_b32_e32 v10, v2
	v_mov_b32_e32 v11, v2
	v_mov_b32_e32 v12, v2
	v_mov_b32_e32 v13, v2
	v_mov_b32_e32 v14, v2
	v_mov_b32_e32 v15, v2
	v_mov_b32_e32 v16, v2
	v_mov_b32_e32 v17, v2
	v_mov_b32_e32 v18, v2
	v_mov_b32_e32 v19, v2
	v_mov_b32_e32 v20, v2
	v_mov_b32_e32 v21, v2
	v_mov_b32_e32 v22, v2
	v_mov_b32_e32 v23, v2
	v_mov_b32_e32 v24, v2
	v_mov_b32_e32 v25, v2
	v_mov_b32_e32 v26, v2
	v_mov_b32_e32 v27, v2
	v_mov_b32_e32 v28, v2
	v_mov_b32_e32 v29, v2
	v_mov_b32_e32 v30, v2
	v_mov_b32_e32 v31, v2
	v_mov_b32_e32 v32, v2
	v_mov_b32_e32 v33, v2
	v_mov_b32_e32 v34, v2
	v_mov_b32_e32 v35, v2
	v_mov_b32_e32 v36, v2
	v_mov_b32_e32 v37, v2
	v_mov_b32_e32 v38, v2
	v_mov_b32_e32 v39, v2
	v_mov_b32_e32 v40, v2
	v_mov_b32_e32 v41, v2
	v_mov_b32_e32 v42, v2
	v_mov_b32_e32 v43, v2
	v_mov_b32_e32 v44, v2
	v_mov_b32_e32 v45, v2
	v_mov_b32_e32 v46, v2
	v_mov_b32_e32 v47, v2
	v_mov_b32_e32 v48, v2
	v_mov_b32_e32 v49, v2
	v_mov_b32_e32 v50, v2
	v_mov_b32_e32 v51, v2
	v_mov_b32_e32 v52, v2
	v_mov_b32_e32 v53, v2
	v_mov_b32_e32 v54, v2
	v_mov_b32_e32 v55, v2
	v_mov_b32_e32 v56, v2
	v_mov_b32_e32 v57, v2
	v_mov_b32_e32 v58, v2
	v_mov_b32_e32 v59, v2
	v_mov_b32_e32 v60, v2
	v_mov_b32_e32 v61, v2
	v_mov_b32_e32 v62, v2
	v_mov_b32_e32 v63, v2
	v_mov_b32_e32 v64, v2
	v_mov_b32_e32 v65, v2
	s_waitcnt vmcnt(8)
	v_mov_b32_e32 v66, v2
	v_mov_b32_e32 v67, v2
	v_mov_b32_e32 v68, v2
	v_mov_b32_e32 v69, v2
	v_mov_b32_e32 v70, v2
	v_mov_b32_e32 v71, v2
	v_mov_b32_e32 v72, v2
	v_mov_b32_e32 v73, v2
	v_mov_b32_e32 v74, v2
	v_mov_b32_e32 v75, v2
	v_mov_b32_e32 v76, v2
	v_mov_b32_e32 v77, v2
	v_mov_b32_e32 v78, v2
	v_mov_b32_e32 v79, v2
	v_mov_b32_e32 v80, v2
	v_mov_b32_e32 v81, v2
	v_mov_b32_e32 v82, v2
	v_mov_b32_e32 v83, v2
	v_mov_b32_e32 v84, v2
	v_mov_b32_e32 v85, v2
	v_mov_b32_e32 v86, v2
	v_mov_b32_e32 v87, v2
	v_mov_b32_e32 v88, v2
	v_mov_b32_e32 v89, v2
	v_mov_b32_e32 v90, v2
	v_mov_b32_e32 v91, v2
	v_mov_b32_e32 v92, v2
	v_mov_b32_e32 v93, v2
	v_mov_b32_e32 v94, v2
	v_mov_b32_e32 v95, v2
	v_mov_b32_e32 v96, v2
	v_mov_b32_e32 v97, v2
	v_mov_b32_e32 v98, v2
	v_mov_b32_e32 v99, v2
	v_mov_b32_e32 v100, v2
	v_mov_b32_e32 v101, v2
	v_mov_b32_e32 v102, v2
	v_mov_b32_e32 v103, v2
	v_mov_b32_e32 v104, v2
	v_mov_b32_e32 v105, v2
	v_mov_b32_e32 v106, v2
	v_mov_b32_e32 v107, v2
	v_mov_b32_e32 v108, v2
	v_mov_b32_e32 v109, v2
	v_mov_b32_e32 v110, v2
	v_mov_b32_e32 v111, v2
	v_mov_b32_e32 v112, v2
	v_mov_b32_e32 v113, v2
	v_mov_b32_e32 v114, v2
	v_mov_b32_e32 v115, v2
	v_mov_b32_e32 v116, v2
	v_mov_b32_e32 v117, v2
	v_mov_b32_e32 v118, v2
	v_mov_b32_e32 v119, v2
	v_mov_b32_e32 v120, v2
	v_mov_b32_e32 v121, v2
	v_mov_b32_e32 v122, v2
	v_mov_b32_e32 v123, v2
	v_mov_b32_e32 v124, v2
	v_mov_b32_e32 v125, v2
	v_mov_b32_e32 v126, v2
	v_mov_b32_e32 v127, v2
	v_mov_b32_e32 v128, v2
	v_mov_b32_e32 v129, v2
	s_mov_b32 s56, 0
	v_add3_u32 v0, s56, v152, v151
	v_add3_u32 v159, s56, v152, v153
	v_add3_u32 v209, s56, v158, v167
	v_add3_u32 v240, s56, v158, v165
	v_add3_u32 v242, s56, v158, v163
	v_add3_u32 v208, s56, v158, v150
	v_add3_u32 v231, s56, v158, v166
	v_add3_u32 v241, s56, v158, v164
	v_add3_u32 v243, s56, v158, v162
	ds_read_b128 v[168:171], v0 offset:32768
	ds_read_b128 v[172:175], v0 offset:34816
	ds_read_b128 v[184:187], v159
	ds_read_b128 v[188:191], v208
	ds_read_b128 v[192:195], v209
	ds_read_b128 v[196:199], v231
	ds_read_b128 v[200:203], v240
	ds_read_b128 v[204:207], v241
	ds_read_b128 v[232:235], v242
	ds_read_b128 v[236:239], v243
	ds_read_b128 v[176:179], v0 offset:36864
	ds_read_b128 v[180:183], v0 offset:38912
	v_add_u32_e32 v244, 0x10000, v157
	s_nop 0
	v_readfirstlane_b32 s56, v244
	s_mov_b32 m0, s56
	v_lshl_add_u64 v[160:161], v[144:145], 0, s[0:1]
	global_load_lds_dwordx4 v[160:161], off
	s_add_u32 m0, s56, 0x8000
	v_lshl_add_u64 v[160:161], v[136:137], 0, s[0:1]
	global_load_lds_dwordx4 v[160:161], off
	s_add_u32 m0, s56, 0x2000
	v_lshl_add_u64 v[160:161], v[142:143], 0, s[0:1]
	global_load_lds_dwordx4 v[160:161], off
	s_add_u32 m0, s56, 0xa000
	v_lshl_add_u64 v[160:161], v[134:135], 0, s[0:1]
	global_load_lds_dwordx4 v[160:161], off
	s_add_u32 m0, s56, 0x4000
	v_lshl_add_u64 v[160:161], v[140:141], 0, s[0:1]
	global_load_lds_dwordx4 v[160:161], off
	s_add_u32 m0, s56, 0xc000
	v_lshl_add_u64 v[160:161], v[132:133], 0, s[0:1]
	global_load_lds_dwordx4 v[160:161], off
	s_add_u32 m0, s56, 0x6000
	v_lshl_add_u64 v[160:161], v[138:139], 0, s[0:1]
	global_load_lds_dwordx4 v[160:161], off
	s_add_u32 m0, s56, 0xe000
	v_lshl_add_u64 v[160:161], v[130:131], 0, s[0:1]
	global_load_lds_dwordx4 v[160:161], off
; #define MFMA16(a, b, c) __builtin_amdgcn_mfma_f32_16x16x32_bf16((a), (b), (c), 0, 0, 0)
; template <class Epi>
; DI void gemm8_tile(const bf16_t* __restrict__ Ab, int lda, const bf16_t* __restrict__ Bb, int ldb, int K, int brow, int bcol, const Epi epi,
;                    bool staged, bool has_next, const bf16_t* __restrict__ Abn, const bf16_t* __restrict__ Bbn) {
;     ...
;   for (int t = 0; t < nt; ++t) {
;     const int cur = t & 1;
;     const unsigned char* sa = smem + cur * G8_STAGE_B;
;     const unsigned char* sb = sa + G8_TILE_B;
; #pragma unroll
;     for (int ks = 0; ks < 2; ++ks) {
;       bf16x8 At[8], Bf[4];
;       Bf[0] = *(const bf16x8*)(sb + lds_byte2(wc * 64 + fr, ks * 32 + fq * 8));
;       At[0] = *(const bf16x8*)(sa + lds_byte2(wr * 128 + fr, ks * 32 + fq * 8));
; #pragma unroll
;       for (int n = 1; n < 4; ++n) Bf[n] = *(const bf16x8*)(sb + lds_byte2(wc * 64 + n * 16 + fr, ks * 32 + fq * 8));
; #pragma unroll
;       for (int m = 1; m < 8; ++m) At[m] = *(const bf16x8*)(sa + lds_byte2(wr * 128 + m * 16 + fr, ks * 32 + fq * 8));
;       {
;         __builtin_amdgcn_sched_barrier(0);
;         if (t + 1 < nt) { G8_STAGE_R(cur ^ 1, Ab + (t + 1) * 64, Bb + (t + 1) * 64, 2 * ks, 2 * ks + 2); }
;         else if (has_next) { G8_STAGE_R(0, Abn, Bbn, 2 * ks, 2 * ks + 2); }
;         __builtin_amdgcn_sched_barrier(0);
;       }
; #pragma unroll
;       for (int m = 0; m < 8; ++m)
; #pragma unroll
;         for (int n = 0; n < 4; ++n) acc[m][n] = MFMA16(At[m], Bf[n], acc[m][n]);
;       __builtin_amdgcn_sched_barrier(0);
;     }
;     asm volatile("s_waitcnt vmcnt(0)" ::: "memory");
;     __syncthreads();
.LBB0_462:
	s_and_b32 s15, s14, 0x10000
	s_xor_b32 s56, s15, 0x10000
	v_add_u32_e32 v244, s56, v157
	s_nop 0
	v_readfirstlane_b32 s15, v244
	s_waitcnt lgkmcnt(8)
	v_mfma_f32_16x16x32_bf16 v[126:129], v[184:187], v[168:171], v[126:129]
	v_mfma_f32_16x16x32_bf16 v[122:125], v[184:187], v[172:175], v[122:125]
	v_mfma_f32_16x16x32_bf16 v[110:113], v[188:191], v[168:171], v[110:113]
	v_mfma_f32_16x16x32_bf16 v[106:109], v[188:191], v[172:175], v[106:109]
	s_waitcnt lgkmcnt(6)
	v_mfma_f32_16x16x32_bf16 v[94:97], v[192:195], v[168:171], v[94:97]
	v_mfma_f32_16x16x32_bf16 v[90:93], v[192:195], v[172:175], v[90:93]
	v_mfma_f32_16x16x32_bf16 v[78:81], v[196:199], v[168:171], v[78:81]
	v_mfma_f32_16x16x32_bf16 v[74:77], v[196:199], v[172:175], v[74:77]
	s_waitcnt lgkmcnt(4)
	v_mfma_f32_16x16x32_bf16 v[62:65], v[200:203], v[168:171], v[62:65]
	v_mfma_f32_16x16x32_bf16 v[58:61], v[200:203], v[172:175], v[58:61]
	v_mfma_f32_16x16x32_bf16 v[46:49], v[204:207], v[168:171], v[46:49]
	v_mfma_f32_16x16x32_bf16 v[42:45], v[204:207], v[172:175], v[42:45]
	s_waitcnt lgkmcnt(2)
	v_mfma_f32_16x16x32_bf16 v[30:33], v[232:235], v[168:171], v[30:33]
	v_mfma_f32_16x16x32_bf16 v[26:29], v[232:235], v[172:175], v[26:29]
	v_mfma_f32_16x16x32_bf16 v[14:17], v[236:239], v[168:171], v[14:17]
	v_mfma_f32_16x16x32_bf16 v[10:13], v[236:239], v[172:175], v[10:13]
	ds_read_b128 v[168:171], v0 offset:33792
	ds_read_b128 v[172:175], v0 offset:35840
	s_waitcnt lgkmcnt(2)
	v_mfma_f32_16x16x32_bf16 v[118:121], v[184:187], v[176:179], v[118:121]
	v_mfma_f32_16x16x32_bf16 v[114:117], v[184:187], v[180:183], v[114:117]
	ds_read_b128 v[184:187], v159 offset:1024
	v_mfma_f32_16x16x32_bf16 v[102:105], v[188:191], v[176:179], v[102:105]
	v_mfma_f32_16x16x32_bf16 v[98:101], v[188:191], v[180:183], v[98:101]
	ds_read_b128 v[188:191], v208 offset:1024
	v_mfma_f32_16x16x32_bf16 v[86:89], v[192:195], v[176:179], v[86:89]
	v_mfma_f32_16x16x32_bf16 v[82:85], v[192:195], v[180:183], v[82:85]
	ds_read_b128 v[192:195], v209 offset:1024
	v_mfma_f32_16x16x32_bf16 v[70:73], v[196:199], v[176:179], v[70:73]
	v_mfma_f32_16x16x32_bf16 v[66:69], v[196:199], v[180:183], v[66:69]
	ds_read_b128 v[196:199], v231 offset:1024
	v_mfma_f32_16x16x32_bf16 v[54:57], v[200:203], v[176:179], v[54:57]
	v_mfma_f32_16x16x32_bf16 v[50:53], v[200:203], v[180:183], v[50:53]
	ds_read_b128 v[200:203], v240 offset:1024
	v_mfma_f32_16x16x32_bf16 v[38:41], v[204:207], v[176:179], v[38:41]
	v_mfma_f32_16x16x32_bf16 v[34:37], v[204:207], v[180:183], v[34:37]
	ds_read_b128 v[204:207], v241 offset:1024
	v_mfma_f32_16x16x32_bf16 v[22:25], v[232:235], v[176:179], v[22:25]
	v_mfma_f32_16x16x32_bf16 v[18:21], v[232:235], v[180:183], v[18:21]
	ds_read_b128 v[232:235], v242 offset:1024
	v_mfma_f32_16x16x32_bf16 v[6:9], v[236:239], v[176:179], v[6:9]
	v_mfma_f32_16x16x32_bf16 v[2:5], v[236:239], v[180:183], v[2:5]
	ds_read_b128 v[236:239], v243 offset:1024
	ds_read_b128 v[176:179], v0 offset:37888
	ds_read_b128 v[180:183], v0 offset:39936
	s_waitcnt lgkmcnt(8)
	v_mfma_f32_16x16x32_bf16 v[126:129], v[184:187], v[168:171], v[126:129]
	v_mfma_f32_16x16x32_bf16 v[122:125], v[184:187], v[172:175], v[122:125]
	v_add3_u32 v0, s56, v152, v151
	v_mfma_f32_16x16x32_bf16 v[110:113], v[188:191], v[168:171], v[110:113]
	v_mfma_f32_16x16x32_bf16 v[106:109], v[188:191], v[172:175], v[106:109]
	v_add3_u32 v159, s56, v152, v153
	s_waitcnt lgkmcnt(6)
	v_mfma_f32_16x16x32_bf16 v[94:97], v[192:195], v[168:171], v[94:97]
	v_mfma_f32_16x16x32_bf16 v[90:93], v[192:195], v[172:175], v[90:93]
	v_add3_u32 v209, s56, v158, v167
	v_mfma_f32_16x16x32_bf16 v[78:81], v[196:199], v[168:171], v[78:81]
	v_mfma_f32_16x16x32_bf16 v[74:77], v[196:199], v[172:175], v[74:77]
	v_add3_u32 v240, s56, v158, v165
	s_waitcnt lgkmcnt(4)
	v_mfma_f32_16x16x32_bf16 v[62:65], v[200:203], v[168:171], v[62:65]
	v_mfma_f32_16x16x32_bf16 v[58:61], v[200:203], v[172:175], v[58:61]
	v_add3_u32 v242, s56, v158, v163
	v_mfma_f32_16x16x32_bf16 v[46:49], v[204:207], v[168:171], v[46:49]
	v_mfma_f32_16x16x32_bf16 v[42:45], v[204:207], v[172:175], v[42:45]
	v_add3_u32 v208, s56, v158, v150
	s_waitcnt lgkmcnt(2)
	v_mfma_f32_16x16x32_bf16 v[30:33], v[232:235], v[168:171], v[30:33]
	v_mfma_f32_16x16x32_bf16 v[26:29], v[232:235], v[172:175], v[26:29]
	v_add3_u32 v231, s56, v158, v166
	v_mfma_f32_16x16x32_bf16 v[14:17], v[236:239], v[168:171], v[14:17]
	v_mfma_f32_16x16x32_bf16 v[10:13], v[236:239], v[172:175], v[10:13]
	v_add3_u32 v241, s56, v158, v164
	v_add3_u32 v243, s56, v158, v162
	s_waitcnt vmcnt(0) lgkmcnt(0)
	s_barrier
	s_add_u32 s0, s0, 0x80
	s_addc_u32 s1, s1, 0
	s_add_i32 s14, s14, 0x10000
	s_xor_b32 s56, s15, 0x10000
	s_cmpk_eq_i32 s0, 0x780
	s_cbranch_scc1 .Lg80_462_last
; #define MFMA16(a, b, c) __builtin_amdgcn_mfma_f32_16x16x32_bf16((a), (b), (c), 0, 0, 0)
; template <class Epi>
; DI void gemm8_tile(const bf16_t* __restrict__ Ab, int lda, const bf16_t* __restrict__ Bb, int ldb, int K, int brow, int bcol, const Epi epi,
;                    bool staged, bool has_next, const bf16_t* __restrict__ Abn, const bf16_t* __restrict__ Bbn) {
;     ...
;   for (int t = 0; t < nt; ++t) {
;     const int cur = t & 1;
;     const unsigned char* sa = smem + cur * G8_STAGE_B;
;     const unsigned char* sb = sa + G8_TILE_B;
; #pragma unroll
;     for (int ks = 0; ks < 2; ++ks) {
;       bf16x8 At[8], Bf[4];
;       Bf[0] = *(const bf16x8*)(sb + lds_byte2(wc * 64 + fr, ks * 32 + fq * 8));
;       At[0] = *(const bf16x8*)(sa + lds_byte2(wr * 128 + fr, ks * 32 + fq * 8));
; #pragma unroll
;       for (int n = 1; n < 4; ++n) Bf[n] = *(const bf16x8*)(sb + lds_byte2(wc * 64 + n * 16 + fr, ks * 32 + fq * 8));
; #pragma unroll
;       for (int m = 1; m < 8; ++m) At[m] = *(const bf16x8*)(sa + lds_byte2(wr * 128 + m * 16 + fr, ks * 32 + fq * 8));
;       {
;         __builtin_amdgcn_sched_barrier(0);
;         if (t + 1 < nt) { G8_STAGE_R(cur ^ 1, Ab + (t + 1) * 64, Bb + (t + 1) * 64, 2 * ks, 2 * ks + 2); }
;         else if (has_next) { G8_STAGE_R(0, Abn, Bbn, 2 * ks, 2 * ks + 2); }
;         __builtin_amdgcn_sched_barrier(0);
;       }
; #pragma unroll
;       for (int m = 0; m < 8; ++m)
; #pragma unroll
;         for (int n = 0; n < 4; ++n) acc[m][n] = MFMA16(At[m], Bf[n], acc[m][n]);
;       __builtin_amdgcn_sched_barrier(0);
;     }
;     asm volatile("s_waitcnt vmcnt(0)" ::: "memory");
;     __syncthreads();
;   }
	ds_read_b128 v[168:171], v0 offset:32768
	ds_read_b128 v[172:175], v0 offset:34816
	v_mfma_f32_16x16x32_bf16 v[118:121], v[184:187], v[176:179], v[118:121]
	v_mfma_f32_16x16x32_bf16 v[114:117], v[184:187], v[180:183], v[114:117]
	ds_read_b128 v[184:187], v159
	s_mov_b32 m0, s56
	v_lshl_add_u64 v[160:161], v[144:145], 0, s[0:1]
	global_load_lds_dwordx4 v[160:161], off
	v_mfma_f32_16x16x32_bf16 v[102:105], v[188:191], v[176:179], v[102:105]
	v_mfma_f32_16x16x32_bf16 v[98:101], v[188:191], v[180:183], v[98:101]
	ds_read_b128 v[188:191], v208
	s_add_u32 m0, s56, 0x8000
	v_lshl_add_u64 v[160:161], v[136:137], 0, s[0:1]
	global_load_lds_dwordx4 v[160:161], off
	v_mfma_f32_16x16x32_bf16 v[86:89], v[192:195], v[176:179], v[86:89]
	v_mfma_f32_16x16x32_bf16 v[82:85], v[192:195], v[180:183], v[82:85]
	ds_read_b128 v[192:195], v209
	s_add_u32 m0, s56, 0x2000
	v_lshl_add_u64 v[160:161], v[142:143], 0, s[0:1]
	global_load_lds_dwordx4 v[160:161], off
	v_mfma_f32_16x16x32_bf16 v[70:73], v[196:199], v[176:179], v[70:73]
	v_mfma_f32_16x16x32_bf16 v[66:69], v[196:199], v[180:183], v[66:69]
	ds_read_b128 v[196:199], v231
	s_add_u32 m0, s56, 0xa000
	v_lshl_add_u64 v[160:161], v[134:135], 0, s[0:1]
	global_load_lds_dwordx4 v[160:161], off
	v_mfma_f32_16x16x32_bf16 v[54:57], v[200:203], v[176:179], v[54:57]
	v_mfma_f32_16x16x32_bf16 v[50:53], v[200:203], v[180:183], v[50:53]
	ds_read_b128 v[200:203], v240
	s_add_u32 m0, s56, 0x4000
	v_lshl_add_u64 v[160:161], v[140:141], 0, s[0:1]
	global_load_lds_dwordx4 v[160:161], off
	v_mfma_f32_16x16x32_bf16 v[38:41], v[204:207], v[176:179], v[38:41]
	v_mfma_f32_16x16x32_bf16 v[34:37], v[204:207], v[180:183], v[34:37]
	ds_read_b128 v[204:207], v241
	s_add_u32 m0, s56, 0xc000
	v_lshl_add_u64 v[160:161], v[132:133], 0, s[0:1]
	global_load_lds_dwordx4 v[160:161], off
	v_mfma_f32_16x16x32_bf16 v[22:25], v[232:235], v[176:179], v[22:25]
	v_mfma_f32_16x16x32_bf16 v[18:21], v[232:235], v[180:183], v[18:21]
	ds_read_b128 v[232:235], v242
	s_add_u32 m0, s56, 0x6000
	v_lshl_add_u64 v[160:161], v[138:139], 0, s[0:1]
	global_load_lds_dwordx4 v[160:161], off
	v_mfma_f32_16x16x32_bf16 v[6:9], v[236:239], v[176:179], v[6:9]
	v_mfma_f32_16x16x32_bf16 v[2:5], v[236:239], v[180:183], v[2:5]
	ds_read_b128 v[236:239], v243
	s_add_u32 m0, s56, 0xe000
	v_lshl_add_u64 v[160:161], v[130:131], 0, s[0:1]
	global_load_lds_dwordx4 v[160:161], off
	ds_read_b128 v[176:179], v0 offset:36864
	ds_read_b128 v[180:183], v0 offset:38912
	s_branch .LBB0_462
.Lg80_462_last:
	ds_read_b128 v[168:171], v0 offset:32768
	ds_read_b128 v[172:175], v0 offset:34816
	v_mfma_f32_16x16x32_bf16 v[118:121], v[184:187], v[176:179], v[118:121]
	v_mfma_f32_16x16x32_bf16 v[114:117], v[184:187], v[180:183], v[114:117]
	ds_read_b128 v[184:187], v159
	v_mfma_f32_16x16x32_bf16 v[102:105], v[188:191], v[176:179], v[102:105]
	v_mfma_f32_16x16x32_bf16 v[98:101], v[188:191], v[180:183], v[98:101]
	ds_read_b128 v[188:191], v208
	v_mfma_f32_16x16x32_bf16 v[86:89], v[192:195], v[176:179], v[86:89]
	v_mfma_f32_16x16x32_bf16 v[82:85], v[192:195], v[180:183], v[82:85]
	ds_read_b128 v[192:195], v209
	v_mfma_f32_16x16x32_bf16 v[70:73], v[196:199], v[176:179], v[70:73]
	v_mfma_f32_16x16x32_bf16 v[66:69], v[196:199], v[180:183], v[66:69]
	ds_read_b128 v[196:199], v231
	v_mfma_f32_16x16x32_bf16 v[54:57], v[200:203], v[176:179], v[54:57]
	v_mfma_f32_16x16x32_bf16 v[50:53], v[200:203], v[180:183], v[50:53]
	ds_read_b128 v[200:203], v240
	v_mfma_f32_16x16x32_bf16 v[38:41], v[204:207], v[176:179], v[38:41]
	v_mfma_f32_16x16x32_bf16 v[34:37], v[204:207], v[180:183], v[34:37]
	ds_read_b128 v[204:207], v241
	v_mfma_f32_16x16x32_bf16 v[22:25], v[232:235], v[176:179], v[22:25]
	v_mfma_f32_16x16x32_bf16 v[18:21], v[232:235], v[180:183], v[18:21]
	ds_read_b128 v[232:235], v242
	v_mfma_f32_16x16x32_bf16 v[6:9], v[236:239], v[176:179], v[6:9]
	v_mfma_f32_16x16x32_bf16 v[2:5], v[236:239], v[180:183], v[2:5]
	ds_read_b128 v[236:239], v243
	ds_read_b128 v[176:179], v0 offset:36864
	ds_read_b128 v[180:183], v0 offset:38912
	s_waitcnt lgkmcnt(0)
	s_add_i32 s0, 0, 0x18000
	v_add_u32_e32 v0, s0, v152
	v_add_u32_e32 v0, v0, v151
	v_add_u32_e32 v130, s30, v152
	v_add_u32_e32 v206, v130, v153
	ds_read_b128 v[130:133], v0
	ds_read_b128 v[134:137], v0 offset:2048
	ds_read_b128 v[138:141], v0 offset:4096
	ds_read_b128 v[142:145], v0 offset:6144
	v_add_u32_e32 v170, s30, v158
	v_add_u32_e32 v208, v170, v167
	v_add_u32_e32 v231, v170, v165
	v_add_u32_e32 v233, v170, v163
	v_add_u32_e32 v207, v170, v150
	ds_read_b128 v[150:153], v206
	ds_read_b128 v[158:161], v207
	v_add_u32_e32 v209, v170, v166
	ds_read_b128 v[166:169], v208
	ds_read_b128 v[174:177], v209
	v_add_u32_e32 v232, v170, v164
	ds_read_b128 v[182:185], v231
	ds_read_b128 v[190:193], v232
	v_add_u32_e32 v234, v170, v162
	ds_read_b128 v[198:201], v233
	ds_read_b128 v[202:205], v234
	v_cndmask_b32_e64 v162, 0, 1, s[54:55]
	v_cmp_ne_u32_e64 s[0:1], 1, v162
	s_andn2_b64 vcc, exec, s[54:55]
	s_cbranch_vccnz .LBB0_465
	v_readfirstlane_b32 s14, v157
	v_lshl_add_u64 v[162:163], s[10:11], 0, v[148:149]
	s_mov_b32 m0, s14
	v_readfirstlane_b32 s14, v156
	v_lshl_add_u64 v[148:149], s[38:39], 0, v[148:149]
	global_load_lds_dwordx4 v[162:163], off
	s_mov_b32 m0, s14
	v_readfirstlane_b32 s14, v155
	v_lshl_add_u64 v[164:165], s[10:11], 0, v[146:147]
	global_load_lds_dwordx4 v[148:149], off
	s_mov_b32 m0, s14
	v_readfirstlane_b32 s14, v154
	v_lshl_add_u64 v[146:147], s[38:39], 0, v[146:147]
	global_load_lds_dwordx4 v[164:165], off
	s_mov_b32 m0, s14
	s_nop 0
	global_load_lds_dwordx4 v[146:147], off

; DI int opaque_tid512() { int t = threadIdx.x; asm volatile("" : "+v"(t)); return t; }
; #define G8_STAGE(buf_, ap_, bp_) G8_STAGE_R(buf_, ap_, bp_, 0, 4)
; template <class Epi>
; DI void gemm8_tile(const bf16_t* __restrict__ Ab, int lda, const bf16_t* __restrict__ Bb, int ldb, int K, int brow, int bcol, const Epi epi,
;                    bool staged, bool has_next, const bf16_t* __restrict__ Abn, const bf16_t* __restrict__ Bbn) {
;   const int tid = opaque_tid512(), wid = tid >> 6, lane = tid & 63, wr = wid >> 2, wc = wid & 3, fr = lane & 15, fq = lane >> 4;
;   unsigned aoff[4], boff[4];
; #pragma unroll
;   for (int i = 0; i < 4; ++i) { int R, C; stage_rc2(wid * 1024 + i * 8192 + lane * 16, R, C); aoff[i] = (unsigned)R * (unsigned)lda + (unsigned)C; boff[i] = (unsigned)R * (unsigned)ldb + (unsigned)C; }
;     ...
;   f32x4 acc[8][4];
; #pragma unroll
;   for (int m = 0; m < 8; ++m)
; #pragma unroll
;     for (int n = 0; n < 4; ++n) acc[m][n] = (f32x4){0.f, 0.f, 0.f, 0.f};
;   const int nt = K / 64;
;   if (!staged) {
;     G8_STAGE(0, Ab, Bb);
;     asm volatile("s_waitcnt vmcnt(0)" ::: "memory");
;     __syncthreads();
;   }
;   for (int t = 0; t < nt; ++t) {
;     const int cur = t & 1;
;     const unsigned char* sa = smem + cur * G8_STAGE_B;
;     const unsigned char* sb = sa + G8_TILE_B;
; #pragma unroll
;     for (int ks = 0; ks < 2; ++ks) {
;       bf16x8 At[8], Bf[4];
;       Bf[0] = *(const bf16x8*)(sb + lds_byte2(wc * 64 + fr, ks * 32 + fq * 8));
;       At[0] = *(const bf16x8*)(sa + lds_byte2(wr * 128 + fr, ks * 32 + fq * 8));
; #pragma unroll
;       for (int n = 1; n < 4; ++n) Bf[n] = *(const bf16x8*)(sb + lds_byte2(wc * 64 + n * 16 + fr, ks * 32 + fq * 8));
; #pragma unroll
;       for (int m = 1; m < 8; ++m) At[m] = *(const bf16x8*)(sa + lds_byte2(wr * 128 + m * 16 + fr, ks * 32 + fq * 8));
; template <class Epi>
; DI void gemm8_phase(int x, int j, const bf16_t* __restrict__ A, int lda, const bf16_t* __restrict__ Bt, int K, int N, int a_grp, const Epi epi) {
;     ...
;     const int brow = pm * 256, bcol = pn * 256;
;     const bf16_t* Ab = A + (size_t)brow * lda + (a_grp ? (bcol / a_grp) * K : 0);
;     const bf16_t* Bb = Bt + (size_t)bcol * ldb;
.LBB0_482:
	s_lshl_b32 s0, s71, 3
	s_add_i32 s0, s28, s0
	s_add_i32 s0, s0, s75
	s_lshl_b32 s1, s70, 3
	s_sub_i32 s0, s0, s1
	s_lshl_b32 s1, s0, 8
	s_mul_i32 s0, s0, 0x168000
	s_mul_hi_i32 s1, s1, 0x1680
	s_add_u32 s0, s91, s0
	v_lshlrev_b64 v[178:179], 1, v[4:5]
	s_addc_u32 s1, s72, s1
	v_lshlrev_b64 v[180:181], 1, v[2:3]
	v_lshlrev_b64 v[194:195], 1, v[6:7]
	v_lshlrev_b64 v[196:197], 1, v[0:1]
	v_and_b32_e32 v198, 15, v8
	v_lshl_add_u64 v[130:131], s[0:1], 0, v[178:179]
	v_lshl_add_u64 v[132:133], s[0:1], 0, v[180:181]
	v_lshl_add_u64 v[134:135], s[0:1], 0, v[194:195]
	v_lshl_add_u64 v[136:137], s[0:1], 0, v[196:197]
	v_readlane_b32 s0, v253, 8
	v_and_b32_e32 v206, 63, v8
	v_ashrrev_i32_e32 v10, 8, v8
	v_and_b32_e32 v204, 3, v9
	v_and_b32_e32 v9, 48, v8
	v_lshlrev_b32_e32 v199, 2, v198
	v_lshlrev_b32_e32 v8, 6, v8
	s_add_u32 s0, s0, s78
	v_readlane_b32 s1, v253, 9
	v_lshlrev_b32_e32 v11, 6, v198
	v_and_b32_e32 v12, 32, v199
	v_lshlrev_b32_e32 v156, 14, v10
	v_and_b32_e32 v8, 0x3c0, v8
	s_addc_u32 s1, s1, s79
	v_mov_b32_e32 v2, 0
	v_lshlrev_b32_e32 v153, 13, v204
	v_bitop3_b32 v155, v11, v12, v9 bitop3:0x36
	v_lshlrev_b32_e32 v205, 7, v10
	v_or_b32_e32 v150, 0x800, v156
	v_bitop3_b32 v154, v8, v12, v9 bitop3:0x36
	v_or_b32_e32 v152, 0x1000, v156
	v_or_b32_e32 v151, 0x1800, v156
	v_or_b32_e32 v149, 0x2000, v156
	v_or_b32_e32 v148, 0x2800, v156
	v_or_b32_e32 v147, 0x3000, v156
	v_or_b32_e32 v146, 0x3800, v156
	v_lshl_add_u64 v[138:139], s[0:1], 0, v[178:179]
	v_lshl_add_u64 v[140:141], s[0:1], 0, v[180:181]
	v_lshl_add_u64 v[142:143], s[0:1], 0, v[194:195]
	v_lshl_add_u64 v[144:145], s[0:1], 0, v[196:197]
	s_mov_b64 s[0:1], 0
	s_mov_b32 s56, 0
	v_mov_b32_e32 v3, v2
	v_mov_b32_e32 v4, v2
	v_mov_b32_e32 v5, v2
	v_mov_b32_e32 v6, v2
	v_mov_b32_e32 v7, v2
	v_mov_b32_e32 v8, v2
	v_mov_b32_e32 v9, v2
	v_mov_b32_e32 v10, v2
	v_mov_b32_e32 v11, v2
	v_mov_b32_e32 v12, v2
	v_mov_b32_e32 v13, v2
	v_mov_b32_e32 v14, v2
	v_mov_b32_e32 v15, v2
	v_mov_b32_e32 v16, v2
	v_mov_b32_e32 v17, v2
	v_mov_b32_e32 v18, v2
	v_mov_b32_e32 v19, v2
	v_mov_b32_e32 v20, v2
	v_mov_b32_e32 v21, v2
	v_mov_b32_e32 v22, v2
	v_mov_b32_e32 v23, v2
	v_mov_b32_e32 v24, v2
	v_mov_b32_e32 v25, v2
	v_mov_b32_e32 v26, v2
	v_mov_b32_e32 v27, v2
	v_mov_b32_e32 v28, v2
	v_mov_b32_e32 v29, v2
	v_mov_b32_e32 v30, v2
	v_mov_b32_e32 v31, v2
	v_mov_b32_e32 v32, v2
	v_mov_b32_e32 v33, v2
	v_mov_b32_e32 v34, v2
	v_mov_b32_e32 v35, v2
	v_mov_b32_e32 v36, v2
	v_mov_b32_e32 v37, v2
	v_mov_b32_e32 v38, v2
	v_mov_b32_e32 v39, v2
	v_mov_b32_e32 v40, v2
	v_mov_b32_e32 v41, v2
	v_mov_b32_e32 v42, v2
	v_mov_b32_e32 v43, v2
	v_mov_b32_e32 v44, v2
	v_mov_b32_e32 v45, v2
	v_mov_b32_e32 v46, v2
	v_mov_b32_e32 v47, v2
	v_mov_b32_e32 v48, v2
	v_mov_b32_e32 v49, v2
	v_mov_b32_e32 v50, v2
	v_mov_b32_e32 v51, v2
	v_mov_b32_e32 v52, v2
	v_mov_b32_e32 v53, v2
	v_mov_b32_e32 v54, v2
	v_mov_b32_e32 v55, v2
	v_mov_b32_e32 v56, v2
	v_mov_b32_e32 v57, v2
	v_mov_b32_e32 v58, v2
	v_mov_b32_e32 v59, v2
	v_mov_b32_e32 v60, v2
	v_mov_b32_e32 v61, v2
	v_mov_b32_e32 v62, v2
	v_mov_b32_e32 v63, v2
	v_mov_b32_e32 v64, v2
	v_mov_b32_e32 v65, v2
	s_waitcnt vmcnt(8)
	v_mov_b32_e32 v66, v2
	v_mov_b32_e32 v67, v2
	v_mov_b32_e32 v68, v2
	v_mov_b32_e32 v69, v2
	v_mov_b32_e32 v70, v2
	v_mov_b32_e32 v71, v2
	v_mov_b32_e32 v72, v2
	v_mov_b32_e32 v73, v2
	v_mov_b32_e32 v74, v2
	v_mov_b32_e32 v75, v2
	v_mov_b32_e32 v76, v2
	v_mov_b32_e32 v77, v2
	v_mov_b32_e32 v78, v2
	v_mov_b32_e32 v79, v2
	v_mov_b32_e32 v80, v2
	v_mov_b32_e32 v81, v2
	v_mov_b32_e32 v82, v2
	v_mov_b32_e32 v83, v2
	v_mov_b32_e32 v84, v2
	v_mov_b32_e32 v85, v2
	v_mov_b32_e32 v86, v2
	v_mov_b32_e32 v87, v2
	v_mov_b32_e32 v88, v2
	v_mov_b32_e32 v89, v2
	v_mov_b32_e32 v90, v2
	v_mov_b32_e32 v91, v2
	v_mov_b32_e32 v92, v2
	v_mov_b32_e32 v93, v2
	v_mov_b32_e32 v94, v2
	v_mov_b32_e32 v95, v2
	v_mov_b32_e32 v96, v2
	v_mov_b32_e32 v97, v2
	v_mov_b32_e32 v98, v2
	v_mov_b32_e32 v99, v2
	v_mov_b32_e32 v100, v2
	v_mov_b32_e32 v101, v2
	v_mov_b32_e32 v102, v2
	v_mov_b32_e32 v103, v2
	v_mov_b32_e32 v104, v2
	v_mov_b32_e32 v105, v2
	v_mov_b32_e32 v106, v2
	v_mov_b32_e32 v107, v2
	v_mov_b32_e32 v108, v2
	v_mov_b32_e32 v109, v2
	v_mov_b32_e32 v110, v2
	v_mov_b32_e32 v111, v2
	v_mov_b32_e32 v112, v2
	v_mov_b32_e32 v113, v2
	v_mov_b32_e32 v114, v2
	v_mov_b32_e32 v115, v2
	v_mov_b32_e32 v116, v2
	v_mov_b32_e32 v117, v2
	v_mov_b32_e32 v118, v2
	v_mov_b32_e32 v119, v2
	v_mov_b32_e32 v120, v2
	v_mov_b32_e32 v121, v2
	v_mov_b32_e32 v122, v2
	v_mov_b32_e32 v123, v2
	v_mov_b32_e32 v124, v2
	v_mov_b32_e32 v125, v2
	v_mov_b32_e32 v126, v2
	v_mov_b32_e32 v127, v2
	v_mov_b32_e32 v128, v2
	v_mov_b32_e32 v129, v2
	s_mov_b32 s58, 0
	v_add3_u32 v0, s58, v155, v153
	v_add3_u32 v157, s58, v155, v156
	v_add3_u32 v238, s58, v154, v152
	v_add3_u32 v240, s58, v154, v149
	v_add3_u32 v242, s58, v154, v147
	v_add3_u32 v207, s58, v154, v150
	v_add3_u32 v239, s58, v154, v151
	v_add3_u32 v241, s58, v154, v148
	v_add3_u32 v243, s58, v154, v146
	ds_read_b128 v[158:161], v0 offset:32768
	ds_read_b128 v[162:165], v0 offset:34816
	ds_read_b128 v[174:177], v157
	ds_read_b128 v[186:189], v207
	ds_read_b128 v[190:193], v238
	ds_read_b128 v[212:215], v239
	ds_read_b128 v[222:225], v240
	ds_read_b128 v[226:229], v241
	ds_read_b128 v[230:233], v242
	ds_read_b128 v[234:237], v243
	ds_read_b128 v[166:169], v0 offset:36864
	ds_read_b128 v[170:173], v0 offset:38912
	v_add_u32_e32 v244, 0x10000, v185
	s_nop 0
	v_readfirstlane_b32 s58, v244
	s_mov_b32 m0, s58
	v_lshl_add_u64 v[208:209], v[130:131], 0, s[0:1]
	global_load_lds_dwordx4 v[208:209], off
	s_add_u32 m0, s58, 0x8000
	v_lshl_add_u64 v[208:209], v[138:139], 0, s[0:1]
	global_load_lds_dwordx4 v[208:209], off
	s_add_u32 m0, s58, 0x2000
	v_lshl_add_u64 v[208:209], v[132:133], 0, s[0:1]
	global_load_lds_dwordx4 v[208:209], off
	s_add_u32 m0, s58, 0xa000
	v_lshl_add_u64 v[208:209], v[140:141], 0, s[0:1]
	global_load_lds_dwordx4 v[208:209], off
	s_add_u32 m0, s58, 0x4000
	v_lshl_add_u64 v[208:209], v[134:135], 0, s[0:1]
	global_load_lds_dwordx4 v[208:209], off
	s_add_u32 m0, s58, 0xc000
	v_lshl_add_u64 v[208:209], v[142:143], 0, s[0:1]
	global_load_lds_dwordx4 v[208:209], off
	s_add_u32 m0, s58, 0x6000
	v_lshl_add_u64 v[208:209], v[136:137], 0, s[0:1]
	global_load_lds_dwordx4 v[208:209], off
	s_add_u32 m0, s58, 0xe000
	v_lshl_add_u64 v[208:209], v[144:145], 0, s[0:1]
	global_load_lds_dwordx4 v[208:209], off
; #define MFMA16(a, b, c) __builtin_amdgcn_mfma_f32_16x16x32_bf16((a), (b), (c), 0, 0, 0)
; template <class Epi>
; DI void gemm8_tile(const bf16_t* __restrict__ Ab, int lda, const bf16_t* __restrict__ Bb, int ldb, int K, int brow, int bcol, const Epi epi,
;                    bool staged, bool has_next, const bf16_t* __restrict__ Abn, const bf16_t* __restrict__ Bbn) {
;     ...
;   for (int t = 0; t < nt; ++t) {
;     const int cur = t & 1;
;     const unsigned char* sa = smem + cur * G8_STAGE_B;
;     const unsigned char* sb = sa + G8_TILE_B;
; #pragma unroll
;     for (int ks = 0; ks < 2; ++ks) {
;       bf16x8 At[8], Bf[4];
;       Bf[0] = *(const bf16x8*)(sb + lds_byte2(wc * 64 + fr, ks * 32 + fq * 8));
;       At[0] = *(const bf16x8*)(sa + lds_byte2(wr * 128 + fr, ks * 32 + fq * 8));
; #pragma unroll
;       for (int n = 1; n < 4; ++n) Bf[n] = *(const bf16x8*)(sb + lds_byte2(wc * 64 + n * 16 + fr, ks * 32 + fq * 8));
; #pragma unroll
;       for (int m = 1; m < 8; ++m) At[m] = *(const bf16x8*)(sa + lds_byte2(wr * 128 + m * 16 + fr, ks * 32 + fq * 8));
;       {
;         __builtin_amdgcn_sched_barrier(0);
;         if (t + 1 < nt) { G8_STAGE_R(cur ^ 1, Ab + (t + 1) * 64, Bb + (t + 1) * 64, 2 * ks, 2 * ks + 2); }
;         else if (has_next) { G8_STAGE_R(0, Abn, Bbn, 2 * ks, 2 * ks + 2); }
;         __builtin_amdgcn_sched_barrier(0);
;       }
; #pragma unroll
;       for (int m = 0; m < 8; ++m)
; #pragma unroll
;         for (int n = 0; n < 4; ++n) acc[m][n] = MFMA16(At[m], Bf[n], acc[m][n]);
;       __builtin_amdgcn_sched_barrier(0);
;     }
;     asm volatile("s_waitcnt vmcnt(0)" ::: "memory");
;     __syncthreads();
.LBB0_483:
	s_and_b32 s57, s56, 0x10000
	s_xor_b32 s58, s57, 0x10000
	v_add_u32_e32 v244, s58, v185
	s_nop 0
	v_readfirstlane_b32 s57, v244
	s_waitcnt lgkmcnt(8)
	v_mfma_f32_16x16x32_bf16 v[126:129], v[174:177], v[158:161], v[126:129]
	v_mfma_f32_16x16x32_bf16 v[122:125], v[174:177], v[162:165], v[122:125]
	v_mfma_f32_16x16x32_bf16 v[110:113], v[186:189], v[158:161], v[110:113]
	v_mfma_f32_16x16x32_bf16 v[106:109], v[186:189], v[162:165], v[106:109]
	s_waitcnt lgkmcnt(6)
	v_mfma_f32_16x16x32_bf16 v[94:97], v[190:193], v[158:161], v[94:97]
	v_mfma_f32_16x16x32_bf16 v[90:93], v[190:193], v[162:165], v[90:93]
	v_mfma_f32_16x16x32_bf16 v[78:81], v[212:215], v[158:161], v[78:81]
	v_mfma_f32_16x16x32_bf16 v[74:77], v[212:215], v[162:165], v[74:77]
	s_waitcnt lgkmcnt(4)
	v_mfma_f32_16x16x32_bf16 v[62:65], v[222:225], v[158:161], v[62:65]
	v_mfma_f32_16x16x32_bf16 v[58:61], v[222:225], v[162:165], v[58:61]
	v_mfma_f32_16x16x32_bf16 v[46:49], v[226:229], v[158:161], v[46:49]
	v_mfma_f32_16x16x32_bf16 v[42:45], v[226:229], v[162:165], v[42:45]
	s_waitcnt lgkmcnt(2)
	v_mfma_f32_16x16x32_bf16 v[30:33], v[230:233], v[158:161], v[30:33]
	v_mfma_f32_16x16x32_bf16 v[26:29], v[230:233], v[162:165], v[26:29]
	v_mfma_f32_16x16x32_bf16 v[14:17], v[234:237], v[158:161], v[14:17]
	v_mfma_f32_16x16x32_bf16 v[10:13], v[234:237], v[162:165], v[10:13]
	ds_read_b128 v[158:161], v0 offset:33792
	ds_read_b128 v[162:165], v0 offset:35840
	s_waitcnt lgkmcnt(2)
	v_mfma_f32_16x16x32_bf16 v[118:121], v[174:177], v[166:169], v[118:121]
	v_mfma_f32_16x16x32_bf16 v[114:117], v[174:177], v[170:173], v[114:117]
	ds_read_b128 v[174:177], v157 offset:1024
	v_mfma_f32_16x16x32_bf16 v[102:105], v[186:189], v[166:169], v[102:105]
	v_mfma_f32_16x16x32_bf16 v[98:101], v[186:189], v[170:173], v[98:101]
	ds_read_b128 v[186:189], v207 offset:1024
	v_mfma_f32_16x16x32_bf16 v[86:89], v[190:193], v[166:169], v[86:89]
	v_mfma_f32_16x16x32_bf16 v[82:85], v[190:193], v[170:173], v[82:85]
	ds_read_b128 v[190:193], v238 offset:1024
	v_mfma_f32_16x16x32_bf16 v[70:73], v[212:215], v[166:169], v[70:73]
	v_mfma_f32_16x16x32_bf16 v[66:69], v[212:215], v[170:173], v[66:69]
	ds_read_b128 v[212:215], v239 offset:1024
	v_mfma_f32_16x16x32_bf16 v[54:57], v[222:225], v[166:169], v[54:57]
	v_mfma_f32_16x16x32_bf16 v[50:53], v[222:225], v[170:173], v[50:53]
	ds_read_b128 v[222:225], v240 offset:1024
	v_mfma_f32_16x16x32_bf16 v[38:41], v[226:229], v[166:169], v[38:41]
	v_mfma_f32_16x16x32_bf16 v[34:37], v[226:229], v[170:173], v[34:37]
	ds_read_b128 v[226:229], v241 offset:1024
	v_mfma_f32_16x16x32_bf16 v[22:25], v[230:233], v[166:169], v[22:25]
	v_mfma_f32_16x16x32_bf16 v[18:21], v[230:233], v[170:173], v[18:21]
	ds_read_b128 v[230:233], v242 offset:1024
	v_mfma_f32_16x16x32_bf16 v[6:9], v[234:237], v[166:169], v[6:9]
	v_mfma_f32_16x16x32_bf16 v[2:5], v[234:237], v[170:173], v[2:5]
	ds_read_b128 v[234:237], v243 offset:1024
	ds_read_b128 v[166:169], v0 offset:37888
	ds_read_b128 v[170:173], v0 offset:39936
	s_waitcnt lgkmcnt(8)
	v_mfma_f32_16x16x32_bf16 v[126:129], v[174:177], v[158:161], v[126:129]
	v_mfma_f32_16x16x32_bf16 v[122:125], v[174:177], v[162:165], v[122:125]
	v_add3_u32 v0, s58, v155, v153
	v_mfma_f32_16x16x32_bf16 v[110:113], v[186:189], v[158:161], v[110:113]
	v_mfma_f32_16x16x32_bf16 v[106:109], v[186:189], v[162:165], v[106:109]
	v_add3_u32 v157, s58, v155, v156
	s_waitcnt lgkmcnt(6)
	v_mfma_f32_16x16x32_bf16 v[94:97], v[190:193], v[158:161], v[94:97]
	v_mfma_f32_16x16x32_bf16 v[90:93], v[190:193], v[162:165], v[90:93]
	v_add3_u32 v238, s58, v154, v152
	v_mfma_f32_16x16x32_bf16 v[78:81], v[212:215], v[158:161], v[78:81]
	v_mfma_f32_16x16x32_bf16 v[74:77], v[212:215], v[162:165], v[74:77]
	v_add3_u32 v240, s58, v154, v149
	s_waitcnt lgkmcnt(4)
	v_mfma_f32_16x16x32_bf16 v[62:65], v[222:225], v[158:161], v[62:65]
	v_mfma_f32_16x16x32_bf16 v[58:61], v[222:225], v[162:165], v[58:61]
	v_add3_u32 v242, s58, v154, v147
	v_mfma_f32_16x16x32_bf16 v[46:49], v[226:229], v[158:161], v[46:49]
	v_mfma_f32_16x16x32_bf16 v[42:45], v[226:229], v[162:165], v[42:45]
	v_add3_u32 v207, s58, v154, v150
	s_waitcnt lgkmcnt(2)
	v_mfma_f32_16x16x32_bf16 v[30:33], v[230:233], v[158:161], v[30:33]
	v_mfma_f32_16x16x32_bf16 v[26:29], v[230:233], v[162:165], v[26:29]
	v_add3_u32 v239, s58, v154, v151
	v_mfma_f32_16x16x32_bf16 v[14:17], v[234:237], v[158:161], v[14:17]
	v_mfma_f32_16x16x32_bf16 v[10:13], v[234:237], v[162:165], v[10:13]
	v_add3_u32 v241, s58, v154, v148
	v_add3_u32 v243, s58, v154, v146
	s_waitcnt vmcnt(0) lgkmcnt(0)
	s_barrier
	s_add_u32 s0, s0, 0x80
	s_addc_u32 s1, s1, 0
	s_add_i32 s56, s56, 0x10000
	s_xor_b32 s58, s57, 0x10000
	s_cmpk_eq_i32 s0, 0x1580
	s_cbranch_scc1 .Lg80_483_last
; #define MFMA16(a, b, c) __builtin_amdgcn_mfma_f32_16x16x32_bf16((a), (b), (c), 0, 0, 0)
; template <class Epi>
; DI void gemm8_tile(const bf16_t* __restrict__ Ab, int lda, const bf16_t* __restrict__ Bb, int ldb, int K, int brow, int bcol, const Epi epi,
;                    bool staged, bool has_next, const bf16_t* __restrict__ Abn, const bf16_t* __restrict__ Bbn) {
;     ...
;   for (int t = 0; t < nt; ++t) {
;     const int cur = t & 1;
;     const unsigned char* sa = smem + cur * G8_STAGE_B;
;     const unsigned char* sb = sa + G8_TILE_B;
; #pragma unroll
;     for (int ks = 0; ks < 2; ++ks) {
;       bf16x8 At[8], Bf[4];
;       Bf[0] = *(const bf16x8*)(sb + lds_byte2(wc * 64 + fr, ks * 32 + fq * 8));
;       At[0] = *(const bf16x8*)(sa + lds_byte2(wr * 128 + fr, ks * 32 + fq * 8));
; #pragma unroll
;       for (int n = 1; n < 4; ++n) Bf[n] = *(const bf16x8*)(sb + lds_byte2(wc * 64 + n * 16 + fr, ks * 32 + fq * 8));
; #pragma unroll
;       for (int m = 1; m < 8; ++m) At[m] = *(const bf16x8*)(sa + lds_byte2(wr * 128 + m * 16 + fr, ks * 32 + fq * 8));
;       {
;         __builtin_amdgcn_sched_barrier(0);
;         if (t + 1 < nt) { G8_STAGE_R(cur ^ 1, Ab + (t + 1) * 64, Bb + (t + 1) * 64, 2 * ks, 2 * ks + 2); }
;         else if (has_next) { G8_STAGE_R(0, Abn, Bbn, 2 * ks, 2 * ks + 2); }
;         __builtin_amdgcn_sched_barrier(0);
;       }
; #pragma unroll
;       for (int m = 0; m < 8; ++m)
; #pragma unroll
;         for (int n = 0; n < 4; ++n) acc[m][n] = MFMA16(At[m], Bf[n], acc[m][n]);
;       __builtin_amdgcn_sched_barrier(0);
;     }
;     asm volatile("s_waitcnt vmcnt(0)" ::: "memory");
;     __syncthreads();
;   }
	ds_read_b128 v[158:161], v0 offset:32768
	ds_read_b128 v[162:165], v0 offset:34816
	v_mfma_f32_16x16x32_bf16 v[118:121], v[174:177], v[166:169], v[118:121]
	v_mfma_f32_16x16x32_bf16 v[114:117], v[174:177], v[170:173], v[114:117]
	ds_read_b128 v[174:177], v157
	s_mov_b32 m0, s58
	v_lshl_add_u64 v[208:209], v[130:131], 0, s[0:1]
	global_load_lds_dwordx4 v[208:209], off
	v_mfma_f32_16x16x32_bf16 v[102:105], v[186:189], v[166:169], v[102:105]
	v_mfma_f32_16x16x32_bf16 v[98:101], v[186:189], v[170:173], v[98:101]
	ds_read_b128 v[186:189], v207
	s_add_u32 m0, s58, 0x8000
	v_lshl_add_u64 v[208:209], v[138:139], 0, s[0:1]
	global_load_lds_dwordx4 v[208:209], off
	v_mfma_f32_16x16x32_bf16 v[86:89], v[190:193], v[166:169], v[86:89]
	v_mfma_f32_16x16x32_bf16 v[82:85], v[190:193], v[170:173], v[82:85]
	ds_read_b128 v[190:193], v238
	s_add_u32 m0, s58, 0x2000
	v_lshl_add_u64 v[208:209], v[132:133], 0, s[0:1]
	global_load_lds_dwordx4 v[208:209], off
	v_mfma_f32_16x16x32_bf16 v[70:73], v[212:215], v[166:169], v[70:73]
	v_mfma_f32_16x16x32_bf16 v[66:69], v[212:215], v[170:173], v[66:69]
	ds_read_b128 v[212:215], v239
	s_add_u32 m0, s58, 0xa000
	v_lshl_add_u64 v[208:209], v[140:141], 0, s[0:1]
	global_load_lds_dwordx4 v[208:209], off
	v_mfma_f32_16x16x32_bf16 v[54:57], v[222:225], v[166:169], v[54:57]
	v_mfma_f32_16x16x32_bf16 v[50:53], v[222:225], v[170:173], v[50:53]
	ds_read_b128 v[222:225], v240
	s_add_u32 m0, s58, 0x4000
	v_lshl_add_u64 v[208:209], v[134:135], 0, s[0:1]
	global_load_lds_dwordx4 v[208:209], off
	v_mfma_f32_16x16x32_bf16 v[38:41], v[226:229], v[166:169], v[38:41]
	v_mfma_f32_16x16x32_bf16 v[34:37], v[226:229], v[170:173], v[34:37]
	ds_read_b128 v[226:229], v241
	s_add_u32 m0, s58, 0xc000
	v_lshl_add_u64 v[208:209], v[142:143], 0, s[0:1]
	global_load_lds_dwordx4 v[208:209], off
	v_mfma_f32_16x16x32_bf16 v[22:25], v[230:233], v[166:169], v[22:25]
	v_mfma_f32_16x16x32_bf16 v[18:21], v[230:233], v[170:173], v[18:21]
	ds_read_b128 v[230:233], v242
	s_add_u32 m0, s58, 0x6000
	v_lshl_add_u64 v[208:209], v[136:137], 0, s[0:1]
	global_load_lds_dwordx4 v[208:209], off
	v_mfma_f32_16x16x32_bf16 v[6:9], v[234:237], v[166:169], v[6:9]
	v_mfma_f32_16x16x32_bf16 v[2:5], v[234:237], v[170:173], v[2:5]
	ds_read_b128 v[234:237], v243
	s_add_u32 m0, s58, 0xe000
	v_lshl_add_u64 v[208:209], v[144:145], 0, s[0:1]
	global_load_lds_dwordx4 v[208:209], off
	ds_read_b128 v[166:169], v0 offset:36864
	ds_read_b128 v[170:173], v0 offset:38912
	s_branch .LBB0_483
.Lg80_483_last:
	ds_read_b128 v[158:161], v0 offset:32768
	ds_read_b128 v[162:165], v0 offset:34816
	v_mfma_f32_16x16x32_bf16 v[118:121], v[174:177], v[166:169], v[118:121]
	v_mfma_f32_16x16x32_bf16 v[114:117], v[174:177], v[170:173], v[114:117]
	ds_read_b128 v[174:177], v157
	v_mfma_f32_16x16x32_bf16 v[102:105], v[186:189], v[166:169], v[102:105]
	v_mfma_f32_16x16x32_bf16 v[98:101], v[186:189], v[170:173], v[98:101]
	ds_read_b128 v[186:189], v207
	v_mfma_f32_16x16x32_bf16 v[86:89], v[190:193], v[166:169], v[86:89]
	v_mfma_f32_16x16x32_bf16 v[82:85], v[190:193], v[170:173], v[82:85]
	ds_read_b128 v[190:193], v238
	v_mfma_f32_16x16x32_bf16 v[70:73], v[212:215], v[166:169], v[70:73]
	v_mfma_f32_16x16x32_bf16 v[66:69], v[212:215], v[170:173], v[66:69]
	ds_read_b128 v[212:215], v239
	v_mfma_f32_16x16x32_bf16 v[54:57], v[222:225], v[166:169], v[54:57]
	v_mfma_f32_16x16x32_bf16 v[50:53], v[222:225], v[170:173], v[50:53]
	ds_read_b128 v[222:225], v240
	v_mfma_f32_16x16x32_bf16 v[38:41], v[226:229], v[166:169], v[38:41]
	v_mfma_f32_16x16x32_bf16 v[34:37], v[226:229], v[170:173], v[34:37]
	ds_read_b128 v[226:229], v241
	v_mfma_f32_16x16x32_bf16 v[22:25], v[230:233], v[166:169], v[22:25]
	v_mfma_f32_16x16x32_bf16 v[18:21], v[230:233], v[170:173], v[18:21]
	ds_read_b128 v[230:233], v242
	v_mfma_f32_16x16x32_bf16 v[6:9], v[234:237], v[166:169], v[6:9]
	v_mfma_f32_16x16x32_bf16 v[2:5], v[234:237], v[170:173], v[2:5]
	ds_read_b128 v[234:237], v243
	ds_read_b128 v[166:169], v0 offset:36864
	ds_read_b128 v[170:173], v0 offset:38912
	s_waitcnt lgkmcnt(0)
	s_add_i32 s0, 0, 0x18000
	v_add_u32_e32 v0, s0, v155
	v_add_u32_e32 v0, v0, v153
	v_add_u32_e32 v130, s30, v155
	v_add_u32_e32 v190, v130, v156
	ds_read_b128 v[130:133], v0
	ds_read_b128 v[134:137], v0 offset:2048
	ds_read_b128 v[138:141], v0 offset:4096
	ds_read_b128 v[142:145], v0 offset:6144
	v_add_u32_e32 v154, s30, v154
	v_add_u32_e32 v192, v154, v152
	v_add_u32_e32 v207, v154, v149
	v_add_u32_e32 v209, v154, v147
	v_add_u32_e32 v191, v154, v150
	ds_read_b128 v[174:177], v190
	ds_read_b128 v[166:169], v191
	v_add_u32_e32 v193, v154, v151
	ds_read_b128 v[170:173], v192
	ds_read_b128 v[158:161], v193
	v_add_u32_e32 v208, v154, v148
	ds_read_b128 v[162:165], v207
	ds_read_b128 v[150:153], v208
	v_add_u32_e32 v212, v154, v146
	ds_read_b128 v[154:157], v209
	ds_read_b128 v[146:149], v212
	v_cndmask_b32_e64 v186, 0, 1, s[14:15]
	v_cmp_ne_u32_e64 s[0:1], 1, v186
	s_andn2_b64 vcc, exec, s[14:15]
	s_cbranch_vccnz .LBB0_486
	v_readfirstlane_b32 s14, v185
	v_lshl_add_u64 v[188:189], s[10:11], 0, v[178:179]
	v_lshl_add_u64 v[178:179], s[8:9], 0, v[178:179]
	s_mov_b32 m0, s14
	v_readfirstlane_b32 s14, v184
	global_load_lds_dwordx4 v[178:179], off
	s_mov_b32 m0, s14
	v_readfirstlane_b32 s14, v183
	v_lshl_add_u64 v[186:187], s[10:11], 0, v[180:181]
	v_lshl_add_u64 v[180:181], s[8:9], 0, v[180:181]
	global_load_lds_dwordx4 v[188:189], off
	s_mov_b32 m0, s14
	v_readfirstlane_b32 s14, v182
	global_load_lds_dwordx4 v[180:181], off
	s_mov_b32 m0, s14
	s_nop 0
	global_load_lds_dwordx4 v[186:187], off

; DI int opaque_tid512() { int t = threadIdx.x; asm volatile("" : "+v"(t)); return t; }
; #define G8_STAGE(buf_, ap_, bp_) G8_STAGE_R(buf_, ap_, bp_, 0, 4)
; template <class Epi>
; DI void gemm8_tile(const bf16_t* __restrict__ Ab, int lda, const bf16_t* __restrict__ Bb, int ldb, int K, int brow, int bcol, const Epi epi,
;                    bool staged, bool has_next, const bf16_t* __restrict__ Abn, const bf16_t* __restrict__ Bbn) {
;   const int tid = opaque_tid512(), wid = tid >> 6, lane = tid & 63, wr = wid >> 2, wc = wid & 3, fr = lane & 15, fq = lane >> 4;
;   unsigned aoff[4], boff[4];
; #pragma unroll
;   for (int i = 0; i < 4; ++i) { int R, C; stage_rc2(wid * 1024 + i * 8192 + lane * 16, R, C); aoff[i] = (unsigned)R * (unsigned)lda + (unsigned)C; boff[i] = (unsigned)R * (unsigned)ldb + (unsigned)C; }
;     ...
;   f32x4 acc[8][4];
; #pragma unroll
;   for (int m = 0; m < 8; ++m)
; #pragma unroll
;     for (int n = 0; n < 4; ++n) acc[m][n] = (f32x4){0.f, 0.f, 0.f, 0.f};
;   const int nt = K / 64;
;   if (!staged) {
;     G8_STAGE(0, Ab, Bb);
;     asm volatile("s_waitcnt vmcnt(0)" ::: "memory");
;     __syncthreads();
;   }
;   for (int t = 0; t < nt; ++t) {
;     const int cur = t & 1;
;     const unsigned char* sa = smem + cur * G8_STAGE_B;
;     const unsigned char* sb = sa + G8_TILE_B;
; #pragma unroll
;     for (int ks = 0; ks < 2; ++ks) {
;       bf16x8 At[8], Bf[4];
;       Bf[0] = *(const bf16x8*)(sb + lds_byte2(wc * 64 + fr, ks * 32 + fq * 8));
;       At[0] = *(const bf16x8*)(sa + lds_byte2(wr * 128 + fr, ks * 32 + fq * 8));
; #pragma unroll
;       for (int n = 1; n < 4; ++n) Bf[n] = *(const bf16x8*)(sb + lds_byte2(wc * 64 + n * 16 + fr, ks * 32 + fq * 8));
; #pragma unroll
;       for (int m = 1; m < 8; ++m) At[m] = *(const bf16x8*)(sa + lds_byte2(wr * 128 + m * 16 + fr, ks * 32 + fq * 8));
; template <class Epi>
; DI void gemm8_phase(int x, int j, const bf16_t* __restrict__ A, int lda, const bf16_t* __restrict__ Bt, int K, int N, int a_grp, const Epi epi) {
;     ...
;     const int brow = pm * 256, bcol = pn * 256;
;     const bf16_t* Ab = A + (size_t)brow * lda + (a_grp ? (bcol / a_grp) * K : 0);
;     const bf16_t* Bb = Bt + (size_t)bcol * ldb;
.LBB0_649:
	s_add_u32 s0, s56, s79
	v_lshlrev_b64 v[190:191], 1, v[0:1]
	s_addc_u32 s1, s57, s81
	v_lshlrev_b64 v[192:193], 1, v[6:7]
	v_lshlrev_b64 v[178:179], 1, v[4:5]
	v_lshlrev_b64 v[180:181], 1, v[2:3]
	v_lshl_add_u64 v[130:131], s[0:1], 0, v[190:191]
	v_lshl_add_u64 v[132:133], s[0:1], 0, v[192:193]
	v_lshl_add_u64 v[134:135], s[0:1], 0, v[178:179]
	v_lshl_add_u64 v[136:137], s[0:1], 0, v[180:181]
	s_lshl_b32 s0, s59, 3
	s_add_i32 s0, s28, s0
	s_add_i32 s0, s0, s78
	s_lshl_b32 s1, s31, 3
	s_sub_i32 s0, s0, s1
	v_and_b32_e32 v200, 3, v8
	v_ashrrev_i32_e32 v8, 8, v195
	s_lshl_b32 s1, s0, 8
	s_mul_i32 s0, s0, 0x88000
	v_readlane_b32 s4, v253, 6
	v_and_b32_e32 v194, 15, v195
	v_lshlrev_b32_e32 v11, 2, v195
	v_lshlrev_b32_e32 v201, 7, v8
	v_lshlrev_b32_e32 v156, 14, v8
	v_lshlrev_b32_e32 v8, 6, v195
	s_mul_hi_i32 s1, s1, 0x880
	s_add_u32 s0, s4, s0
	v_readlane_b32 s4, v253, 7
	v_and_b32_e32 v9, 48, v195
	v_lshlrev_b32_e32 v10, 6, v194
	v_and_b32_e32 v11, 32, v11
	v_and_b32_e32 v8, 0x3c0, v8
	s_addc_u32 s1, s4, s1
	v_mov_b32_e32 v2, 0
	v_lshlrev_b32_e32 v153, 13, v200
	v_bitop3_b32 v155, v10, v11, v9 bitop3:0x36
	v_or_b32_e32 v150, 0x800, v156
	v_bitop3_b32 v154, v8, v11, v9 bitop3:0x36
	v_or_b32_e32 v152, 0x1000, v156
	v_or_b32_e32 v151, 0x1800, v156
	v_or_b32_e32 v149, 0x2000, v156
	v_or_b32_e32 v148, 0x2800, v156
	v_or_b32_e32 v147, 0x3000, v156
	v_or_b32_e32 v146, 0x3800, v156
	v_lshl_add_u64 v[138:139], s[0:1], 0, v[190:191]
	v_lshl_add_u64 v[140:141], s[0:1], 0, v[192:193]
	v_lshl_add_u64 v[142:143], s[0:1], 0, v[178:179]
	v_lshl_add_u64 v[144:145], s[0:1], 0, v[180:181]
	s_mov_b64 s[0:1], 0
	s_mov_b32 s14, 0
	v_mov_b32_e32 v3, v2
	v_mov_b32_e32 v4, v2
	v_mov_b32_e32 v5, v2
	v_mov_b32_e32 v6, v2
	v_mov_b32_e32 v7, v2
	v_mov_b32_e32 v8, v2
	v_mov_b32_e32 v9, v2
	v_mov_b32_e32 v10, v2
	v_mov_b32_e32 v11, v2
	v_mov_b32_e32 v12, v2
	v_mov_b32_e32 v13, v2
	v_mov_b32_e32 v14, v2
	v_mov_b32_e32 v15, v2
	v_mov_b32_e32 v16, v2
	v_mov_b32_e32 v17, v2
	v_mov_b32_e32 v18, v2
	v_mov_b32_e32 v19, v2
	v_mov_b32_e32 v20, v2
	v_mov_b32_e32 v21, v2
	v_mov_b32_e32 v22, v2
	v_mov_b32_e32 v23, v2
	v_mov_b32_e32 v24, v2
	v_mov_b32_e32 v25, v2
	v_mov_b32_e32 v26, v2
	v_mov_b32_e32 v27, v2
	v_mov_b32_e32 v28, v2
	v_mov_b32_e32 v29, v2
	v_mov_b32_e32 v30, v2
	v_mov_b32_e32 v31, v2
	v_mov_b32_e32 v32, v2
	v_mov_b32_e32 v33, v2
	v_mov_b32_e32 v34, v2
	v_mov_b32_e32 v35, v2
	v_mov_b32_e32 v36, v2
	v_mov_b32_e32 v37, v2
	v_mov_b32_e32 v38, v2
	v_mov_b32_e32 v39, v2
	v_mov_b32_e32 v40, v2
	v_mov_b32_e32 v41, v2
	v_mov_b32_e32 v42, v2
	v_mov_b32_e32 v43, v2
	v_mov_b32_e32 v44, v2
	v_mov_b32_e32 v45, v2
	v_mov_b32_e32 v46, v2
	v_mov_b32_e32 v47, v2
	v_mov_b32_e32 v48, v2
	v_mov_b32_e32 v49, v2
	v_mov_b32_e32 v50, v2
	v_mov_b32_e32 v51, v2
	v_mov_b32_e32 v52, v2
	v_mov_b32_e32 v53, v2
	v_mov_b32_e32 v54, v2
	v_mov_b32_e32 v55, v2
	v_mov_b32_e32 v56, v2
	v_mov_b32_e32 v57, v2
	v_mov_b32_e32 v58, v2
	v_mov_b32_e32 v59, v2
	v_mov_b32_e32 v60, v2
	v_mov_b32_e32 v61, v2
	v_mov_b32_e32 v62, v2
	v_mov_b32_e32 v63, v2
	v_mov_b32_e32 v64, v2
	v_mov_b32_e32 v65, v2
	s_waitcnt vmcnt(8)
	v_mov_b32_e32 v66, v2
	v_mov_b32_e32 v67, v2
	v_mov_b32_e32 v68, v2
	v_mov_b32_e32 v69, v2
	v_mov_b32_e32 v70, v2
	v_mov_b32_e32 v71, v2
	v_mov_b32_e32 v72, v2
	v_mov_b32_e32 v73, v2
	v_mov_b32_e32 v74, v2
	v_mov_b32_e32 v75, v2
	v_mov_b32_e32 v76, v2
	v_mov_b32_e32 v77, v2
	v_mov_b32_e32 v78, v2
	v_mov_b32_e32 v79, v2
	v_mov_b32_e32 v80, v2
	v_mov_b32_e32 v81, v2
	v_mov_b32_e32 v82, v2
	v_mov_b32_e32 v83, v2
	v_mov_b32_e32 v84, v2
	v_mov_b32_e32 v85, v2
	v_mov_b32_e32 v86, v2
	v_mov_b32_e32 v87, v2
	v_mov_b32_e32 v88, v2
	v_mov_b32_e32 v89, v2
	v_mov_b32_e32 v90, v2
	v_mov_b32_e32 v91, v2
	v_mov_b32_e32 v92, v2
	v_mov_b32_e32 v93, v2
	v_mov_b32_e32 v94, v2
	v_mov_b32_e32 v95, v2
	v_mov_b32_e32 v96, v2
	v_mov_b32_e32 v97, v2
	v_mov_b32_e32 v98, v2
	v_mov_b32_e32 v99, v2
	v_mov_b32_e32 v100, v2
	v_mov_b32_e32 v101, v2
	v_mov_b32_e32 v102, v2
	v_mov_b32_e32 v103, v2
	v_mov_b32_e32 v104, v2
	v_mov_b32_e32 v105, v2
	v_mov_b32_e32 v106, v2
	v_mov_b32_e32 v107, v2
	v_mov_b32_e32 v108, v2
	v_mov_b32_e32 v109, v2
	v_mov_b32_e32 v110, v2
	v_mov_b32_e32 v111, v2
	v_mov_b32_e32 v112, v2
	v_mov_b32_e32 v113, v2
	v_mov_b32_e32 v114, v2
	v_mov_b32_e32 v115, v2
	v_mov_b32_e32 v116, v2
	v_mov_b32_e32 v117, v2
	v_mov_b32_e32 v118, v2
	v_mov_b32_e32 v119, v2
	v_mov_b32_e32 v120, v2
	v_mov_b32_e32 v121, v2
	v_mov_b32_e32 v122, v2
	v_mov_b32_e32 v123, v2
	v_mov_b32_e32 v124, v2
	v_mov_b32_e32 v125, v2
	v_mov_b32_e32 v126, v2
	v_mov_b32_e32 v127, v2
	v_mov_b32_e32 v128, v2
	v_mov_b32_e32 v129, v2
	s_mov_b32 s31, 0
	v_add3_u32 v0, s31, v155, v153
	v_add3_u32 v157, s31, v155, v156
	v_add3_u32 v237, s31, v154, v152
	v_add3_u32 v239, s31, v154, v149
	v_add3_u32 v241, s31, v154, v147
	v_add3_u32 v236, s31, v154, v150
	v_add3_u32 v238, s31, v154, v151
	v_add3_u32 v240, s31, v154, v148
	v_add3_u32 v242, s31, v154, v146
	ds_read_b128 v[158:161], v0 offset:32768
	ds_read_b128 v[162:165], v0 offset:34816
	ds_read_b128 v[174:177], v157
	ds_read_b128 v[186:189], v236
	ds_read_b128 v[202:205], v237
	ds_read_b128 v[206:209], v238
	ds_read_b128 v[212:215], v239
	ds_read_b128 v[222:225], v240
	ds_read_b128 v[226:229], v241
	ds_read_b128 v[230:233], v242
	ds_read_b128 v[166:169], v0 offset:36864
	ds_read_b128 v[170:173], v0 offset:38912
	v_add_u32_e32 v243, 0x10000, v185
	s_nop 0
	v_readfirstlane_b32 s31, v243
	s_mov_b32 m0, s31
	v_lshl_add_u64 v[234:235], v[144:145], 0, s[0:1]
	global_load_lds_dwordx4 v[234:235], off
	s_add_u32 m0, s31, 0x8000
	v_lshl_add_u64 v[234:235], v[136:137], 0, s[0:1]
	global_load_lds_dwordx4 v[234:235], off
	s_add_u32 m0, s31, 0x2000
	v_lshl_add_u64 v[234:235], v[142:143], 0, s[0:1]
	global_load_lds_dwordx4 v[234:235], off
	s_add_u32 m0, s31, 0xa000
	v_lshl_add_u64 v[234:235], v[134:135], 0, s[0:1]
	global_load_lds_dwordx4 v[234:235], off
	s_add_u32 m0, s31, 0x4000
	v_lshl_add_u64 v[234:235], v[140:141], 0, s[0:1]
	global_load_lds_dwordx4 v[234:235], off
	s_add_u32 m0, s31, 0xc000
	v_lshl_add_u64 v[234:235], v[132:133], 0, s[0:1]
	global_load_lds_dwordx4 v[234:235], off
	s_add_u32 m0, s31, 0x6000
	v_lshl_add_u64 v[234:235], v[138:139], 0, s[0:1]
	global_load_lds_dwordx4 v[234:235], off
	s_add_u32 m0, s31, 0xe000
	v_lshl_add_u64 v[234:235], v[130:131], 0, s[0:1]
	global_load_lds_dwordx4 v[234:235], off
; #define MFMA16(a, b, c) __builtin_amdgcn_mfma_f32_16x16x32_bf16((a), (b), (c), 0, 0, 0)
; template <class Epi>
; DI void gemm8_tile(const bf16_t* __restrict__ Ab, int lda, const bf16_t* __restrict__ Bb, int ldb, int K, int brow, int bcol, const Epi epi,
;                    bool staged, bool has_next, const bf16_t* __restrict__ Abn, const bf16_t* __restrict__ Bbn) {
;     ...
;   for (int t = 0; t < nt; ++t) {
;     const int cur = t & 1;
;     const unsigned char* sa = smem + cur * G8_STAGE_B;
;     const unsigned char* sb = sa + G8_TILE_B;
; #pragma unroll
;     for (int ks = 0; ks < 2; ++ks) {
;       bf16x8 At[8], Bf[4];
;       Bf[0] = *(const bf16x8*)(sb + lds_byte2(wc * 64 + fr, ks * 32 + fq * 8));
;       At[0] = *(const bf16x8*)(sa + lds_byte2(wr * 128 + fr, ks * 32 + fq * 8));
; #pragma unroll
;       for (int n = 1; n < 4; ++n) Bf[n] = *(const bf16x8*)(sb + lds_byte2(wc * 64 + n * 16 + fr, ks * 32 + fq * 8));
; #pragma unroll
;       for (int m = 1; m < 8; ++m) At[m] = *(const bf16x8*)(sa + lds_byte2(wr * 128 + m * 16 + fr, ks * 32 + fq * 8));
;       {
;         __builtin_amdgcn_sched_barrier(0);
;         if (t + 1 < nt) { G8_STAGE_R(cur ^ 1, Ab + (t + 1) * 64, Bb + (t + 1) * 64, 2 * ks, 2 * ks + 2); }
;         else if (has_next) { G8_STAGE_R(0, Abn, Bbn, 2 * ks, 2 * ks + 2); }
;         __builtin_amdgcn_sched_barrier(0);
;       }
; #pragma unroll
;       for (int m = 0; m < 8; ++m)
; #pragma unroll
;         for (int n = 0; n < 4; ++n) acc[m][n] = MFMA16(At[m], Bf[n], acc[m][n]);
;       __builtin_amdgcn_sched_barrier(0);
;     }
;     asm volatile("s_waitcnt vmcnt(0)" ::: "memory");
;     __syncthreads();
.LBB0_650:
	s_and_b32 s15, s14, 0x10000
	s_xor_b32 s31, s15, 0x10000
	v_add_u32_e32 v243, s31, v185
	s_nop 0
	v_readfirstlane_b32 s15, v243
	s_waitcnt lgkmcnt(8)
	v_mfma_f32_16x16x32_bf16 v[126:129], v[174:177], v[158:161], v[126:129]
	v_mfma_f32_16x16x32_bf16 v[122:125], v[174:177], v[162:165], v[122:125]
	v_mfma_f32_16x16x32_bf16 v[110:113], v[186:189], v[158:161], v[110:113]
	v_mfma_f32_16x16x32_bf16 v[106:109], v[186:189], v[162:165], v[106:109]
	s_waitcnt lgkmcnt(6)
	v_mfma_f32_16x16x32_bf16 v[94:97], v[202:205], v[158:161], v[94:97]
	v_mfma_f32_16x16x32_bf16 v[90:93], v[202:205], v[162:165], v[90:93]
	v_mfma_f32_16x16x32_bf16 v[78:81], v[206:209], v[158:161], v[78:81]
	v_mfma_f32_16x16x32_bf16 v[74:77], v[206:209], v[162:165], v[74:77]
	s_waitcnt lgkmcnt(4)
	v_mfma_f32_16x16x32_bf16 v[62:65], v[212:215], v[158:161], v[62:65]
	v_mfma_f32_16x16x32_bf16 v[58:61], v[212:215], v[162:165], v[58:61]
	v_mfma_f32_16x16x32_bf16 v[46:49], v[222:225], v[158:161], v[46:49]
	v_mfma_f32_16x16x32_bf16 v[42:45], v[222:225], v[162:165], v[42:45]
	s_waitcnt lgkmcnt(2)
	v_mfma_f32_16x16x32_bf16 v[30:33], v[226:229], v[158:161], v[30:33]
	v_mfma_f32_16x16x32_bf16 v[26:29], v[226:229], v[162:165], v[26:29]
	v_mfma_f32_16x16x32_bf16 v[14:17], v[230:233], v[158:161], v[14:17]
	v_mfma_f32_16x16x32_bf16 v[10:13], v[230:233], v[162:165], v[10:13]
	ds_read_b128 v[158:161], v0 offset:33792
	ds_read_b128 v[162:165], v0 offset:35840
	s_waitcnt lgkmcnt(2)
	v_mfma_f32_16x16x32_bf16 v[118:121], v[174:177], v[166:169], v[118:121]
	v_mfma_f32_16x16x32_bf16 v[114:117], v[174:177], v[170:173], v[114:117]
	ds_read_b128 v[174:177], v157 offset:1024
	v_mfma_f32_16x16x32_bf16 v[102:105], v[186:189], v[166:169], v[102:105]
	v_mfma_f32_16x16x32_bf16 v[98:101], v[186:189], v[170:173], v[98:101]
	ds_read_b128 v[186:189], v236 offset:1024
	v_mfma_f32_16x16x32_bf16 v[86:89], v[202:205], v[166:169], v[86:89]
	v_mfma_f32_16x16x32_bf16 v[82:85], v[202:205], v[170:173], v[82:85]
	ds_read_b128 v[202:205], v237 offset:1024
	v_mfma_f32_16x16x32_bf16 v[70:73], v[206:209], v[166:169], v[70:73]
	v_mfma_f32_16x16x32_bf16 v[66:69], v[206:209], v[170:173], v[66:69]
	ds_read_b128 v[206:209], v238 offset:1024
	v_mfma_f32_16x16x32_bf16 v[54:57], v[212:215], v[166:169], v[54:57]
	v_mfma_f32_16x16x32_bf16 v[50:53], v[212:215], v[170:173], v[50:53]
	ds_read_b128 v[212:215], v239 offset:1024
	v_mfma_f32_16x16x32_bf16 v[38:41], v[222:225], v[166:169], v[38:41]
	v_mfma_f32_16x16x32_bf16 v[34:37], v[222:225], v[170:173], v[34:37]
	ds_read_b128 v[222:225], v240 offset:1024
	v_mfma_f32_16x16x32_bf16 v[22:25], v[226:229], v[166:169], v[22:25]
	v_mfma_f32_16x16x32_bf16 v[18:21], v[226:229], v[170:173], v[18:21]
	ds_read_b128 v[226:229], v241 offset:1024
	v_mfma_f32_16x16x32_bf16 v[6:9], v[230:233], v[166:169], v[6:9]
	v_mfma_f32_16x16x32_bf16 v[2:5], v[230:233], v[170:173], v[2:5]
	ds_read_b128 v[230:233], v242 offset:1024
	ds_read_b128 v[166:169], v0 offset:37888
	ds_read_b128 v[170:173], v0 offset:39936
	s_waitcnt lgkmcnt(8)
	v_mfma_f32_16x16x32_bf16 v[126:129], v[174:177], v[158:161], v[126:129]
	v_mfma_f32_16x16x32_bf16 v[122:125], v[174:177], v[162:165], v[122:125]
	v_add3_u32 v0, s31, v155, v153
	v_mfma_f32_16x16x32_bf16 v[110:113], v[186:189], v[158:161], v[110:113]
	v_mfma_f32_16x16x32_bf16 v[106:109], v[186:189], v[162:165], v[106:109]
	v_add3_u32 v157, s31, v155, v156
	s_waitcnt lgkmcnt(6)
	v_mfma_f32_16x16x32_bf16 v[94:97], v[202:205], v[158:161], v[94:97]
	v_mfma_f32_16x16x32_bf16 v[90:93], v[202:205], v[162:165], v[90:93]
	v_add3_u32 v237, s31, v154, v152
	v_mfma_f32_16x16x32_bf16 v[78:81], v[206:209], v[158:161], v[78:81]
	v_mfma_f32_16x16x32_bf16 v[74:77], v[206:209], v[162:165], v[74:77]
	v_add3_u32 v239, s31, v154, v149
	s_waitcnt lgkmcnt(4)
	v_mfma_f32_16x16x32_bf16 v[62:65], v[212:215], v[158:161], v[62:65]
	v_mfma_f32_16x16x32_bf16 v[58:61], v[212:215], v[162:165], v[58:61]
	v_add3_u32 v241, s31, v154, v147
	v_mfma_f32_16x16x32_bf16 v[46:49], v[222:225], v[158:161], v[46:49]
	v_mfma_f32_16x16x32_bf16 v[42:45], v[222:225], v[162:165], v[42:45]
	v_add3_u32 v236, s31, v154, v150
	s_waitcnt lgkmcnt(2)
	v_mfma_f32_16x16x32_bf16 v[30:33], v[226:229], v[158:161], v[30:33]
	v_mfma_f32_16x16x32_bf16 v[26:29], v[226:229], v[162:165], v[26:29]
	v_add3_u32 v238, s31, v154, v151
	v_mfma_f32_16x16x32_bf16 v[14:17], v[230:233], v[158:161], v[14:17]
	v_mfma_f32_16x16x32_bf16 v[10:13], v[230:233], v[162:165], v[10:13]
	v_add3_u32 v240, s31, v154, v148
	v_add3_u32 v242, s31, v154, v146
	s_waitcnt vmcnt(0) lgkmcnt(0)
	s_barrier
	s_add_u32 s0, s0, 0x80
	s_addc_u32 s1, s1, 0
	s_add_i32 s14, s14, 0x10000
	s_xor_b32 s31, s15, 0x10000
	s_cmpk_eq_i32 s0, 0x780
	s_cbranch_scc1 .Lg80_650_last
; #define MFMA16(a, b, c) __builtin_amdgcn_mfma_f32_16x16x32_bf16((a), (b), (c), 0, 0, 0)
; template <class Epi>
; DI void gemm8_tile(const bf16_t* __restrict__ Ab, int lda, const bf16_t* __restrict__ Bb, int ldb, int K, int brow, int bcol, const Epi epi,
;                    bool staged, bool has_next, const bf16_t* __restrict__ Abn, const bf16_t* __restrict__ Bbn) {
;     ...
;   for (int t = 0; t < nt; ++t) {
;     const int cur = t & 1;
;     const unsigned char* sa = smem + cur * G8_STAGE_B;
;     const unsigned char* sb = sa + G8_TILE_B;
; #pragma unroll
;     for (int ks = 0; ks < 2; ++ks) {
;       bf16x8 At[8], Bf[4];
;       Bf[0] = *(const bf16x8*)(sb + lds_byte2(wc * 64 + fr, ks * 32 + fq * 8));
;       At[0] = *(const bf16x8*)(sa + lds_byte2(wr * 128 + fr, ks * 32 + fq * 8));
; #pragma unroll
;       for (int n = 1; n < 4; ++n) Bf[n] = *(const bf16x8*)(sb + lds_byte2(wc * 64 + n * 16 + fr, ks * 32 + fq * 8));
; #pragma unroll
;       for (int m = 1; m < 8; ++m) At[m] = *(const bf16x8*)(sa + lds_byte2(wr * 128 + m * 16 + fr, ks * 32 + fq * 8));
;       {
;         __builtin_amdgcn_sched_barrier(0);
;         if (t + 1 < nt) { G8_STAGE_R(cur ^ 1, Ab + (t + 1) * 64, Bb + (t + 1) * 64, 2 * ks, 2 * ks + 2); }
;         else if (has_next) { G8_STAGE_R(0, Abn, Bbn, 2 * ks, 2 * ks + 2); }
;         __builtin_amdgcn_sched_barrier(0);
;       }
; #pragma unroll
;       for (int m = 0; m < 8; ++m)
; #pragma unroll
;         for (int n = 0; n < 4; ++n) acc[m][n] = MFMA16(At[m], Bf[n], acc[m][n]);
;       __builtin_amdgcn_sched_barrier(0);
;     }
;     asm volatile("s_waitcnt vmcnt(0)" ::: "memory");
;     __syncthreads();
;   }
	ds_read_b128 v[158:161], v0 offset:32768
	ds_read_b128 v[162:165], v0 offset:34816
	v_mfma_f32_16x16x32_bf16 v[118:121], v[174:177], v[166:169], v[118:121]
	v_mfma_f32_16x16x32_bf16 v[114:117], v[174:177], v[170:173], v[114:117]
	ds_read_b128 v[174:177], v157
	s_mov_b32 m0, s31
	v_lshl_add_u64 v[234:235], v[144:145], 0, s[0:1]
	global_load_lds_dwordx4 v[234:235], off
	v_mfma_f32_16x16x32_bf16 v[102:105], v[186:189], v[166:169], v[102:105]
	v_mfma_f32_16x16x32_bf16 v[98:101], v[186:189], v[170:173], v[98:101]
	ds_read_b128 v[186:189], v236
	s_add_u32 m0, s31, 0x8000
	v_lshl_add_u64 v[234:235], v[136:137], 0, s[0:1]
	global_load_lds_dwordx4 v[234:235], off
	v_mfma_f32_16x16x32_bf16 v[86:89], v[202:205], v[166:169], v[86:89]
	v_mfma_f32_16x16x32_bf16 v[82:85], v[202:205], v[170:173], v[82:85]
	ds_read_b128 v[202:205], v237
	s_add_u32 m0, s31, 0x2000
	v_lshl_add_u64 v[234:235], v[142:143], 0, s[0:1]
	global_load_lds_dwordx4 v[234:235], off
	v_mfma_f32_16x16x32_bf16 v[70:73], v[206:209], v[166:169], v[70:73]
	v_mfma_f32_16x16x32_bf16 v[66:69], v[206:209], v[170:173], v[66:69]
	ds_read_b128 v[206:209], v238
	s_add_u32 m0, s31, 0xa000
	v_lshl_add_u64 v[234:235], v[134:135], 0, s[0:1]
	global_load_lds_dwordx4 v[234:235], off
	v_mfma_f32_16x16x32_bf16 v[54:57], v[212:215], v[166:169], v[54:57]
	v_mfma_f32_16x16x32_bf16 v[50:53], v[212:215], v[170:173], v[50:53]
	ds_read_b128 v[212:215], v239
	s_add_u32 m0, s31, 0x4000
	v_lshl_add_u64 v[234:235], v[140:141], 0, s[0:1]
	global_load_lds_dwordx4 v[234:235], off
	v_mfma_f32_16x16x32_bf16 v[38:41], v[222:225], v[166:169], v[38:41]
	v_mfma_f32_16x16x32_bf16 v[34:37], v[222:225], v[170:173], v[34:37]
	ds_read_b128 v[222:225], v240
	s_add_u32 m0, s31, 0xc000
	v_lshl_add_u64 v[234:235], v[132:133], 0, s[0:1]
	global_load_lds_dwordx4 v[234:235], off
	v_mfma_f32_16x16x32_bf16 v[22:25], v[226:229], v[166:169], v[22:25]
	v_mfma_f32_16x16x32_bf16 v[18:21], v[226:229], v[170:173], v[18:21]
	ds_read_b128 v[226:229], v241
	s_add_u32 m0, s31, 0x6000
	v_lshl_add_u64 v[234:235], v[138:139], 0, s[0:1]
	global_load_lds_dwordx4 v[234:235], off
	v_mfma_f32_16x16x32_bf16 v[6:9], v[230:233], v[166:169], v[6:9]
	v_mfma_f32_16x16x32_bf16 v[2:5], v[230:233], v[170:173], v[2:5]
	ds_read_b128 v[230:233], v242
	s_add_u32 m0, s31, 0xe000
	v_lshl_add_u64 v[234:235], v[130:131], 0, s[0:1]
	global_load_lds_dwordx4 v[234:235], off
	ds_read_b128 v[166:169], v0 offset:36864
	ds_read_b128 v[170:173], v0 offset:38912
	s_branch .LBB0_650
.Lg80_650_last:
	ds_read_b128 v[158:161], v0 offset:32768
	ds_read_b128 v[162:165], v0 offset:34816
	v_mfma_f32_16x16x32_bf16 v[118:121], v[174:177], v[166:169], v[118:121]
	v_mfma_f32_16x16x32_bf16 v[114:117], v[174:177], v[170:173], v[114:117]
	ds_read_b128 v[174:177], v157
	v_mfma_f32_16x16x32_bf16 v[102:105], v[186:189], v[166:169], v[102:105]
	v_mfma_f32_16x16x32_bf16 v[98:101], v[186:189], v[170:173], v[98:101]
	ds_read_b128 v[186:189], v236
	v_mfma_f32_16x16x32_bf16 v[86:89], v[202:205], v[166:169], v[86:89]
	v_mfma_f32_16x16x32_bf16 v[82:85], v[202:205], v[170:173], v[82:85]
	ds_read_b128 v[202:205], v237
	v_mfma_f32_16x16x32_bf16 v[70:73], v[206:209], v[166:169], v[70:73]
	v_mfma_f32_16x16x32_bf16 v[66:69], v[206:209], v[170:173], v[66:69]
	ds_read_b128 v[206:209], v238
	v_mfma_f32_16x16x32_bf16 v[54:57], v[212:215], v[166:169], v[54:57]
	v_mfma_f32_16x16x32_bf16 v[50:53], v[212:215], v[170:173], v[50:53]
	ds_read_b128 v[212:215], v239
	v_mfma_f32_16x16x32_bf16 v[38:41], v[222:225], v[166:169], v[38:41]
	v_mfma_f32_16x16x32_bf16 v[34:37], v[222:225], v[170:173], v[34:37]
	ds_read_b128 v[222:225], v240
	v_mfma_f32_16x16x32_bf16 v[22:25], v[226:229], v[166:169], v[22:25]
	v_mfma_f32_16x16x32_bf16 v[18:21], v[226:229], v[170:173], v[18:21]
	ds_read_b128 v[226:229], v241
	v_mfma_f32_16x16x32_bf16 v[6:9], v[230:233], v[166:169], v[6:9]
	v_mfma_f32_16x16x32_bf16 v[2:5], v[230:233], v[170:173], v[2:5]
	ds_read_b128 v[230:233], v242
	ds_read_b128 v[166:169], v0 offset:36864
	ds_read_b128 v[170:173], v0 offset:38912
	s_waitcnt lgkmcnt(0)
	s_add_i32 s0, 0, 0x18000
	v_add_u32_e32 v0, s0, v155
	v_add_u32_e32 v0, v0, v153
	v_add_u32_e32 v130, s30, v155
	v_add_u32_e32 v186, v130, v156
	ds_read_b128 v[130:133], v0
	ds_read_b128 v[134:137], v0 offset:2048
	ds_read_b128 v[138:141], v0 offset:4096
	ds_read_b128 v[142:145], v0 offset:6144
	v_add_u32_e32 v154, s30, v154
	v_add_u32_e32 v203, v154, v152
	v_add_u32_e32 v205, v154, v149
	v_add_u32_e32 v207, v154, v147
	v_add_u32_e32 v202, v154, v150
	ds_read_b128 v[174:177], v186
	ds_read_b128 v[166:169], v202
	v_add_u32_e32 v204, v154, v151
	ds_read_b128 v[170:173], v203
	ds_read_b128 v[158:161], v204
	v_add_u32_e32 v206, v154, v148
	ds_read_b128 v[162:165], v205
	ds_read_b128 v[150:153], v206
	v_add_u32_e32 v208, v154, v146
	ds_read_b128 v[154:157], v207
	ds_read_b128 v[146:149], v208
	v_cndmask_b32_e64 v187, 0, 1, s[12:13]
	v_cmp_ne_u32_e64 s[0:1], 1, v187
	s_andn2_b64 vcc, exec, s[12:13]
	s_cbranch_vccnz .LBB0_653
	v_readfirstlane_b32 s12, v185
	v_lshl_add_u64 v[188:189], s[8:9], 0, v[180:181]
	s_mov_b32 m0, s12
	v_readfirstlane_b32 s12, v184
	v_lshl_add_u64 v[180:181], s[10:11], 0, v[180:181]
	global_load_lds_dwordx4 v[188:189], off
	s_mov_b32 m0, s12
	v_readfirstlane_b32 s12, v183
	v_lshl_add_u64 v[212:213], s[8:9], 0, v[178:179]
	global_load_lds_dwordx4 v[180:181], off
	s_mov_b32 m0, s12
	v_readfirstlane_b32 s12, v182
	v_lshl_add_u64 v[178:179], s[10:11], 0, v[178:179]
	global_load_lds_dwordx4 v[212:213], off
	s_mov_b32 m0, s12
	s_nop 0
	global_load_lds_dwordx4 v[178:179], off

; DI int opaque_tid512() { int t = threadIdx.x; asm volatile("" : "+v"(t)); return t; }
; #define G8_STAGE(buf_, ap_, bp_) G8_STAGE_R(buf_, ap_, bp_, 0, 4)
; template <class Epi>
; DI void gemm8_tile(const bf16_t* __restrict__ Ab, int lda, const bf16_t* __restrict__ Bb, int ldb, int K, int brow, int bcol, const Epi epi,
;                    bool staged, bool has_next, const bf16_t* __restrict__ Abn, const bf16_t* __restrict__ Bbn) {
;   const int tid = opaque_tid512(), wid = tid >> 6, lane = tid & 63, wr = wid >> 2, wc = wid & 3, fr = lane & 15, fq = lane >> 4;
;   unsigned aoff[4], boff[4];
; #pragma unroll
;   for (int i = 0; i < 4; ++i) { int R, C; stage_rc2(wid * 1024 + i * 8192 + lane * 16, R, C); aoff[i] = (unsigned)R * (unsigned)lda + (unsigned)C; boff[i] = (unsigned)R * (unsigned)ldb + (unsigned)C; }
;     ...
;   f32x4 acc[8][4];
; #pragma unroll
;   for (int m = 0; m < 8; ++m)
; #pragma unroll
;     for (int n = 0; n < 4; ++n) acc[m][n] = (f32x4){0.f, 0.f, 0.f, 0.f};
;   const int nt = K / 64;
;   if (!staged) {
;     G8_STAGE(0, Ab, Bb);
;     asm volatile("s_waitcnt vmcnt(0)" ::: "memory");
;     __syncthreads();
;   }
;   for (int t = 0; t < nt; ++t) {
;     const int cur = t & 1;
;     const unsigned char* sa = smem + cur * G8_STAGE_B;
;     const unsigned char* sb = sa + G8_TILE_B;
; #pragma unroll
;     for (int ks = 0; ks < 2; ++ks) {
;       bf16x8 At[8], Bf[4];
;       Bf[0] = *(const bf16x8*)(sb + lds_byte2(wc * 64 + fr, ks * 32 + fq * 8));
;       At[0] = *(const bf16x8*)(sa + lds_byte2(wr * 128 + fr, ks * 32 + fq * 8));
; #pragma unroll
;       for (int n = 1; n < 4; ++n) Bf[n] = *(const bf16x8*)(sb + lds_byte2(wc * 64 + n * 16 + fr, ks * 32 + fq * 8));
; #pragma unroll
;       for (int m = 1; m < 8; ++m) At[m] = *(const bf16x8*)(sa + lds_byte2(wr * 128 + m * 16 + fr, ks * 32 + fq * 8));
; template <class Epi>
; DI void gemm8_phase(int x, int j, const bf16_t* __restrict__ A, int lda, const bf16_t* __restrict__ Bt, int K, int N, int a_grp, const Epi epi) {
;     ...
;     const int brow = pm * 256, bcol = pn * 256;
;     const bf16_t* Ab = A + (size_t)brow * lda + (a_grp ? (bcol / a_grp) * K : 0);
;     const bf16_t* Bb = Bt + (size_t)bcol * ldb;
.LBB0_1253:
	s_add_u32 s0, s57, s81
	s_addc_u32 s1, s58, s87
	v_lshl_add_u64 v[130:131], v[0:1], 1, s[0:1]
	v_lshl_add_u64 v[132:133], v[180:181], 1, s[0:1]
	v_lshl_add_u64 v[134:135], v[190:191], 1, s[0:1]
	v_lshl_add_u64 v[136:137], v[186:187], 1, s[0:1]
	s_lshl_b32 s0, s78, 3
	s_add_i32 s0, s28, s0
	s_add_i32 s0, s0, s79
	s_lshl_b32 s1, s75, 3
	s_sub_i32 s0, s0, s1
	v_and_b32_e32 v198, 3, v3
	v_ashrrev_i32_e32 v3, 8, v2
	v_and_b32_e32 v197, 15, v2
	v_and_b32_e32 v4, 48, v2
	v_lshlrev_b32_e32 v6, 2, v2
	v_lshlrev_b32_e32 v2, 6, v2
	s_lshl_b32 s1, s0, 8
	s_mul_i32 s0, s0, 0x88000
	v_and_b32_e32 v6, 32, v6
	v_and_b32_e32 v2, 0x3c0, v2
	s_mul_hi_i32 s1, s1, 0x880
	s_add_u32 s0, s91, s0
	v_lshlrev_b32_e32 v5, 6, v197
	v_lshlrev_b32_e32 v156, 14, v3
	v_bitop3_b32 v154, v2, v6, v4 bitop3:0x36
	s_addc_u32 s1, s72, s1
	v_mov_b32_e32 v2, 0
	v_lshlrev_b32_e32 v153, 13, v198
	v_bitop3_b32 v155, v5, v6, v4 bitop3:0x36
	v_lshlrev_b32_e32 v199, 7, v3
	v_or_b32_e32 v150, 0x800, v156
	v_or_b32_e32 v152, 0x1000, v156
	v_or_b32_e32 v151, 0x1800, v156
	v_or_b32_e32 v149, 0x2000, v156
	v_or_b32_e32 v148, 0x2800, v156
	v_or_b32_e32 v147, 0x3000, v156
	v_or_b32_e32 v146, 0x3800, v156
	v_lshl_add_u64 v[138:139], v[182:183], 1, s[0:1]
	v_lshl_add_u64 v[140:141], v[178:179], 1, s[0:1]
	v_lshl_add_u64 v[142:143], v[188:189], 1, s[0:1]
	v_lshl_add_u64 v[144:145], v[184:185], 1, s[0:1]
	s_mov_b64 s[0:1], 0
	s_mov_b32 s38, 0
	v_mov_b32_e32 v3, v2
	v_mov_b32_e32 v4, v2
	v_mov_b32_e32 v5, v2
	v_mov_b32_e32 v6, v2
	v_mov_b32_e32 v7, v2
	v_mov_b32_e32 v8, v2
	v_mov_b32_e32 v9, v2
	v_mov_b32_e32 v10, v2
	v_mov_b32_e32 v11, v2
	v_mov_b32_e32 v12, v2
	v_mov_b32_e32 v13, v2
	v_mov_b32_e32 v14, v2
	v_mov_b32_e32 v15, v2
	v_mov_b32_e32 v16, v2
	v_mov_b32_e32 v17, v2
	v_mov_b32_e32 v18, v2
	v_mov_b32_e32 v19, v2
	v_mov_b32_e32 v20, v2
	v_mov_b32_e32 v21, v2
	v_mov_b32_e32 v22, v2
	v_mov_b32_e32 v23, v2
	v_mov_b32_e32 v24, v2
	v_mov_b32_e32 v25, v2
	v_mov_b32_e32 v26, v2
	v_mov_b32_e32 v27, v2
	v_mov_b32_e32 v28, v2
	v_mov_b32_e32 v29, v2
	v_mov_b32_e32 v30, v2
	v_mov_b32_e32 v31, v2
	v_mov_b32_e32 v32, v2
	v_mov_b32_e32 v33, v2
	v_mov_b32_e32 v34, v2
	v_mov_b32_e32 v35, v2
	v_mov_b32_e32 v36, v2
	v_mov_b32_e32 v37, v2
	v_mov_b32_e32 v38, v2
	v_mov_b32_e32 v39, v2
	v_mov_b32_e32 v40, v2
	v_mov_b32_e32 v41, v2
	v_mov_b32_e32 v42, v2
	v_mov_b32_e32 v43, v2
	v_mov_b32_e32 v44, v2
	v_mov_b32_e32 v45, v2
	v_mov_b32_e32 v46, v2
	v_mov_b32_e32 v47, v2
	v_mov_b32_e32 v48, v2
	v_mov_b32_e32 v49, v2
	v_mov_b32_e32 v50, v2
	v_mov_b32_e32 v51, v2
	v_mov_b32_e32 v52, v2
	v_mov_b32_e32 v53, v2
	v_mov_b32_e32 v54, v2
	v_mov_b32_e32 v55, v2
	v_mov_b32_e32 v56, v2
	v_mov_b32_e32 v57, v2
	v_mov_b32_e32 v58, v2
	v_mov_b32_e32 v59, v2
	v_mov_b32_e32 v60, v2
	v_mov_b32_e32 v61, v2
	v_mov_b32_e32 v62, v2
	v_mov_b32_e32 v63, v2
	v_mov_b32_e32 v64, v2
	v_mov_b32_e32 v65, v2
	s_waitcnt vmcnt(8)
	v_mov_b32_e32 v66, v2
	v_mov_b32_e32 v67, v2
	v_mov_b32_e32 v68, v2
	v_mov_b32_e32 v69, v2
	v_mov_b32_e32 v70, v2
	v_mov_b32_e32 v71, v2
	v_mov_b32_e32 v72, v2
	v_mov_b32_e32 v73, v2
	v_mov_b32_e32 v74, v2
	v_mov_b32_e32 v75, v2
	v_mov_b32_e32 v76, v2
	v_mov_b32_e32 v77, v2
	v_mov_b32_e32 v78, v2
	v_mov_b32_e32 v79, v2
	v_mov_b32_e32 v80, v2
	v_mov_b32_e32 v81, v2
	v_mov_b32_e32 v82, v2
	v_mov_b32_e32 v83, v2
	v_mov_b32_e32 v84, v2
	v_mov_b32_e32 v85, v2
	v_mov_b32_e32 v86, v2
	v_mov_b32_e32 v87, v2
	v_mov_b32_e32 v88, v2
	v_mov_b32_e32 v89, v2
	v_mov_b32_e32 v90, v2
	v_mov_b32_e32 v91, v2
	v_mov_b32_e32 v92, v2
	v_mov_b32_e32 v93, v2
	v_mov_b32_e32 v94, v2
	v_mov_b32_e32 v95, v2
	v_mov_b32_e32 v96, v2
	v_mov_b32_e32 v97, v2
	v_mov_b32_e32 v98, v2
	v_mov_b32_e32 v99, v2
	v_mov_b32_e32 v100, v2
	v_mov_b32_e32 v101, v2
	v_mov_b32_e32 v102, v2
	v_mov_b32_e32 v103, v2
	v_mov_b32_e32 v104, v2
	v_mov_b32_e32 v105, v2
	v_mov_b32_e32 v106, v2
	v_mov_b32_e32 v107, v2
	v_mov_b32_e32 v108, v2
	v_mov_b32_e32 v109, v2
	v_mov_b32_e32 v110, v2
	v_mov_b32_e32 v111, v2
	v_mov_b32_e32 v112, v2
	v_mov_b32_e32 v113, v2
	v_mov_b32_e32 v114, v2
	v_mov_b32_e32 v115, v2
	v_mov_b32_e32 v116, v2
	v_mov_b32_e32 v117, v2
	v_mov_b32_e32 v118, v2
	v_mov_b32_e32 v119, v2
	v_mov_b32_e32 v120, v2
	v_mov_b32_e32 v121, v2
	v_mov_b32_e32 v122, v2
	v_mov_b32_e32 v123, v2
	v_mov_b32_e32 v124, v2
	v_mov_b32_e32 v125, v2
	v_mov_b32_e32 v126, v2
	v_mov_b32_e32 v127, v2
	v_mov_b32_e32 v128, v2
	v_mov_b32_e32 v129, v2
	s_mov_b32 s54, 0
	v_add3_u32 v157, s54, v155, v153
	v_add3_u32 v242, s54, v155, v156
	v_add3_u32 v244, s54, v154, v152
	v_add3_u32 v246, s54, v154, v149
	v_add3_u32 v248, s54, v154, v147
	v_add3_u32 v243, s54, v154, v150
	v_add3_u32 v245, s54, v154, v151
	v_add3_u32 v247, s54, v154, v148
	v_add3_u32 v249, s54, v154, v146
	ds_read_b128 v[158:161], v157 offset:32768
	ds_read_b128 v[162:165], v157 offset:34816
	ds_read_b128 v[174:177], v242
	ds_read_b128 v[204:207], v243
	ds_read_b128 v[212:215], v244
	ds_read_b128 v[222:225], v245
	ds_read_b128 v[226:229], v246
	ds_read_b128 v[230:233], v247
	ds_read_b128 v[234:237], v248
	ds_read_b128 v[238:241], v249
	ds_read_b128 v[166:169], v157 offset:36864
	ds_read_b128 v[170:173], v157 offset:38912
	v_add_u32_e32 v250, 0x10000, v203
	s_nop 0
	v_readfirstlane_b32 s54, v250
	s_mov_b32 m0, s54
	v_lshl_add_u64 v[208:209], v[144:145], 0, s[0:1]
	global_load_lds_dwordx4 v[208:209], off
	s_add_u32 m0, s54, 0x8000
	v_lshl_add_u64 v[208:209], v[136:137], 0, s[0:1]
	global_load_lds_dwordx4 v[208:209], off
	s_add_u32 m0, s54, 0x2000
	v_lshl_add_u64 v[208:209], v[142:143], 0, s[0:1]
	global_load_lds_dwordx4 v[208:209], off
	s_add_u32 m0, s54, 0xa000
	v_lshl_add_u64 v[208:209], v[134:135], 0, s[0:1]
	global_load_lds_dwordx4 v[208:209], off
	s_add_u32 m0, s54, 0x4000
	v_lshl_add_u64 v[208:209], v[140:141], 0, s[0:1]
	global_load_lds_dwordx4 v[208:209], off
	s_add_u32 m0, s54, 0xc000
	v_lshl_add_u64 v[208:209], v[132:133], 0, s[0:1]
	global_load_lds_dwordx4 v[208:209], off
	s_add_u32 m0, s54, 0x6000
	v_lshl_add_u64 v[208:209], v[138:139], 0, s[0:1]
	global_load_lds_dwordx4 v[208:209], off
	s_add_u32 m0, s54, 0xe000
	v_lshl_add_u64 v[208:209], v[130:131], 0, s[0:1]
	global_load_lds_dwordx4 v[208:209], off
; #define MFMA16(a, b, c) __builtin_amdgcn_mfma_f32_16x16x32_bf16((a), (b), (c), 0, 0, 0)
; template <class Epi>
; DI void gemm8_tile(const bf16_t* __restrict__ Ab, int lda, const bf16_t* __restrict__ Bb, int ldb, int K, int brow, int bcol, const Epi epi,
;                    bool staged, bool has_next, const bf16_t* __restrict__ Abn, const bf16_t* __restrict__ Bbn) {
;     ...
;   for (int t = 0; t < nt; ++t) {
;     const int cur = t & 1;
;     const unsigned char* sa = smem + cur * G8_STAGE_B;
;     const unsigned char* sb = sa + G8_TILE_B;
; #pragma unroll
;     for (int ks = 0; ks < 2; ++ks) {
;       bf16x8 At[8], Bf[4];
;       Bf[0] = *(const bf16x8*)(sb + lds_byte2(wc * 64 + fr, ks * 32 + fq * 8));
;       At[0] = *(const bf16x8*)(sa + lds_byte2(wr * 128 + fr, ks * 32 + fq * 8));
; #pragma unroll
;       for (int n = 1; n < 4; ++n) Bf[n] = *(const bf16x8*)(sb + lds_byte2(wc * 64 + n * 16 + fr, ks * 32 + fq * 8));
; #pragma unroll
;       for (int m = 1; m < 8; ++m) At[m] = *(const bf16x8*)(sa + lds_byte2(wr * 128 + m * 16 + fr, ks * 32 + fq * 8));
;       {
;         __builtin_amdgcn_sched_barrier(0);
;         if (t + 1 < nt) { G8_STAGE_R(cur ^ 1, Ab + (t + 1) * 64, Bb + (t + 1) * 64, 2 * ks, 2 * ks + 2); }
;         else if (has_next) { G8_STAGE_R(0, Abn, Bbn, 2 * ks, 2 * ks + 2); }
;         __builtin_amdgcn_sched_barrier(0);
;       }
; #pragma unroll
;       for (int m = 0; m < 8; ++m)
; #pragma unroll
;         for (int n = 0; n < 4; ++n) acc[m][n] = MFMA16(At[m], Bf[n], acc[m][n]);
;       __builtin_amdgcn_sched_barrier(0);
;     }
;     asm volatile("s_waitcnt vmcnt(0)" ::: "memory");
;     __syncthreads();
.LBB0_1254:
	s_and_b32 s39, s38, 0x10000
	s_xor_b32 s54, s39, 0x10000
	v_add_u32_e32 v250, s54, v203
	s_nop 0
	v_readfirstlane_b32 s39, v250
	s_waitcnt lgkmcnt(8)
	v_mfma_f32_16x16x32_bf16 v[126:129], v[174:177], v[158:161], v[126:129]
	v_mfma_f32_16x16x32_bf16 v[122:125], v[174:177], v[162:165], v[122:125]
	v_mfma_f32_16x16x32_bf16 v[110:113], v[204:207], v[158:161], v[110:113]
	v_mfma_f32_16x16x32_bf16 v[106:109], v[204:207], v[162:165], v[106:109]
	s_waitcnt lgkmcnt(6)
	v_mfma_f32_16x16x32_bf16 v[94:97], v[212:215], v[158:161], v[94:97]
	v_mfma_f32_16x16x32_bf16 v[90:93], v[212:215], v[162:165], v[90:93]
	v_mfma_f32_16x16x32_bf16 v[78:81], v[222:225], v[158:161], v[78:81]
	v_mfma_f32_16x16x32_bf16 v[74:77], v[222:225], v[162:165], v[74:77]
	s_waitcnt lgkmcnt(4)
	v_mfma_f32_16x16x32_bf16 v[62:65], v[226:229], v[158:161], v[62:65]
	v_mfma_f32_16x16x32_bf16 v[58:61], v[226:229], v[162:165], v[58:61]
	v_mfma_f32_16x16x32_bf16 v[46:49], v[230:233], v[158:161], v[46:49]
	v_mfma_f32_16x16x32_bf16 v[42:45], v[230:233], v[162:165], v[42:45]
	s_waitcnt lgkmcnt(2)
	v_mfma_f32_16x16x32_bf16 v[30:33], v[234:237], v[158:161], v[30:33]
	v_mfma_f32_16x16x32_bf16 v[26:29], v[234:237], v[162:165], v[26:29]
	v_mfma_f32_16x16x32_bf16 v[14:17], v[238:241], v[158:161], v[14:17]
	v_mfma_f32_16x16x32_bf16 v[10:13], v[238:241], v[162:165], v[10:13]
	ds_read_b128 v[158:161], v157 offset:33792
	ds_read_b128 v[162:165], v157 offset:35840
	s_waitcnt lgkmcnt(2)
	v_mfma_f32_16x16x32_bf16 v[118:121], v[174:177], v[166:169], v[118:121]
	v_mfma_f32_16x16x32_bf16 v[114:117], v[174:177], v[170:173], v[114:117]
	ds_read_b128 v[174:177], v242 offset:1024
	v_mfma_f32_16x16x32_bf16 v[102:105], v[204:207], v[166:169], v[102:105]
	v_mfma_f32_16x16x32_bf16 v[98:101], v[204:207], v[170:173], v[98:101]
	ds_read_b128 v[204:207], v243 offset:1024
	v_mfma_f32_16x16x32_bf16 v[86:89], v[212:215], v[166:169], v[86:89]
	v_mfma_f32_16x16x32_bf16 v[82:85], v[212:215], v[170:173], v[82:85]
	ds_read_b128 v[212:215], v244 offset:1024
	v_mfma_f32_16x16x32_bf16 v[70:73], v[222:225], v[166:169], v[70:73]
	v_mfma_f32_16x16x32_bf16 v[66:69], v[222:225], v[170:173], v[66:69]
	ds_read_b128 v[222:225], v245 offset:1024
	v_mfma_f32_16x16x32_bf16 v[54:57], v[226:229], v[166:169], v[54:57]
	v_mfma_f32_16x16x32_bf16 v[50:53], v[226:229], v[170:173], v[50:53]
	ds_read_b128 v[226:229], v246 offset:1024
	v_mfma_f32_16x16x32_bf16 v[38:41], v[230:233], v[166:169], v[38:41]
	v_mfma_f32_16x16x32_bf16 v[34:37], v[230:233], v[170:173], v[34:37]
	ds_read_b128 v[230:233], v247 offset:1024
	v_mfma_f32_16x16x32_bf16 v[22:25], v[234:237], v[166:169], v[22:25]
	v_mfma_f32_16x16x32_bf16 v[18:21], v[234:237], v[170:173], v[18:21]
	ds_read_b128 v[234:237], v248 offset:1024
	v_mfma_f32_16x16x32_bf16 v[6:9], v[238:241], v[166:169], v[6:9]
	v_mfma_f32_16x16x32_bf16 v[2:5], v[238:241], v[170:173], v[2:5]
	ds_read_b128 v[238:241], v249 offset:1024
	ds_read_b128 v[166:169], v157 offset:37888
	ds_read_b128 v[170:173], v157 offset:39936
	s_waitcnt lgkmcnt(8)
	v_mfma_f32_16x16x32_bf16 v[126:129], v[174:177], v[158:161], v[126:129]
	v_mfma_f32_16x16x32_bf16 v[122:125], v[174:177], v[162:165], v[122:125]
	v_add3_u32 v157, s54, v155, v153
	v_mfma_f32_16x16x32_bf16 v[110:113], v[204:207], v[158:161], v[110:113]
	v_mfma_f32_16x16x32_bf16 v[106:109], v[204:207], v[162:165], v[106:109]
	v_add3_u32 v242, s54, v155, v156
	s_waitcnt lgkmcnt(6)
	v_mfma_f32_16x16x32_bf16 v[94:97], v[212:215], v[158:161], v[94:97]
	v_mfma_f32_16x16x32_bf16 v[90:93], v[212:215], v[162:165], v[90:93]
	v_add3_u32 v244, s54, v154, v152
	v_mfma_f32_16x16x32_bf16 v[78:81], v[222:225], v[158:161], v[78:81]
	v_mfma_f32_16x16x32_bf16 v[74:77], v[222:225], v[162:165], v[74:77]
	v_add3_u32 v246, s54, v154, v149
	s_waitcnt lgkmcnt(4)
	v_mfma_f32_16x16x32_bf16 v[62:65], v[226:229], v[158:161], v[62:65]
	v_mfma_f32_16x16x32_bf16 v[58:61], v[226:229], v[162:165], v[58:61]
	v_add3_u32 v248, s54, v154, v147
	v_mfma_f32_16x16x32_bf16 v[46:49], v[230:233], v[158:161], v[46:49]
	v_mfma_f32_16x16x32_bf16 v[42:45], v[230:233], v[162:165], v[42:45]
	v_add3_u32 v243, s54, v154, v150
	s_waitcnt lgkmcnt(2)
	v_mfma_f32_16x16x32_bf16 v[30:33], v[234:237], v[158:161], v[30:33]
	v_mfma_f32_16x16x32_bf16 v[26:29], v[234:237], v[162:165], v[26:29]
	v_add3_u32 v245, s54, v154, v151
	v_mfma_f32_16x16x32_bf16 v[14:17], v[238:241], v[158:161], v[14:17]
	v_mfma_f32_16x16x32_bf16 v[10:13], v[238:241], v[162:165], v[10:13]
	v_add3_u32 v247, s54, v154, v148
	v_add3_u32 v249, s54, v154, v146
	s_waitcnt vmcnt(0) lgkmcnt(0)
	s_barrier
	s_add_u32 s0, s0, 0x80
	s_addc_u32 s1, s1, 0
	s_add_i32 s38, s38, 0x10000
	s_xor_b32 s54, s39, 0x10000
	s_cmpk_eq_i32 s0, 0x580
	s_cbranch_scc1 .Lg80_1254_last
; #define MFMA16(a, b, c) __builtin_amdgcn_mfma_f32_16x16x32_bf16((a), (b), (c), 0, 0, 0)
; template <class Epi>
; DI void gemm8_tile(const bf16_t* __restrict__ Ab, int lda, const bf16_t* __restrict__ Bb, int ldb, int K, int brow, int bcol, const Epi epi,
;                    bool staged, bool has_next, const bf16_t* __restrict__ Abn, const bf16_t* __restrict__ Bbn) {
;     ...
;   for (int t = 0; t < nt; ++t) {
;     const int cur = t & 1;
;     const unsigned char* sa = smem + cur * G8_STAGE_B;
;     const unsigned char* sb = sa + G8_TILE_B;
; #pragma unroll
;     for (int ks = 0; ks < 2; ++ks) {
;       bf16x8 At[8], Bf[4];
;       Bf[0] = *(const bf16x8*)(sb + lds_byte2(wc * 64 + fr, ks * 32 + fq * 8));
;       At[0] = *(const bf16x8*)(sa + lds_byte2(wr * 128 + fr, ks * 32 + fq * 8));
; #pragma unroll
;       for (int n = 1; n < 4; ++n) Bf[n] = *(const bf16x8*)(sb + lds_byte2(wc * 64 + n * 16 + fr, ks * 32 + fq * 8));
; #pragma unroll
;       for (int m = 1; m < 8; ++m) At[m] = *(const bf16x8*)(sa + lds_byte2(wr * 128 + m * 16 + fr, ks * 32 + fq * 8));
;       {
;         __builtin_amdgcn_sched_barrier(0);
;         if (t + 1 < nt) { G8_STAGE_R(cur ^ 1, Ab + (t + 1) * 64, Bb + (t + 1) * 64, 2 * ks, 2 * ks + 2); }
;         else if (has_next) { G8_STAGE_R(0, Abn, Bbn, 2 * ks, 2 * ks + 2); }
;         __builtin_amdgcn_sched_barrier(0);
;       }
; #pragma unroll
;       for (int m = 0; m < 8; ++m)
; #pragma unroll
;         for (int n = 0; n < 4; ++n) acc[m][n] = MFMA16(At[m], Bf[n], acc[m][n]);
;       __builtin_amdgcn_sched_barrier(0);
;     }
;     asm volatile("s_waitcnt vmcnt(0)" ::: "memory");
;     __syncthreads();
;   }
	ds_read_b128 v[158:161], v157 offset:32768
	ds_read_b128 v[162:165], v157 offset:34816
	v_mfma_f32_16x16x32_bf16 v[118:121], v[174:177], v[166:169], v[118:121]
	v_mfma_f32_16x16x32_bf16 v[114:117], v[174:177], v[170:173], v[114:117]
	ds_read_b128 v[174:177], v242
	s_mov_b32 m0, s54
	v_lshl_add_u64 v[208:209], v[144:145], 0, s[0:1]
	global_load_lds_dwordx4 v[208:209], off
	v_mfma_f32_16x16x32_bf16 v[102:105], v[204:207], v[166:169], v[102:105]
	v_mfma_f32_16x16x32_bf16 v[98:101], v[204:207], v[170:173], v[98:101]
	ds_read_b128 v[204:207], v243
	s_add_u32 m0, s54, 0x8000
	v_lshl_add_u64 v[208:209], v[136:137], 0, s[0:1]
	global_load_lds_dwordx4 v[208:209], off
	v_mfma_f32_16x16x32_bf16 v[86:89], v[212:215], v[166:169], v[86:89]
	v_mfma_f32_16x16x32_bf16 v[82:85], v[212:215], v[170:173], v[82:85]
	ds_read_b128 v[212:215], v244
	s_add_u32 m0, s54, 0x2000
	v_lshl_add_u64 v[208:209], v[142:143], 0, s[0:1]
	global_load_lds_dwordx4 v[208:209], off
	v_mfma_f32_16x16x32_bf16 v[70:73], v[222:225], v[166:169], v[70:73]
	v_mfma_f32_16x16x32_bf16 v[66:69], v[222:225], v[170:173], v[66:69]
	ds_read_b128 v[222:225], v245
	s_add_u32 m0, s54, 0xa000
	v_lshl_add_u64 v[208:209], v[134:135], 0, s[0:1]
	global_load_lds_dwordx4 v[208:209], off
	v_mfma_f32_16x16x32_bf16 v[54:57], v[226:229], v[166:169], v[54:57]
	v_mfma_f32_16x16x32_bf16 v[50:53], v[226:229], v[170:173], v[50:53]
	ds_read_b128 v[226:229], v246
	s_add_u32 m0, s54, 0x4000
	v_lshl_add_u64 v[208:209], v[140:141], 0, s[0:1]
	global_load_lds_dwordx4 v[208:209], off
	v_mfma_f32_16x16x32_bf16 v[38:41], v[230:233], v[166:169], v[38:41]
	v_mfma_f32_16x16x32_bf16 v[34:37], v[230:233], v[170:173], v[34:37]
	ds_read_b128 v[230:233], v247
	s_add_u32 m0, s54, 0xc000
	v_lshl_add_u64 v[208:209], v[132:133], 0, s[0:1]
	global_load_lds_dwordx4 v[208:209], off
	v_mfma_f32_16x16x32_bf16 v[22:25], v[234:237], v[166:169], v[22:25]
	v_mfma_f32_16x16x32_bf16 v[18:21], v[234:237], v[170:173], v[18:21]
	ds_read_b128 v[234:237], v248
	s_add_u32 m0, s54, 0x6000
	v_lshl_add_u64 v[208:209], v[138:139], 0, s[0:1]
	global_load_lds_dwordx4 v[208:209], off
	v_mfma_f32_16x16x32_bf16 v[6:9], v[238:241], v[166:169], v[6:9]
	v_mfma_f32_16x16x32_bf16 v[2:5], v[238:241], v[170:173], v[2:5]
	ds_read_b128 v[238:241], v249
	s_add_u32 m0, s54, 0xe000
	v_lshl_add_u64 v[208:209], v[130:131], 0, s[0:1]
	global_load_lds_dwordx4 v[208:209], off
	ds_read_b128 v[166:169], v157 offset:36864
	ds_read_b128 v[170:173], v157 offset:38912
	s_branch .LBB0_1254
.Lg80_1254_last:
	ds_read_b128 v[158:161], v157 offset:32768
	ds_read_b128 v[162:165], v157 offset:34816
	v_mfma_f32_16x16x32_bf16 v[118:121], v[174:177], v[166:169], v[118:121]
	v_mfma_f32_16x16x32_bf16 v[114:117], v[174:177], v[170:173], v[114:117]
	ds_read_b128 v[174:177], v242
	v_mfma_f32_16x16x32_bf16 v[102:105], v[204:207], v[166:169], v[102:105]
	v_mfma_f32_16x16x32_bf16 v[98:101], v[204:207], v[170:173], v[98:101]
	ds_read_b128 v[204:207], v243
	v_mfma_f32_16x16x32_bf16 v[86:89], v[212:215], v[166:169], v[86:89]
	v_mfma_f32_16x16x32_bf16 v[82:85], v[212:215], v[170:173], v[82:85]
	ds_read_b128 v[212:215], v244
	v_mfma_f32_16x16x32_bf16 v[70:73], v[222:225], v[166:169], v[70:73]
	v_mfma_f32_16x16x32_bf16 v[66:69], v[222:225], v[170:173], v[66:69]
	ds_read_b128 v[222:225], v245
	v_mfma_f32_16x16x32_bf16 v[54:57], v[226:229], v[166:169], v[54:57]
	v_mfma_f32_16x16x32_bf16 v[50:53], v[226:229], v[170:173], v[50:53]
	ds_read_b128 v[226:229], v246
	v_mfma_f32_16x16x32_bf16 v[38:41], v[230:233], v[166:169], v[38:41]
	v_mfma_f32_16x16x32_bf16 v[34:37], v[230:233], v[170:173], v[34:37]
	ds_read_b128 v[230:233], v247
	v_mfma_f32_16x16x32_bf16 v[22:25], v[234:237], v[166:169], v[22:25]
	v_mfma_f32_16x16x32_bf16 v[18:21], v[234:237], v[170:173], v[18:21]
	ds_read_b128 v[234:237], v248
	v_mfma_f32_16x16x32_bf16 v[6:9], v[238:241], v[166:169], v[6:9]
	v_mfma_f32_16x16x32_bf16 v[2:5], v[238:241], v[170:173], v[2:5]
	ds_read_b128 v[238:241], v249
	ds_read_b128 v[166:169], v157 offset:36864
	ds_read_b128 v[170:173], v157 offset:38912
	s_waitcnt lgkmcnt(0)
	s_add_i32 s0, 0, 0x18000
	v_add_u32_e32 v130, s0, v155
	v_add_u32_e32 v204, v130, v153
	v_add_u32_e32 v130, s30, v155
	v_add_u32_e32 v205, v130, v156
	ds_read_b128 v[130:133], v204
	ds_read_b128 v[134:137], v204 offset:2048
	ds_read_b128 v[138:141], v204 offset:4096
	ds_read_b128 v[142:145], v204 offset:6144
	v_add_u32_e32 v154, s30, v154
	v_add_u32_e32 v207, v154, v152
	v_add_u32_e32 v209, v154, v149
	v_add_u32_e32 v213, v154, v147
	v_add_u32_e32 v206, v154, v150
	ds_read_b128 v[174:177], v205
	ds_read_b128 v[166:169], v206
	v_add_u32_e32 v208, v154, v151
	ds_read_b128 v[170:173], v207
	ds_read_b128 v[158:161], v208
	v_add_u32_e32 v212, v154, v148
	ds_read_b128 v[162:165], v209
	ds_read_b128 v[150:153], v212
	v_add_u32_e32 v214, v154, v146
	ds_read_b128 v[154:157], v213
	ds_read_b128 v[146:149], v214
	v_cndmask_b32_e64 v215, 0, 1, s[14:15]
	v_cmp_ne_u32_e64 s[0:1], 1, v215
	s_andn2_b64 vcc, exec, s[14:15]
	s_cbranch_vccnz .LBB0_1257
	v_readfirstlane_b32 s14, v203
	v_lshl_add_u64 v[184:185], v[184:185], 1, s[10:11]
	s_mov_b32 m0, s14
	v_readfirstlane_b32 s14, v202
	v_lshl_add_u64 v[186:187], v[186:187], 1, s[12:13]
	global_load_lds_dwordx4 v[184:185], off
	s_mov_b32 m0, s14
	v_readfirstlane_b32 s14, v201
	v_lshl_add_u64 v[188:189], v[188:189], 1, s[10:11]
	global_load_lds_dwordx4 v[186:187], off
	s_mov_b32 m0, s14
	v_readfirstlane_b32 s14, v200
	v_lshl_add_u64 v[190:191], v[190:191], 1, s[12:13]
	global_load_lds_dwordx4 v[188:189], off
	s_mov_b32 m0, s14
	s_nop 0
	global_load_lds_dwordx4 v[190:191], off

; DI int opaque_tid512() { int t = threadIdx.x; asm volatile("" : "+v"(t)); return t; }
; #define G8_STAGE(buf_, ap_, bp_) G8_STAGE_R(buf_, ap_, bp_, 0, 4)
; template <class Epi>
; DI void gemm8_tile(const bf16_t* __restrict__ Ab, int lda, const bf16_t* __restrict__ Bb, int ldb, int K, int brow, int bcol, const Epi epi,
;                    bool staged, bool has_next, const bf16_t* __restrict__ Abn, const bf16_t* __restrict__ Bbn) {
;   const int tid = opaque_tid512(), wid = tid >> 6, lane = tid & 63, wr = wid >> 2, wc = wid & 3, fr = lane & 15, fq = lane >> 4;
;   unsigned aoff[4], boff[4];
; #pragma unroll
;   for (int i = 0; i < 4; ++i) { int R, C; stage_rc2(wid * 1024 + i * 8192 + lane * 16, R, C); aoff[i] = (unsigned)R * (unsigned)lda + (unsigned)C; boff[i] = (unsigned)R * (unsigned)ldb + (unsigned)C; }
;     ...
;   f32x4 acc[8][4];
; #pragma unroll
;   for (int m = 0; m < 8; ++m)
; #pragma unroll
;     for (int n = 0; n < 4; ++n) acc[m][n] = (f32x4){0.f, 0.f, 0.f, 0.f};
;   const int nt = K / 64;
;   if (!staged) {
;     G8_STAGE(0, Ab, Bb);
;     asm volatile("s_waitcnt vmcnt(0)" ::: "memory");
;     __syncthreads();
;   }
;   for (int t = 0; t < nt; ++t) {
;     const int cur = t & 1;
;     const unsigned char* sa = smem + cur * G8_STAGE_B;
;     const unsigned char* sb = sa + G8_TILE_B;
; #pragma unroll
;     for (int ks = 0; ks < 2; ++ks) {
;       bf16x8 At[8], Bf[4];
;       Bf[0] = *(const bf16x8*)(sb + lds_byte2(wc * 64 + fr, ks * 32 + fq * 8));
;       At[0] = *(const bf16x8*)(sa + lds_byte2(wr * 128 + fr, ks * 32 + fq * 8));
; #pragma unroll
;       for (int n = 1; n < 4; ++n) Bf[n] = *(const bf16x8*)(sb + lds_byte2(wc * 64 + n * 16 + fr, ks * 32 + fq * 8));
; #pragma unroll
;       for (int m = 1; m < 8; ++m) At[m] = *(const bf16x8*)(sa + lds_byte2(wr * 128 + m * 16 + fr, ks * 32 + fq * 8));
; template <class Epi>
; DI void gemm8_phase(int x, int j, const bf16_t* __restrict__ A, int lda, const bf16_t* __restrict__ Bt, int K, int N, int a_grp, const Epi epi) {
;     ...
;     const int brow = pm * 256, bcol = pn * 256;
;     const bf16_t* Ab = A + (size_t)brow * lda + (a_grp ? (bcol / a_grp) * K : 0);
;     const bf16_t* Bb = Bt + (size_t)bcol * ldb;
.LBB0_1311:
	s_lshl_b32 s0, s74, 3
	s_add_i32 s0, s28, s0
	s_add_i32 s0, s0, s75
	s_lshl_b32 s1, s71, 3
	s_sub_i32 s0, s0, s1
	s_lshl_b32 s1, s0, 8
	s_mul_i32 s0, s0, 0x88000
	s_mul_hi_i32 s1, s1, 0x880
	s_add_u32 s0, s91, s0
	v_and_b32_e32 v198, 15, v8
	v_lshlrev_b64 v[178:179], 1, v[4:5]
	s_addc_u32 s1, s72, s1
	v_lshlrev_b64 v[180:181], 1, v[2:3]
	v_lshlrev_b64 v[194:195], 1, v[6:7]
	v_lshlrev_b64 v[196:197], 1, v[0:1]
	v_and_b32_e32 v206, 63, v8
	v_ashrrev_i32_e32 v10, 8, v8
	v_and_b32_e32 v204, 3, v9
	v_and_b32_e32 v9, 48, v8
	v_lshlrev_b32_e32 v199, 2, v198
	v_lshlrev_b32_e32 v8, 6, v8
	v_lshl_add_u64 v[130:131], s[0:1], 0, v[178:179]
	v_lshl_add_u64 v[132:133], s[0:1], 0, v[180:181]
	v_lshl_add_u64 v[134:135], s[0:1], 0, v[194:195]
	v_lshl_add_u64 v[136:137], s[0:1], 0, v[196:197]
	s_add_u32 s0, s57, s78
	v_lshlrev_b32_e32 v11, 6, v198
	v_and_b32_e32 v12, 32, v199
	v_lshlrev_b32_e32 v156, 14, v10
	v_and_b32_e32 v8, 0x3c0, v8
	s_addc_u32 s1, s58, s79
	v_mov_b32_e32 v2, 0
	v_lshlrev_b32_e32 v153, 13, v204
	v_bitop3_b32 v155, v11, v12, v9 bitop3:0x36
	v_lshlrev_b32_e32 v205, 7, v10
	v_or_b32_e32 v150, 0x800, v156
	v_bitop3_b32 v154, v8, v12, v9 bitop3:0x36
	v_or_b32_e32 v152, 0x1000, v156
	v_or_b32_e32 v151, 0x1800, v156
	v_or_b32_e32 v149, 0x2000, v156
	v_or_b32_e32 v148, 0x2800, v156
	v_or_b32_e32 v147, 0x3000, v156
	v_or_b32_e32 v146, 0x3800, v156
	v_lshl_add_u64 v[138:139], s[0:1], 0, v[178:179]
	v_lshl_add_u64 v[140:141], s[0:1], 0, v[180:181]
	v_lshl_add_u64 v[142:143], s[0:1], 0, v[194:195]
	v_lshl_add_u64 v[144:145], s[0:1], 0, v[196:197]
	s_mov_b64 s[0:1], 0
	s_mov_b32 s38, 0
	v_mov_b32_e32 v3, v2
	v_mov_b32_e32 v4, v2
	v_mov_b32_e32 v5, v2
	v_mov_b32_e32 v6, v2
	v_mov_b32_e32 v7, v2
	v_mov_b32_e32 v8, v2
	v_mov_b32_e32 v9, v2
	v_mov_b32_e32 v10, v2
	v_mov_b32_e32 v11, v2
	v_mov_b32_e32 v12, v2
	v_mov_b32_e32 v13, v2
	v_mov_b32_e32 v14, v2
	v_mov_b32_e32 v15, v2
	v_mov_b32_e32 v16, v2
	v_mov_b32_e32 v17, v2
	v_mov_b32_e32 v18, v2
	v_mov_b32_e32 v19, v2
	v_mov_b32_e32 v20, v2
	v_mov_b32_e32 v21, v2
	v_mov_b32_e32 v22, v2
	v_mov_b32_e32 v23, v2
	v_mov_b32_e32 v24, v2
	v_mov_b32_e32 v25, v2
	v_mov_b32_e32 v26, v2
	v_mov_b32_e32 v27, v2
	v_mov_b32_e32 v28, v2
	v_mov_b32_e32 v29, v2
	v_mov_b32_e32 v30, v2
	v_mov_b32_e32 v31, v2
	v_mov_b32_e32 v32, v2
	v_mov_b32_e32 v33, v2
	v_mov_b32_e32 v34, v2
	v_mov_b32_e32 v35, v2
	v_mov_b32_e32 v36, v2
	v_mov_b32_e32 v37, v2
	v_mov_b32_e32 v38, v2
	v_mov_b32_e32 v39, v2
	v_mov_b32_e32 v40, v2
	v_mov_b32_e32 v41, v2
	v_mov_b32_e32 v42, v2
	v_mov_b32_e32 v43, v2
	v_mov_b32_e32 v44, v2
	v_mov_b32_e32 v45, v2
	v_mov_b32_e32 v46, v2
	v_mov_b32_e32 v47, v2
	v_mov_b32_e32 v48, v2
	v_mov_b32_e32 v49, v2
	v_mov_b32_e32 v50, v2
	v_mov_b32_e32 v51, v2
	v_mov_b32_e32 v52, v2
	v_mov_b32_e32 v53, v2
	v_mov_b32_e32 v54, v2
	v_mov_b32_e32 v55, v2
	v_mov_b32_e32 v56, v2
	v_mov_b32_e32 v57, v2
	v_mov_b32_e32 v58, v2
	v_mov_b32_e32 v59, v2
	v_mov_b32_e32 v60, v2
	v_mov_b32_e32 v61, v2
	v_mov_b32_e32 v62, v2
	v_mov_b32_e32 v63, v2
	v_mov_b32_e32 v64, v2
	v_mov_b32_e32 v65, v2
	s_waitcnt vmcnt(8)
	v_mov_b32_e32 v66, v2
	v_mov_b32_e32 v67, v2
	v_mov_b32_e32 v68, v2
	v_mov_b32_e32 v69, v2
	v_mov_b32_e32 v70, v2
	v_mov_b32_e32 v71, v2
	v_mov_b32_e32 v72, v2
	v_mov_b32_e32 v73, v2
	v_mov_b32_e32 v74, v2
	v_mov_b32_e32 v75, v2
	v_mov_b32_e32 v76, v2
	v_mov_b32_e32 v77, v2
	v_mov_b32_e32 v78, v2
	v_mov_b32_e32 v79, v2
	v_mov_b32_e32 v80, v2
	v_mov_b32_e32 v81, v2
	v_mov_b32_e32 v82, v2
	v_mov_b32_e32 v83, v2
	v_mov_b32_e32 v84, v2
	v_mov_b32_e32 v85, v2
	v_mov_b32_e32 v86, v2
	v_mov_b32_e32 v87, v2
	v_mov_b32_e32 v88, v2
	v_mov_b32_e32 v89, v2
	v_mov_b32_e32 v90, v2
	v_mov_b32_e32 v91, v2
	v_mov_b32_e32 v92, v2
	v_mov_b32_e32 v93, v2
	v_mov_b32_e32 v94, v2
	v_mov_b32_e32 v95, v2
	v_mov_b32_e32 v96, v2
	v_mov_b32_e32 v97, v2
	v_mov_b32_e32 v98, v2
	v_mov_b32_e32 v99, v2
	v_mov_b32_e32 v100, v2
	v_mov_b32_e32 v101, v2
	v_mov_b32_e32 v102, v2
	v_mov_b32_e32 v103, v2
	v_mov_b32_e32 v104, v2
	v_mov_b32_e32 v105, v2
	v_mov_b32_e32 v106, v2
	v_mov_b32_e32 v107, v2
	v_mov_b32_e32 v108, v2
	v_mov_b32_e32 v109, v2
	v_mov_b32_e32 v110, v2
	v_mov_b32_e32 v111, v2
	v_mov_b32_e32 v112, v2
	v_mov_b32_e32 v113, v2
	v_mov_b32_e32 v114, v2
	v_mov_b32_e32 v115, v2
	v_mov_b32_e32 v116, v2
	v_mov_b32_e32 v117, v2
	v_mov_b32_e32 v118, v2
	v_mov_b32_e32 v119, v2
	v_mov_b32_e32 v120, v2
	v_mov_b32_e32 v121, v2
	v_mov_b32_e32 v122, v2
	v_mov_b32_e32 v123, v2
	v_mov_b32_e32 v124, v2
	v_mov_b32_e32 v125, v2
	v_mov_b32_e32 v126, v2
	v_mov_b32_e32 v127, v2
	v_mov_b32_e32 v128, v2
	v_mov_b32_e32 v129, v2
	s_mov_b32 s54, 0
	v_add3_u32 v0, s54, v155, v153
	v_add3_u32 v157, s54, v155, v156
	v_add3_u32 v238, s54, v154, v152
	v_add3_u32 v240, s54, v154, v149
	v_add3_u32 v242, s54, v154, v147
	v_add3_u32 v207, s54, v154, v150
	v_add3_u32 v239, s54, v154, v151
	v_add3_u32 v241, s54, v154, v148
	v_add3_u32 v243, s54, v154, v146
	ds_read_b128 v[158:161], v0 offset:32768
	ds_read_b128 v[162:165], v0 offset:34816
	ds_read_b128 v[174:177], v157
	ds_read_b128 v[186:189], v207
	ds_read_b128 v[190:193], v238
	ds_read_b128 v[212:215], v239
	ds_read_b128 v[222:225], v240
	ds_read_b128 v[226:229], v241
	ds_read_b128 v[230:233], v242
	ds_read_b128 v[234:237], v243
	ds_read_b128 v[166:169], v0 offset:36864
	ds_read_b128 v[170:173], v0 offset:38912
	v_add_u32_e32 v244, 0x10000, v185
	s_nop 0
	v_readfirstlane_b32 s54, v244
	s_mov_b32 m0, s54
	v_lshl_add_u64 v[208:209], v[130:131], 0, s[0:1]
	global_load_lds_dwordx4 v[208:209], off
	s_add_u32 m0, s54, 0x8000
	v_lshl_add_u64 v[208:209], v[138:139], 0, s[0:1]
	global_load_lds_dwordx4 v[208:209], off
	s_add_u32 m0, s54, 0x2000
	v_lshl_add_u64 v[208:209], v[132:133], 0, s[0:1]
	global_load_lds_dwordx4 v[208:209], off
	s_add_u32 m0, s54, 0xa000
	v_lshl_add_u64 v[208:209], v[140:141], 0, s[0:1]
	global_load_lds_dwordx4 v[208:209], off
	s_add_u32 m0, s54, 0x4000
	v_lshl_add_u64 v[208:209], v[134:135], 0, s[0:1]
	global_load_lds_dwordx4 v[208:209], off
	s_add_u32 m0, s54, 0xc000
	v_lshl_add_u64 v[208:209], v[142:143], 0, s[0:1]
	global_load_lds_dwordx4 v[208:209], off
	s_add_u32 m0, s54, 0x6000
	v_lshl_add_u64 v[208:209], v[136:137], 0, s[0:1]
	global_load_lds_dwordx4 v[208:209], off
	s_add_u32 m0, s54, 0xe000
	v_lshl_add_u64 v[208:209], v[144:145], 0, s[0:1]
	global_load_lds_dwordx4 v[208:209], off
; #define MFMA16(a, b, c) __builtin_amdgcn_mfma_f32_16x16x32_bf16((a), (b), (c), 0, 0, 0)
; template <class Epi>
; DI void gemm8_tile(const bf16_t* __restrict__ Ab, int lda, const bf16_t* __restrict__ Bb, int ldb, int K, int brow, int bcol, const Epi epi,
;                    bool staged, bool has_next, const bf16_t* __restrict__ Abn, const bf16_t* __restrict__ Bbn) {
;     ...
;   for (int t = 0; t < nt; ++t) {
;     const int cur = t & 1;
;     const unsigned char* sa = smem + cur * G8_STAGE_B;
;     const unsigned char* sb = sa + G8_TILE_B;
; #pragma unroll
;     for (int ks = 0; ks < 2; ++ks) {
;       bf16x8 At[8], Bf[4];
;       Bf[0] = *(const bf16x8*)(sb + lds_byte2(wc * 64 + fr, ks * 32 + fq * 8));
;       At[0] = *(const bf16x8*)(sa + lds_byte2(wr * 128 + fr, ks * 32 + fq * 8));
; #pragma unroll
;       for (int n = 1; n < 4; ++n) Bf[n] = *(const bf16x8*)(sb + lds_byte2(wc * 64 + n * 16 + fr, ks * 32 + fq * 8));
; #pragma unroll
;       for (int m = 1; m < 8; ++m) At[m] = *(const bf16x8*)(sa + lds_byte2(wr * 128 + m * 16 + fr, ks * 32 + fq * 8));
;       {
;         __builtin_amdgcn_sched_barrier(0);
;         if (t + 1 < nt) { G8_STAGE_R(cur ^ 1, Ab + (t + 1) * 64, Bb + (t + 1) * 64, 2 * ks, 2 * ks + 2); }
;         else if (has_next) { G8_STAGE_R(0, Abn, Bbn, 2 * ks, 2 * ks + 2); }
;         __builtin_amdgcn_sched_barrier(0);
;       }
; #pragma unroll
;       for (int m = 0; m < 8; ++m)
; #pragma unroll
;         for (int n = 0; n < 4; ++n) acc[m][n] = MFMA16(At[m], Bf[n], acc[m][n]);
;       __builtin_amdgcn_sched_barrier(0);
;     }
;     asm volatile("s_waitcnt vmcnt(0)" ::: "memory");
;     __syncthreads();
;   }
.LBB0_1312:
	s_and_b32 s39, s38, 0x10000
	s_xor_b32 s54, s39, 0x10000
	v_add_u32_e32 v244, s54, v185
	s_nop 0
	v_readfirstlane_b32 s39, v244
	s_waitcnt lgkmcnt(8)
	v_mfma_f32_16x16x32_bf16 v[126:129], v[174:177], v[158:161], v[126:129]
	v_mfma_f32_16x16x32_bf16 v[122:125], v[174:177], v[162:165], v[122:125]
	v_mfma_f32_16x16x32_bf16 v[110:113], v[186:189], v[158:161], v[110:113]
	v_mfma_f32_16x16x32_bf16 v[106:109], v[186:189], v[162:165], v[106:109]
	s_waitcnt lgkmcnt(6)
	v_mfma_f32_16x16x32_bf16 v[94:97], v[190:193], v[158:161], v[94:97]
	v_mfma_f32_16x16x32_bf16 v[90:93], v[190:193], v[162:165], v[90:93]
	v_mfma_f32_16x16x32_bf16 v[78:81], v[212:215], v[158:161], v[78:81]
	v_mfma_f32_16x16x32_bf16 v[74:77], v[212:215], v[162:165], v[74:77]
	s_waitcnt lgkmcnt(4)
	v_mfma_f32_16x16x32_bf16 v[62:65], v[222:225], v[158:161], v[62:65]
	v_mfma_f32_16x16x32_bf16 v[58:61], v[222:225], v[162:165], v[58:61]
	v_mfma_f32_16x16x32_bf16 v[46:49], v[226:229], v[158:161], v[46:49]
	v_mfma_f32_16x16x32_bf16 v[42:45], v[226:229], v[162:165], v[42:45]
	s_waitcnt lgkmcnt(2)
	v_mfma_f32_16x16x32_bf16 v[30:33], v[230:233], v[158:161], v[30:33]
	v_mfma_f32_16x16x32_bf16 v[26:29], v[230:233], v[162:165], v[26:29]
	v_mfma_f32_16x16x32_bf16 v[14:17], v[234:237], v[158:161], v[14:17]
	v_mfma_f32_16x16x32_bf16 v[10:13], v[234:237], v[162:165], v[10:13]
	ds_read_b128 v[158:161], v0 offset:33792
	ds_read_b128 v[162:165], v0 offset:35840
	s_waitcnt lgkmcnt(2)
	v_mfma_f32_16x16x32_bf16 v[118:121], v[174:177], v[166:169], v[118:121]
	v_mfma_f32_16x16x32_bf16 v[114:117], v[174:177], v[170:173], v[114:117]
	ds_read_b128 v[174:177], v157 offset:1024
	v_mfma_f32_16x16x32_bf16 v[102:105], v[186:189], v[166:169], v[102:105]
	v_mfma_f32_16x16x32_bf16 v[98:101], v[186:189], v[170:173], v[98:101]
	ds_read_b128 v[186:189], v207 offset:1024
	v_mfma_f32_16x16x32_bf16 v[86:89], v[190:193], v[166:169], v[86:89]
	v_mfma_f32_16x16x32_bf16 v[82:85], v[190:193], v[170:173], v[82:85]
	ds_read_b128 v[190:193], v238 offset:1024
	v_mfma_f32_16x16x32_bf16 v[70:73], v[212:215], v[166:169], v[70:73]
	v_mfma_f32_16x16x32_bf16 v[66:69], v[212:215], v[170:173], v[66:69]
	ds_read_b128 v[212:215], v239 offset:1024
	v_mfma_f32_16x16x32_bf16 v[54:57], v[222:225], v[166:169], v[54:57]
	v_mfma_f32_16x16x32_bf16 v[50:53], v[222:225], v[170:173], v[50:53]
	ds_read_b128 v[222:225], v240 offset:1024
	v_mfma_f32_16x16x32_bf16 v[38:41], v[226:229], v[166:169], v[38:41]
	v_mfma_f32_16x16x32_bf16 v[34:37], v[226:229], v[170:173], v[34:37]
	ds_read_b128 v[226:229], v241 offset:1024
	v_mfma_f32_16x16x32_bf16 v[22:25], v[230:233], v[166:169], v[22:25]
	v_mfma_f32_16x16x32_bf16 v[18:21], v[230:233], v[170:173], v[18:21]
	ds_read_b128 v[230:233], v242 offset:1024
	v_mfma_f32_16x16x32_bf16 v[6:9], v[234:237], v[166:169], v[6:9]
	v_mfma_f32_16x16x32_bf16 v[2:5], v[234:237], v[170:173], v[2:5]
	ds_read_b128 v[234:237], v243 offset:1024
	ds_read_b128 v[166:169], v0 offset:37888
	ds_read_b128 v[170:173], v0 offset:39936
	s_waitcnt lgkmcnt(8)
	v_mfma_f32_16x16x32_bf16 v[126:129], v[174:177], v[158:161], v[126:129]
	v_mfma_f32_16x16x32_bf16 v[122:125], v[174:177], v[162:165], v[122:125]
	v_add3_u32 v0, s54, v155, v153
	v_mfma_f32_16x16x32_bf16 v[110:113], v[186:189], v[158:161], v[110:113]
	v_mfma_f32_16x16x32_bf16 v[106:109], v[186:189], v[162:165], v[106:109]
	v_add3_u32 v157, s54, v155, v156
	s_waitcnt lgkmcnt(6)
	v_mfma_f32_16x16x32_bf16 v[94:97], v[190:193], v[158:161], v[94:97]
	v_mfma_f32_16x16x32_bf16 v[90:93], v[190:193], v[162:165], v[90:93]
	v_add3_u32 v238, s54, v154, v152
	v_mfma_f32_16x16x32_bf16 v[78:81], v[212:215], v[158:161], v[78:81]
	v_mfma_f32_16x16x32_bf16 v[74:77], v[212:215], v[162:165], v[74:77]
	v_add3_u32 v240, s54, v154, v149
	s_waitcnt lgkmcnt(4)
	v_mfma_f32_16x16x32_bf16 v[62:65], v[222:225], v[158:161], v[62:65]
	v_mfma_f32_16x16x32_bf16 v[58:61], v[222:225], v[162:165], v[58:61]
	v_add3_u32 v242, s54, v154, v147
	v_mfma_f32_16x16x32_bf16 v[46:49], v[226:229], v[158:161], v[46:49]
	v_mfma_f32_16x16x32_bf16 v[42:45], v[226:229], v[162:165], v[42:45]
	v_add3_u32 v207, s54, v154, v150
	s_waitcnt lgkmcnt(2)
	v_mfma_f32_16x16x32_bf16 v[30:33], v[230:233], v[158:161], v[30:33]
	v_mfma_f32_16x16x32_bf16 v[26:29], v[230:233], v[162:165], v[26:29]
	v_add3_u32 v239, s54, v154, v151
	v_mfma_f32_16x16x32_bf16 v[14:17], v[234:237], v[158:161], v[14:17]
	v_mfma_f32_16x16x32_bf16 v[10:13], v[234:237], v[162:165], v[10:13]
	v_add3_u32 v241, s54, v154, v148
	v_add3_u32 v243, s54, v154, v146
	s_waitcnt vmcnt(0) lgkmcnt(0)
	s_barrier
; #define MFMA16(a, b, c) __builtin_amdgcn_mfma_f32_16x16x32_bf16((a), (b), (c), 0, 0, 0)
; template <class Epi>
; DI void gemm8_tile(const bf16_t* __restrict__ Ab, int lda, const bf16_t* __restrict__ Bb, int ldb, int K, int brow, int bcol, const Epi epi,
;                    bool staged, bool has_next, const bf16_t* __restrict__ Abn, const bf16_t* __restrict__ Bbn) {
;     ...
;   for (int t = 0; t < nt; ++t) {
;     const int cur = t & 1;
;     const unsigned char* sa = smem + cur * G8_STAGE_B;
;     const unsigned char* sb = sa + G8_TILE_B;
; #pragma unroll
;     for (int ks = 0; ks < 2; ++ks) {
;       bf16x8 At[8], Bf[4];
;       Bf[0] = *(const bf16x8*)(sb + lds_byte2(wc * 64 + fr, ks * 32 + fq * 8));
;       At[0] = *(const bf16x8*)(sa + lds_byte2(wr * 128 + fr, ks * 32 + fq * 8));
; #pragma unroll
;       for (int n = 1; n < 4; ++n) Bf[n] = *(const bf16x8*)(sb + lds_byte2(wc * 64 + n * 16 + fr, ks * 32 + fq * 8));
; #pragma unroll
;       for (int m = 1; m < 8; ++m) At[m] = *(const bf16x8*)(sa + lds_byte2(wr * 128 + m * 16 + fr, ks * 32 + fq * 8));
;       {
;         __builtin_amdgcn_sched_barrier(0);
;         if (t + 1 < nt) { G8_STAGE_R(cur ^ 1, Ab + (t + 1) * 64, Bb + (t + 1) * 64, 2 * ks, 2 * ks + 2); }
;         else if (has_next) { G8_STAGE_R(0, Abn, Bbn, 2 * ks, 2 * ks + 2); }
;         __builtin_amdgcn_sched_barrier(0);
;       }
; #pragma unroll
;       for (int m = 0; m < 8; ++m)
; #pragma unroll
;         for (int n = 0; n < 4; ++n) acc[m][n] = MFMA16(At[m], Bf[n], acc[m][n]);
;       __builtin_amdgcn_sched_barrier(0);
;     }
;     asm volatile("s_waitcnt vmcnt(0)" ::: "memory");
;     __syncthreads();
;   }
	s_add_u32 s0, s0, 0x80
	s_addc_u32 s1, s1, 0
	s_add_i32 s38, s38, 0x10000
	s_xor_b32 s54, s39, 0x10000
	s_cmpk_eq_i32 s0, 0x780
	s_cbranch_scc1 .Lg80_1312_last
	ds_read_b128 v[158:161], v0 offset:32768
	ds_read_b128 v[162:165], v0 offset:34816
	v_mfma_f32_16x16x32_bf16 v[118:121], v[174:177], v[166:169], v[118:121]
	v_mfma_f32_16x16x32_bf16 v[114:117], v[174:177], v[170:173], v[114:117]
	ds_read_b128 v[174:177], v157
	s_mov_b32 m0, s54
	v_lshl_add_u64 v[208:209], v[130:131], 0, s[0:1]
	global_load_lds_dwordx4 v[208:209], off
	v_mfma_f32_16x16x32_bf16 v[102:105], v[186:189], v[166:169], v[102:105]
	v_mfma_f32_16x16x32_bf16 v[98:101], v[186:189], v[170:173], v[98:101]
	ds_read_b128 v[186:189], v207
	s_add_u32 m0, s54, 0x8000
	v_lshl_add_u64 v[208:209], v[138:139], 0, s[0:1]
	global_load_lds_dwordx4 v[208:209], off
	v_mfma_f32_16x16x32_bf16 v[86:89], v[190:193], v[166:169], v[86:89]
	v_mfma_f32_16x16x32_bf16 v[82:85], v[190:193], v[170:173], v[82:85]
	ds_read_b128 v[190:193], v238
	s_add_u32 m0, s54, 0x2000
	v_lshl_add_u64 v[208:209], v[132:133], 0, s[0:1]
	global_load_lds_dwordx4 v[208:209], off
	v_mfma_f32_16x16x32_bf16 v[70:73], v[212:215], v[166:169], v[70:73]
	v_mfma_f32_16x16x32_bf16 v[66:69], v[212:215], v[170:173], v[66:69]
	ds_read_b128 v[212:215], v239
	s_add_u32 m0, s54, 0xa000
	v_lshl_add_u64 v[208:209], v[140:141], 0, s[0:1]
	global_load_lds_dwordx4 v[208:209], off
	v_mfma_f32_16x16x32_bf16 v[54:57], v[222:225], v[166:169], v[54:57]
	v_mfma_f32_16x16x32_bf16 v[50:53], v[222:225], v[170:173], v[50:53]
	ds_read_b128 v[222:225], v240
	s_add_u32 m0, s54, 0x4000
	v_lshl_add_u64 v[208:209], v[134:135], 0, s[0:1]
	global_load_lds_dwordx4 v[208:209], off
	v_mfma_f32_16x16x32_bf16 v[38:41], v[226:229], v[166:169], v[38:41]
	v_mfma_f32_16x16x32_bf16 v[34:37], v[226:229], v[170:173], v[34:37]
	ds_read_b128 v[226:229], v241
	s_add_u32 m0, s54, 0xc000
	v_lshl_add_u64 v[208:209], v[142:143], 0, s[0:1]
	global_load_lds_dwordx4 v[208:209], off
	v_mfma_f32_16x16x32_bf16 v[22:25], v[230:233], v[166:169], v[22:25]
	v_mfma_f32_16x16x32_bf16 v[18:21], v[230:233], v[170:173], v[18:21]
	ds_read_b128 v[230:233], v242
	s_add_u32 m0, s54, 0x6000
	v_lshl_add_u64 v[208:209], v[136:137], 0, s[0:1]
	global_load_lds_dwordx4 v[208:209], off
	v_mfma_f32_16x16x32_bf16 v[6:9], v[234:237], v[166:169], v[6:9]
	v_mfma_f32_16x16x32_bf16 v[2:5], v[234:237], v[170:173], v[2:5]
	ds_read_b128 v[234:237], v243
	s_add_u32 m0, s54, 0xe000
	v_lshl_add_u64 v[208:209], v[144:145], 0, s[0:1]
	global_load_lds_dwordx4 v[208:209], off
	ds_read_b128 v[166:169], v0 offset:36864
	ds_read_b128 v[170:173], v0 offset:38912
	s_branch .LBB0_1312

; DI int opaque_tid512() { int t = threadIdx.x; asm volatile("" : "+v"(t)); return t; }
; #define G8_STAGE(buf_, ap_, bp_) G8_STAGE_R(buf_, ap_, bp_, 0, 4)
; template <class Epi>
; DI void gemm8_tile(const bf16_t* __restrict__ Ab, int lda, const bf16_t* __restrict__ Bb, int ldb, int K, int brow, int bcol, const Epi epi,
;                    bool staged, bool has_next, const bf16_t* __restrict__ Abn, const bf16_t* __restrict__ Bbn) {
;   const int tid = opaque_tid512(), wid = tid >> 6, lane = tid & 63, wr = wid >> 2, wc = wid & 3, fr = lane & 15, fq = lane >> 4;
;   unsigned aoff[4], boff[4];
; #pragma unroll
;   for (int i = 0; i < 4; ++i) { int R, C; stage_rc2(wid * 1024 + i * 8192 + lane * 16, R, C); aoff[i] = (unsigned)R * (unsigned)lda + (unsigned)C; boff[i] = (unsigned)R * (unsigned)ldb + (unsigned)C; }
;     ...
;   f32x4 acc[8][4];
; #pragma unroll
;   for (int m = 0; m < 8; ++m)
; #pragma unroll
;     for (int n = 0; n < 4; ++n) acc[m][n] = (f32x4){0.f, 0.f, 0.f, 0.f};
;   const int nt = K / 64;
;   if (!staged) {
;     G8_STAGE(0, Ab, Bb);
;     asm volatile("s_waitcnt vmcnt(0)" ::: "memory");
;     __syncthreads();
;   }
.LBB0_1509:
	s_lshl_b32 s14, s75, 3
	s_add_i32 s14, s28, s14
	s_add_i32 s14, s14, s78
	s_lshl_b32 s15, s74, 3
	s_sub_i32 s14, s14, s15
	s_lshl_b32 s15, s14, 8
	s_add_u32 s0, s91, s0
	s_mul_i32 s14, s14, 0x88000
	s_addc_u32 s1, s72, s1
	v_and_b32_e32 v200, 15, v2
	s_mul_hi_i32 s15, s15, 0x880
	s_add_u32 s0, s0, s14
	v_and_b32_e32 v208, 63, v2
	v_ashrrev_i32_e32 v4, 8, v2
	v_and_b32_e32 v206, 3, v3
	v_and_b32_e32 v3, 48, v2
	v_lshlrev_b32_e32 v201, 2, v200
	v_lshlrev_b32_e32 v2, 6, v2
	s_addc_u32 s1, s1, s15
	v_and_b32_e32 v6, 32, v201
	v_and_b32_e32 v2, 0x3c0, v2
	v_lshl_add_u64 v[130:131], v[178:179], 1, s[0:1]
	v_lshl_add_u64 v[132:133], v[182:183], 1, s[0:1]
	v_lshl_add_u64 v[134:135], v[194:195], 1, s[0:1]
	v_lshl_add_u64 v[136:137], v[198:199], 1, s[0:1]
	s_add_u32 s0, s59, s9
	v_lshlrev_b32_e32 v5, 6, v200
	v_lshlrev_b32_e32 v156, 14, v4
	v_bitop3_b32 v154, v2, v6, v3 bitop3:0x36
	s_addc_u32 s1, s70, s79
	v_mov_b32_e32 v2, 0
	v_lshlrev_b32_e32 v153, 13, v206
	v_bitop3_b32 v155, v5, v6, v3 bitop3:0x36
	v_lshlrev_b32_e32 v207, 7, v4
	v_or_b32_e32 v150, 0x800, v156
	v_or_b32_e32 v152, 0x1000, v156
	v_or_b32_e32 v151, 0x1800, v156
	v_or_b32_e32 v149, 0x2000, v156
	v_or_b32_e32 v148, 0x2800, v156
	v_or_b32_e32 v147, 0x3000, v156
	v_or_b32_e32 v146, 0x3800, v156
	v_lshl_add_u64 v[138:139], v[180:181], 1, s[0:1]
	v_lshl_add_u64 v[140:141], v[184:185], 1, s[0:1]
	v_lshl_add_u64 v[142:143], v[196:197], 1, s[0:1]
	v_lshl_add_u64 v[144:145], v[0:1], 1, s[0:1]
	s_mov_b64 s[0:1], 0
	s_mov_b32 s9, 0
	v_mov_b32_e32 v3, v2
	v_mov_b32_e32 v4, v2
	v_mov_b32_e32 v5, v2
	v_mov_b32_e32 v6, v2
	v_mov_b32_e32 v7, v2
	v_mov_b32_e32 v8, v2
	v_mov_b32_e32 v9, v2
	v_mov_b32_e32 v10, v2
	v_mov_b32_e32 v11, v2
	v_mov_b32_e32 v12, v2
	v_mov_b32_e32 v13, v2
	v_mov_b32_e32 v14, v2
	v_mov_b32_e32 v15, v2
	v_mov_b32_e32 v16, v2
	v_mov_b32_e32 v17, v2
	v_mov_b32_e32 v18, v2
	v_mov_b32_e32 v19, v2
	v_mov_b32_e32 v20, v2
	v_mov_b32_e32 v21, v2
	v_mov_b32_e32 v22, v2
	v_mov_b32_e32 v23, v2
	v_mov_b32_e32 v24, v2
	v_mov_b32_e32 v25, v2
	v_mov_b32_e32 v26, v2
	v_mov_b32_e32 v27, v2
	v_mov_b32_e32 v28, v2
	v_mov_b32_e32 v29, v2
	v_mov_b32_e32 v30, v2
	v_mov_b32_e32 v31, v2
	v_mov_b32_e32 v32, v2
	v_mov_b32_e32 v33, v2
	v_mov_b32_e32 v34, v2
	v_mov_b32_e32 v35, v2
	v_mov_b32_e32 v36, v2
	v_mov_b32_e32 v37, v2
	v_mov_b32_e32 v38, v2
	v_mov_b32_e32 v39, v2
	v_mov_b32_e32 v40, v2
	v_mov_b32_e32 v41, v2
	v_mov_b32_e32 v42, v2
	v_mov_b32_e32 v43, v2
	v_mov_b32_e32 v44, v2
	v_mov_b32_e32 v45, v2
	v_mov_b32_e32 v46, v2
	v_mov_b32_e32 v47, v2
	v_mov_b32_e32 v48, v2
	v_mov_b32_e32 v49, v2
	v_mov_b32_e32 v50, v2
	v_mov_b32_e32 v51, v2
	v_mov_b32_e32 v52, v2
	v_mov_b32_e32 v53, v2
	v_mov_b32_e32 v54, v2
	v_mov_b32_e32 v55, v2
	v_mov_b32_e32 v56, v2
	v_mov_b32_e32 v57, v2
	v_mov_b32_e32 v58, v2
	v_mov_b32_e32 v59, v2
	v_mov_b32_e32 v60, v2
	v_mov_b32_e32 v61, v2
	v_mov_b32_e32 v62, v2
	v_mov_b32_e32 v63, v2
	v_mov_b32_e32 v64, v2
	v_mov_b32_e32 v65, v2
	s_waitcnt vmcnt(8)
	v_mov_b32_e32 v66, v2
	v_mov_b32_e32 v67, v2
	v_mov_b32_e32 v68, v2
	v_mov_b32_e32 v69, v2
	v_mov_b32_e32 v70, v2
	v_mov_b32_e32 v71, v2
	v_mov_b32_e32 v72, v2
	v_mov_b32_e32 v73, v2
	v_mov_b32_e32 v74, v2
	v_mov_b32_e32 v75, v2
	v_mov_b32_e32 v76, v2
	v_mov_b32_e32 v77, v2
	v_mov_b32_e32 v78, v2
	v_mov_b32_e32 v79, v2
	v_mov_b32_e32 v80, v2
	v_mov_b32_e32 v81, v2
	v_mov_b32_e32 v82, v2
	v_mov_b32_e32 v83, v2
	v_mov_b32_e32 v84, v2
	v_mov_b32_e32 v85, v2
	v_mov_b32_e32 v86, v2
	v_mov_b32_e32 v87, v2
	v_mov_b32_e32 v88, v2
	v_mov_b32_e32 v89, v2
	v_mov_b32_e32 v90, v2
	v_mov_b32_e32 v91, v2
	v_mov_b32_e32 v92, v2
	v_mov_b32_e32 v93, v2
	v_mov_b32_e32 v94, v2
	v_mov_b32_e32 v95, v2
	v_mov_b32_e32 v96, v2
	v_mov_b32_e32 v97, v2
	v_mov_b32_e32 v98, v2
	v_mov_b32_e32 v99, v2
	v_mov_b32_e32 v100, v2
	v_mov_b32_e32 v101, v2
	v_mov_b32_e32 v102, v2
	v_mov_b32_e32 v103, v2
	v_mov_b32_e32 v104, v2
	v_mov_b32_e32 v105, v2
	v_mov_b32_e32 v106, v2
	v_mov_b32_e32 v107, v2
	v_mov_b32_e32 v108, v2
	v_mov_b32_e32 v109, v2
	v_mov_b32_e32 v110, v2
	v_mov_b32_e32 v111, v2
	v_mov_b32_e32 v112, v2
	v_mov_b32_e32 v113, v2
	v_mov_b32_e32 v114, v2
	v_mov_b32_e32 v115, v2
	v_mov_b32_e32 v116, v2
	v_mov_b32_e32 v117, v2
	v_mov_b32_e32 v118, v2
	v_mov_b32_e32 v119, v2
	v_mov_b32_e32 v120, v2
	v_mov_b32_e32 v121, v2
	v_mov_b32_e32 v122, v2
	v_mov_b32_e32 v123, v2
	v_mov_b32_e32 v124, v2
	v_mov_b32_e32 v125, v2
	v_mov_b32_e32 v126, v2
	v_mov_b32_e32 v127, v2
	v_mov_b32_e32 v128, v2
	v_mov_b32_e32 v129, v2
	s_mov_b32 s15, 0
	v_add3_u32 v157, s15, v155, v153
	v_add3_u32 v209, s15, v155, v156
	v_add3_u32 v245, s15, v154, v152
	v_add3_u32 v247, s15, v154, v149
	v_add3_u32 v249, s15, v154, v147
	v_add3_u32 v244, s15, v154, v150
	v_add3_u32 v246, s15, v154, v151
	v_add3_u32 v248, s15, v154, v148
	v_add3_u32 v250, s15, v154, v146
	ds_read_b128 v[158:161], v157 offset:32768
	ds_read_b128 v[162:165], v157 offset:34816
	ds_read_b128 v[174:177], v209
	ds_read_b128 v[190:193], v244
	ds_read_b128 v[212:215], v245
	ds_read_b128 v[222:225], v246
	ds_read_b128 v[226:229], v247
	ds_read_b128 v[230:233], v248
	ds_read_b128 v[234:237], v249
	ds_read_b128 v[238:241], v250
	ds_read_b128 v[166:169], v157 offset:36864
	ds_read_b128 v[170:173], v157 offset:38912
	v_add_u32_e32 v251, 0x10000, v189
	s_nop 0
	v_readfirstlane_b32 s15, v251
	s_mov_b32 m0, s15
	v_lshl_add_u64 v[242:243], v[130:131], 0, s[0:1]
	global_load_lds_dwordx4 v[242:243], off
	s_add_u32 m0, s15, 0x8000
	v_lshl_add_u64 v[242:243], v[138:139], 0, s[0:1]
	global_load_lds_dwordx4 v[242:243], off
	s_add_u32 m0, s15, 0x2000
	v_lshl_add_u64 v[242:243], v[132:133], 0, s[0:1]
	global_load_lds_dwordx4 v[242:243], off
	s_add_u32 m0, s15, 0xa000
	v_lshl_add_u64 v[242:243], v[140:141], 0, s[0:1]
	global_load_lds_dwordx4 v[242:243], off
	s_add_u32 m0, s15, 0x4000
	v_lshl_add_u64 v[242:243], v[134:135], 0, s[0:1]
	global_load_lds_dwordx4 v[242:243], off
	s_add_u32 m0, s15, 0xc000
	v_lshl_add_u64 v[242:243], v[142:143], 0, s[0:1]
	global_load_lds_dwordx4 v[242:243], off
	s_add_u32 m0, s15, 0x6000
	v_lshl_add_u64 v[242:243], v[136:137], 0, s[0:1]
	global_load_lds_dwordx4 v[242:243], off
	s_add_u32 m0, s15, 0xe000
	v_lshl_add_u64 v[242:243], v[144:145], 0, s[0:1]
	global_load_lds_dwordx4 v[242:243], off
; #define MFMA16(a, b, c) __builtin_amdgcn_mfma_f32_16x16x32_bf16((a), (b), (c), 0, 0, 0)
; template <class Epi>
; DI void gemm8_tile(const bf16_t* __restrict__ Ab, int lda, const bf16_t* __restrict__ Bb, int ldb, int K, int brow, int bcol, const Epi epi,
;                    bool staged, bool has_next, const bf16_t* __restrict__ Abn, const bf16_t* __restrict__ Bbn) {
;     ...
;   for (int t = 0; t < nt; ++t) {
;     const int cur = t & 1;
;     const unsigned char* sa = smem + cur * G8_STAGE_B;
;     const unsigned char* sb = sa + G8_TILE_B;
; #pragma unroll
;     for (int ks = 0; ks < 2; ++ks) {
;       bf16x8 At[8], Bf[4];
;       Bf[0] = *(const bf16x8*)(sb + lds_byte2(wc * 64 + fr, ks * 32 + fq * 8));
;       At[0] = *(const bf16x8*)(sa + lds_byte2(wr * 128 + fr, ks * 32 + fq * 8));
; #pragma unroll
;       for (int n = 1; n < 4; ++n) Bf[n] = *(const bf16x8*)(sb + lds_byte2(wc * 64 + n * 16 + fr, ks * 32 + fq * 8));
; #pragma unroll
;       for (int m = 1; m < 8; ++m) At[m] = *(const bf16x8*)(sa + lds_byte2(wr * 128 + m * 16 + fr, ks * 32 + fq * 8));
;       {
;         __builtin_amdgcn_sched_barrier(0);
;         if (t + 1 < nt) { G8_STAGE_R(cur ^ 1, Ab + (t + 1) * 64, Bb + (t + 1) * 64, 2 * ks, 2 * ks + 2); }
;         else if (has_next) { G8_STAGE_R(0, Abn, Bbn, 2 * ks, 2 * ks + 2); }
;         __builtin_amdgcn_sched_barrier(0);
;       }
; #pragma unroll
;       for (int m = 0; m < 8; ++m)
; #pragma unroll
;         for (int n = 0; n < 4; ++n) acc[m][n] = MFMA16(At[m], Bf[n], acc[m][n]);
;       __builtin_amdgcn_sched_barrier(0);
;     }
;     asm volatile("s_waitcnt vmcnt(0)" ::: "memory");
;     __syncthreads();
;   }
.LBB0_1510:
	s_and_b32 s14, s9, 0x10000
	s_xor_b32 s15, s14, 0x10000
	v_add_u32_e32 v251, s15, v189
	s_nop 0
	v_readfirstlane_b32 s14, v251
	s_waitcnt lgkmcnt(8)
	v_mfma_f32_16x16x32_bf16 v[126:129], v[174:177], v[158:161], v[126:129]
	v_mfma_f32_16x16x32_bf16 v[122:125], v[174:177], v[162:165], v[122:125]
	v_mfma_f32_16x16x32_bf16 v[110:113], v[190:193], v[158:161], v[110:113]
	v_mfma_f32_16x16x32_bf16 v[106:109], v[190:193], v[162:165], v[106:109]
	s_waitcnt lgkmcnt(6)
	v_mfma_f32_16x16x32_bf16 v[94:97], v[212:215], v[158:161], v[94:97]
	v_mfma_f32_16x16x32_bf16 v[90:93], v[212:215], v[162:165], v[90:93]
	v_mfma_f32_16x16x32_bf16 v[78:81], v[222:225], v[158:161], v[78:81]
	v_mfma_f32_16x16x32_bf16 v[74:77], v[222:225], v[162:165], v[74:77]
	s_waitcnt lgkmcnt(4)
	v_mfma_f32_16x16x32_bf16 v[62:65], v[226:229], v[158:161], v[62:65]
	v_mfma_f32_16x16x32_bf16 v[58:61], v[226:229], v[162:165], v[58:61]
	v_mfma_f32_16x16x32_bf16 v[46:49], v[230:233], v[158:161], v[46:49]
	v_mfma_f32_16x16x32_bf16 v[42:45], v[230:233], v[162:165], v[42:45]
	s_waitcnt lgkmcnt(2)
	v_mfma_f32_16x16x32_bf16 v[30:33], v[234:237], v[158:161], v[30:33]
	v_mfma_f32_16x16x32_bf16 v[26:29], v[234:237], v[162:165], v[26:29]
	v_mfma_f32_16x16x32_bf16 v[14:17], v[238:241], v[158:161], v[14:17]
	v_mfma_f32_16x16x32_bf16 v[10:13], v[238:241], v[162:165], v[10:13]
	ds_read_b128 v[158:161], v157 offset:33792
	ds_read_b128 v[162:165], v157 offset:35840
	s_waitcnt lgkmcnt(2)
	v_mfma_f32_16x16x32_bf16 v[118:121], v[174:177], v[166:169], v[118:121]
	v_mfma_f32_16x16x32_bf16 v[114:117], v[174:177], v[170:173], v[114:117]
	ds_read_b128 v[174:177], v209 offset:1024
	v_mfma_f32_16x16x32_bf16 v[102:105], v[190:193], v[166:169], v[102:105]
	v_mfma_f32_16x16x32_bf16 v[98:101], v[190:193], v[170:173], v[98:101]
	ds_read_b128 v[190:193], v244 offset:1024
	v_mfma_f32_16x16x32_bf16 v[86:89], v[212:215], v[166:169], v[86:89]
	v_mfma_f32_16x16x32_bf16 v[82:85], v[212:215], v[170:173], v[82:85]
	ds_read_b128 v[212:215], v245 offset:1024
	v_mfma_f32_16x16x32_bf16 v[70:73], v[222:225], v[166:169], v[70:73]
	v_mfma_f32_16x16x32_bf16 v[66:69], v[222:225], v[170:173], v[66:69]
	ds_read_b128 v[222:225], v246 offset:1024
	v_mfma_f32_16x16x32_bf16 v[54:57], v[226:229], v[166:169], v[54:57]
	v_mfma_f32_16x16x32_bf16 v[50:53], v[226:229], v[170:173], v[50:53]
	ds_read_b128 v[226:229], v247 offset:1024
	v_mfma_f32_16x16x32_bf16 v[38:41], v[230:233], v[166:169], v[38:41]
	v_mfma_f32_16x16x32_bf16 v[34:37], v[230:233], v[170:173], v[34:37]
	ds_read_b128 v[230:233], v248 offset:1024
	v_mfma_f32_16x16x32_bf16 v[22:25], v[234:237], v[166:169], v[22:25]
	v_mfma_f32_16x16x32_bf16 v[18:21], v[234:237], v[170:173], v[18:21]
	ds_read_b128 v[234:237], v249 offset:1024
	v_mfma_f32_16x16x32_bf16 v[6:9], v[238:241], v[166:169], v[6:9]
	v_mfma_f32_16x16x32_bf16 v[2:5], v[238:241], v[170:173], v[2:5]
	ds_read_b128 v[238:241], v250 offset:1024
	ds_read_b128 v[166:169], v157 offset:37888
	ds_read_b128 v[170:173], v157 offset:39936
	s_waitcnt lgkmcnt(8)
	v_mfma_f32_16x16x32_bf16 v[126:129], v[174:177], v[158:161], v[126:129]
	v_mfma_f32_16x16x32_bf16 v[122:125], v[174:177], v[162:165], v[122:125]
	v_add3_u32 v157, s15, v155, v153
	v_mfma_f32_16x16x32_bf16 v[110:113], v[190:193], v[158:161], v[110:113]
	v_mfma_f32_16x16x32_bf16 v[106:109], v[190:193], v[162:165], v[106:109]
	v_add3_u32 v209, s15, v155, v156
	s_waitcnt lgkmcnt(6)
	v_mfma_f32_16x16x32_bf16 v[94:97], v[212:215], v[158:161], v[94:97]
	v_mfma_f32_16x16x32_bf16 v[90:93], v[212:215], v[162:165], v[90:93]
	v_add3_u32 v245, s15, v154, v152
	v_mfma_f32_16x16x32_bf16 v[78:81], v[222:225], v[158:161], v[78:81]
	v_mfma_f32_16x16x32_bf16 v[74:77], v[222:225], v[162:165], v[74:77]
	v_add3_u32 v247, s15, v154, v149
	s_waitcnt lgkmcnt(4)
	v_mfma_f32_16x16x32_bf16 v[62:65], v[226:229], v[158:161], v[62:65]
	v_mfma_f32_16x16x32_bf16 v[58:61], v[226:229], v[162:165], v[58:61]
	v_add3_u32 v249, s15, v154, v147
	v_mfma_f32_16x16x32_bf16 v[46:49], v[230:233], v[158:161], v[46:49]
	v_mfma_f32_16x16x32_bf16 v[42:45], v[230:233], v[162:165], v[42:45]
	v_add3_u32 v244, s15, v154, v150
	s_waitcnt lgkmcnt(2)
	v_mfma_f32_16x16x32_bf16 v[30:33], v[234:237], v[158:161], v[30:33]
	v_mfma_f32_16x16x32_bf16 v[26:29], v[234:237], v[162:165], v[26:29]
	v_add3_u32 v246, s15, v154, v151
	v_mfma_f32_16x16x32_bf16 v[14:17], v[238:241], v[158:161], v[14:17]
	v_mfma_f32_16x16x32_bf16 v[10:13], v[238:241], v[162:165], v[10:13]
	v_add3_u32 v248, s15, v154, v148
	v_add3_u32 v250, s15, v154, v146
	s_waitcnt vmcnt(0) lgkmcnt(0)
	s_barrier
	s_add_u32 s0, s0, 0x80
	s_addc_u32 s1, s1, 0
	s_add_i32 s9, s9, 0x10000
	s_xor_b32 s15, s14, 0x10000
	s_cmpk_eq_i32 s0, 0x180
	s_cbranch_scc1 .Lg80_1510_last
; #define MFMA16(a, b, c) __builtin_amdgcn_mfma_f32_16x16x32_bf16((a), (b), (c), 0, 0, 0)
; template <class Epi>
; DI void gemm8_tile(const bf16_t* __restrict__ Ab, int lda, const bf16_t* __restrict__ Bb, int ldb, int K, int brow, int bcol, const Epi epi,
;                    bool staged, bool has_next, const bf16_t* __restrict__ Abn, const bf16_t* __restrict__ Bbn) {
;     ...
;   for (int t = 0; t < nt; ++t) {
;     const int cur = t & 1;
;     const unsigned char* sa = smem + cur * G8_STAGE_B;
;     const unsigned char* sb = sa + G8_TILE_B;
; #pragma unroll
;     for (int ks = 0; ks < 2; ++ks) {
;       bf16x8 At[8], Bf[4];
;       Bf[0] = *(const bf16x8*)(sb + lds_byte2(wc * 64 + fr, ks * 32 + fq * 8));
;       At[0] = *(const bf16x8*)(sa + lds_byte2(wr * 128 + fr, ks * 32 + fq * 8));
; #pragma unroll
;       for (int n = 1; n < 4; ++n) Bf[n] = *(const bf16x8*)(sb + lds_byte2(wc * 64 + n * 16 + fr, ks * 32 + fq * 8));
; #pragma unroll
;       for (int m = 1; m < 8; ++m) At[m] = *(const bf16x8*)(sa + lds_byte2(wr * 128 + m * 16 + fr, ks * 32 + fq * 8));
;       {
;         __builtin_amdgcn_sched_barrier(0);
;         if (t + 1 < nt) { G8_STAGE_R(cur ^ 1, Ab + (t + 1) * 64, Bb + (t + 1) * 64, 2 * ks, 2 * ks + 2); }
;         else if (has_next) { G8_STAGE_R(0, Abn, Bbn, 2 * ks, 2 * ks + 2); }
;         __builtin_amdgcn_sched_barrier(0);
;       }
; #pragma unroll
;       for (int m = 0; m < 8; ++m)
; #pragma unroll
;         for (int n = 0; n < 4; ++n) acc[m][n] = MFMA16(At[m], Bf[n], acc[m][n]);
;       __builtin_amdgcn_sched_barrier(0);
;     }
;     asm volatile("s_waitcnt vmcnt(0)" ::: "memory");
;     __syncthreads();
;   }
	ds_read_b128 v[158:161], v157 offset:32768
	ds_read_b128 v[162:165], v157 offset:34816
	v_mfma_f32_16x16x32_bf16 v[118:121], v[174:177], v[166:169], v[118:121]
	v_mfma_f32_16x16x32_bf16 v[114:117], v[174:177], v[170:173], v[114:117]
	ds_read_b128 v[174:177], v209
	s_mov_b32 m0, s15
	v_lshl_add_u64 v[242:243], v[130:131], 0, s[0:1]
	global_load_lds_dwordx4 v[242:243], off
	v_mfma_f32_16x16x32_bf16 v[102:105], v[190:193], v[166:169], v[102:105]
	v_mfma_f32_16x16x32_bf16 v[98:101], v[190:193], v[170:173], v[98:101]
	ds_read_b128 v[190:193], v244
	s_add_u32 m0, s15, 0x8000
	v_lshl_add_u64 v[242:243], v[138:139], 0, s[0:1]
	global_load_lds_dwordx4 v[242:243], off
	v_mfma_f32_16x16x32_bf16 v[86:89], v[212:215], v[166:169], v[86:89]
	v_mfma_f32_16x16x32_bf16 v[82:85], v[212:215], v[170:173], v[82:85]
	ds_read_b128 v[212:215], v245
	s_add_u32 m0, s15, 0x2000
	v_lshl_add_u64 v[242:243], v[132:133], 0, s[0:1]
	global_load_lds_dwordx4 v[242:243], off
	v_mfma_f32_16x16x32_bf16 v[70:73], v[222:225], v[166:169], v[70:73]
	v_mfma_f32_16x16x32_bf16 v[66:69], v[222:225], v[170:173], v[66:69]
	ds_read_b128 v[222:225], v246
	s_add_u32 m0, s15, 0xa000
	v_lshl_add_u64 v[242:243], v[140:141], 0, s[0:1]
	global_load_lds_dwordx4 v[242:243], off
	v_mfma_f32_16x16x32_bf16 v[54:57], v[226:229], v[166:169], v[54:57]
	v_mfma_f32_16x16x32_bf16 v[50:53], v[226:229], v[170:173], v[50:53]
	ds_read_b128 v[226:229], v247
	s_add_u32 m0, s15, 0x4000
	v_lshl_add_u64 v[242:243], v[134:135], 0, s[0:1]
	global_load_lds_dwordx4 v[242:243], off
	v_mfma_f32_16x16x32_bf16 v[38:41], v[230:233], v[166:169], v[38:41]
	v_mfma_f32_16x16x32_bf16 v[34:37], v[230:233], v[170:173], v[34:37]
	ds_read_b128 v[230:233], v248
	s_add_u32 m0, s15, 0xc000
	v_lshl_add_u64 v[242:243], v[142:143], 0, s[0:1]
	global_load_lds_dwordx4 v[242:243], off
	v_mfma_f32_16x16x32_bf16 v[22:25], v[234:237], v[166:169], v[22:25]
	v_mfma_f32_16x16x32_bf16 v[18:21], v[234:237], v[170:173], v[18:21]
	ds_read_b128 v[234:237], v249
	s_add_u32 m0, s15, 0x6000
	v_lshl_add_u64 v[242:243], v[136:137], 0, s[0:1]
	global_load_lds_dwordx4 v[242:243], off
	v_mfma_f32_16x16x32_bf16 v[6:9], v[238:241], v[166:169], v[6:9]
	v_mfma_f32_16x16x32_bf16 v[2:5], v[238:241], v[170:173], v[2:5]
	ds_read_b128 v[238:241], v250
	s_add_u32 m0, s15, 0xe000
	v_lshl_add_u64 v[242:243], v[144:145], 0, s[0:1]
	global_load_lds_dwordx4 v[242:243], off
	ds_read_b128 v[166:169], v157 offset:36864
	ds_read_b128 v[170:173], v157 offset:38912
	s_branch .LBB0_1510
.Lg80_1510_last:
	ds_read_b128 v[158:161], v157 offset:32768
	ds_read_b128 v[162:165], v157 offset:34816
	v_mfma_f32_16x16x32_bf16 v[118:121], v[174:177], v[166:169], v[118:121]
	v_mfma_f32_16x16x32_bf16 v[114:117], v[174:177], v[170:173], v[114:117]
	ds_read_b128 v[174:177], v209
	v_mfma_f32_16x16x32_bf16 v[102:105], v[190:193], v[166:169], v[102:105]
	v_mfma_f32_16x16x32_bf16 v[98:101], v[190:193], v[170:173], v[98:101]
	ds_read_b128 v[190:193], v244
	v_mfma_f32_16x16x32_bf16 v[86:89], v[212:215], v[166:169], v[86:89]
	v_mfma_f32_16x16x32_bf16 v[82:85], v[212:215], v[170:173], v[82:85]
	ds_read_b128 v[212:215], v245
	v_mfma_f32_16x16x32_bf16 v[70:73], v[222:225], v[166:169], v[70:73]
	v_mfma_f32_16x16x32_bf16 v[66:69], v[222:225], v[170:173], v[66:69]
	ds_read_b128 v[222:225], v246
	v_mfma_f32_16x16x32_bf16 v[54:57], v[226:229], v[166:169], v[54:57]
	v_mfma_f32_16x16x32_bf16 v[50:53], v[226:229], v[170:173], v[50:53]
	ds_read_b128 v[226:229], v247
	v_mfma_f32_16x16x32_bf16 v[38:41], v[230:233], v[166:169], v[38:41]
	v_mfma_f32_16x16x32_bf16 v[34:37], v[230:233], v[170:173], v[34:37]
	ds_read_b128 v[230:233], v248
	v_mfma_f32_16x16x32_bf16 v[22:25], v[234:237], v[166:169], v[22:25]
	v_mfma_f32_16x16x32_bf16 v[18:21], v[234:237], v[170:173], v[18:21]
	ds_read_b128 v[234:237], v249
	v_mfma_f32_16x16x32_bf16 v[6:9], v[238:241], v[166:169], v[6:9]
	v_mfma_f32_16x16x32_bf16 v[2:5], v[238:241], v[170:173], v[2:5]
	ds_read_b128 v[238:241], v250
	ds_read_b128 v[166:169], v157 offset:36864
	ds_read_b128 v[170:173], v157 offset:38912
	s_waitcnt lgkmcnt(0)
	s_add_i32 s0, 0, 0x18000
	v_add_u32_e32 v130, s0, v155
	v_add_u32_e32 v190, v130, v153
	v_add_u32_e32 v130, s30, v155
	v_add_u32_e32 v191, v130, v156
	ds_read_b128 v[130:133], v190
	ds_read_b128 v[134:137], v190 offset:2048
	ds_read_b128 v[138:141], v190 offset:4096
	ds_read_b128 v[142:145], v190 offset:6144
	v_add_u32_e32 v154, s30, v154
	v_add_u32_e32 v193, v154, v152
	v_add_u32_e32 v212, v154, v149
	v_add_u32_e32 v214, v154, v147
	v_add_u32_e32 v192, v154, v150
	ds_read_b128 v[174:177], v191
	ds_read_b128 v[166:169], v192
	v_add_u32_e32 v209, v154, v151
	ds_read_b128 v[170:173], v193
	ds_read_b128 v[158:161], v209
	v_add_u32_e32 v213, v154, v148
	ds_read_b128 v[162:165], v212
	ds_read_b128 v[150:153], v213
	v_add_u32_e32 v215, v154, v146
	ds_read_b128 v[154:157], v214
	ds_read_b128 v[146:149], v215
	v_cndmask_b32_e64 v222, 0, 1, s[38:39]
	v_cmp_ne_u32_e64 s[0:1], 1, v222
	s_andn2_b64 vcc, exec, s[38:39]
	s_movk_i32 s79, 0xffe0
	s_cbranch_vccnz .LBB0_1513
	v_readfirstlane_b32 s9, v189
	v_lshl_add_u64 v[178:179], v[178:179], 1, s[10:11]
	s_mov_b32 m0, s9
	v_readfirstlane_b32 s9, v188
	v_lshl_add_u64 v[180:181], v[180:181], 1, s[12:13]
	global_load_lds_dwordx4 v[178:179], off
	s_mov_b32 m0, s9
	v_readfirstlane_b32 s9, v187
	v_lshl_add_u64 v[182:183], v[182:183], 1, s[10:11]
	global_load_lds_dwordx4 v[180:181], off
	s_mov_b32 m0, s9
	v_readfirstlane_b32 s9, v186
	v_lshl_add_u64 v[184:185], v[184:185], 1, s[12:13]
	global_load_lds_dwordx4 v[182:183], off
	s_mov_b32 m0, s9
	s_nop 0
	global_load_lds_dwordx4 v[184:185], off

; DI int opaque_tid512() { int t = threadIdx.x; asm volatile("" : "+v"(t)); return t; }
; #define G8_STAGE(buf_, ap_, bp_) G8_STAGE_R(buf_, ap_, bp_, 0, 4)
; template <class Epi>
; DI void gemm8_tile(const bf16_t* __restrict__ Ab, int lda, const bf16_t* __restrict__ Bb, int ldb, int K, int brow, int bcol, const Epi epi,
;                    bool staged, bool has_next, const bf16_t* __restrict__ Abn, const bf16_t* __restrict__ Bbn) {
;   const int tid = opaque_tid512(), wid = tid >> 6, lane = tid & 63, wr = wid >> 2, wc = wid & 3, fr = lane & 15, fq = lane >> 4;
;   unsigned aoff[4], boff[4];
; #pragma unroll
;   for (int i = 0; i < 4; ++i) { int R, C; stage_rc2(wid * 1024 + i * 8192 + lane * 16, R, C); aoff[i] = (unsigned)R * (unsigned)lda + (unsigned)C; boff[i] = (unsigned)R * (unsigned)ldb + (unsigned)C; }
;     ...
;   f32x4 acc[8][4];
; #pragma unroll
;   for (int m = 0; m < 8; ++m)
; #pragma unroll
;     for (int n = 0; n < 4; ++n) acc[m][n] = (f32x4){0.f, 0.f, 0.f, 0.f};
;   const int nt = K / 64;
;   if (!staged) {
;     G8_STAGE(0, Ab, Bb);
;     asm volatile("s_waitcnt vmcnt(0)" ::: "memory");
;     __syncthreads();
;   }
.LBB0_1672:
	v_readlane_b32 s0, v253, 23
	s_add_u32 s0, s0, s57
	v_readlane_b32 s1, v253, 24
	v_lshlrev_b64 v[212:213], 1, v[0:1]
	s_addc_u32 s1, s1, s58
	v_lshlrev_b64 v[214:215], 1, v[6:7]
	v_lshlrev_b64 v[146:147], 1, v[4:5]
	v_lshlrev_b64 v[148:149], 1, v[2:3]
	v_lshl_add_u64 v[130:131], s[0:1], 0, v[212:213]
	v_lshl_add_u64 v[132:133], s[0:1], 0, v[214:215]
	v_lshl_add_u64 v[134:135], s[0:1], 0, v[146:147]
	v_lshl_add_u64 v[136:137], s[0:1], 0, v[148:149]
	s_lshl_b32 s0, s55, 3
	s_add_i32 s0, s28, s0
	s_add_i32 s0, s0, s56
	s_lshl_b32 s1, s54, 3
	s_sub_i32 s0, s0, s1
	s_lshl_b32 s1, s0, 8
	s_mul_i32 s0, s0, 0x88000
	v_readlane_b32 s4, v253, 6
	v_and_b32_e32 v228, 63, v8
	v_and_b32_e32 v229, 3, v9
	v_ashrrev_i32_e32 v9, 8, v8
	v_and_b32_e32 v223, 15, v8
	v_and_b32_e32 v10, 48, v8
	v_lshlrev_b32_e32 v12, 2, v8
	v_lshlrev_b32_e32 v8, 6, v8
	s_mul_hi_i32 s1, s1, 0x880
	s_add_u32 s0, s4, s0
	v_readlane_b32 s4, v253, 7
	v_lshlrev_b32_e32 v11, 6, v223
	v_and_b32_e32 v12, 32, v12
	v_lshlrev_b32_e32 v158, 14, v9
	v_and_b32_e32 v8, 0x3c0, v8
	s_addc_u32 s1, s4, s1
	v_mov_b32_e32 v2, 0
	v_lshlrev_b32_e32 v151, 13, v229
	v_bitop3_b32 v153, v11, v12, v10 bitop3:0x36
	v_lshlrev_b32_e32 v230, 7, v9
	v_or_b32_e32 v150, 0x800, v158
	v_bitop3_b32 v152, v8, v12, v10 bitop3:0x36
	v_or_b32_e32 v167, 0x1000, v158
	v_or_b32_e32 v166, 0x1800, v158
	v_or_b32_e32 v165, 0x2000, v158
	v_or_b32_e32 v164, 0x2800, v158
	v_or_b32_e32 v163, 0x3000, v158
	v_or_b32_e32 v162, 0x3800, v158
	v_lshl_add_u64 v[138:139], s[0:1], 0, v[212:213]
	v_lshl_add_u64 v[140:141], s[0:1], 0, v[214:215]
	v_lshl_add_u64 v[142:143], s[0:1], 0, v[146:147]
	v_lshl_add_u64 v[144:145], s[0:1], 0, v[148:149]
	s_mov_b64 s[0:1], 0
	s_mov_b32 s14, 0
	v_mov_b32_e32 v3, v2
	v_mov_b32_e32 v4, v2
	v_mov_b32_e32 v5, v2
	v_mov_b32_e32 v6, v2
	v_mov_b32_e32 v7, v2
	v_mov_b32_e32 v8, v2
	v_mov_b32_e32 v9, v2
	v_mov_b32_e32 v10, v2
	v_mov_b32_e32 v11, v2
	v_mov_b32_e32 v12, v2
	v_mov_b32_e32 v13, v2
	v_mov_b32_e32 v14, v2
	v_mov_b32_e32 v15, v2
	v_mov_b32_e32 v16, v2
	v_mov_b32_e32 v17, v2
	v_mov_b32_e32 v18, v2
	v_mov_b32_e32 v19, v2
	v_mov_b32_e32 v20, v2
	v_mov_b32_e32 v21, v2
	v_mov_b32_e32 v22, v2
	v_mov_b32_e32 v23, v2
	v_mov_b32_e32 v24, v2
	v_mov_b32_e32 v25, v2
	v_mov_b32_e32 v26, v2
	v_mov_b32_e32 v27, v2
	v_mov_b32_e32 v28, v2
	v_mov_b32_e32 v29, v2
	v_mov_b32_e32 v30, v2
	v_mov_b32_e32 v31, v2
	v_mov_b32_e32 v32, v2
	v_mov_b32_e32 v33, v2
	v_mov_b32_e32 v34, v2
	v_mov_b32_e32 v35, v2
	v_mov_b32_e32 v36, v2
	v_mov_b32_e32 v37, v2
	v_mov_b32_e32 v38, v2
	v_mov_b32_e32 v39, v2
	v_mov_b32_e32 v40, v2
	v_mov_b32_e32 v41, v2
	v_mov_b32_e32 v42, v2
	v_mov_b32_e32 v43, v2
	v_mov_b32_e32 v44, v2
	v_mov_b32_e32 v45, v2
	v_mov_b32_e32 v46, v2
	v_mov_b32_e32 v47, v2
	v_mov_b32_e32 v48, v2
	v_mov_b32_e32 v49, v2
	v_mov_b32_e32 v50, v2
	v_mov_b32_e32 v51, v2
	v_mov_b32_e32 v52, v2
	v_mov_b32_e32 v53, v2
	v_mov_b32_e32 v54, v2
	v_mov_b32_e32 v55, v2
	v_mov_b32_e32 v56, v2
	v_mov_b32_e32 v57, v2
	v_mov_b32_e32 v58, v2
	v_mov_b32_e32 v59, v2
	v_mov_b32_e32 v60, v2
	v_mov_b32_e32 v61, v2
	v_mov_b32_e32 v62, v2
	v_mov_b32_e32 v63, v2
	v_mov_b32_e32 v64, v2
	v_mov_b32_e32 v65, v2
	s_waitcnt vmcnt(8)
	v_mov_b32_e32 v66, v2
	v_mov_b32_e32 v67, v2
	v_mov_b32_e32 v68, v2
	v_mov_b32_e32 v69, v2
	v_mov_b32_e32 v70, v2
	v_mov_b32_e32 v71, v2
	v_mov_b32_e32 v72, v2
	v_mov_b32_e32 v73, v2
	v_mov_b32_e32 v74, v2
	v_mov_b32_e32 v75, v2
	v_mov_b32_e32 v76, v2
	v_mov_b32_e32 v77, v2
	v_mov_b32_e32 v78, v2
	v_mov_b32_e32 v79, v2
	v_mov_b32_e32 v80, v2
	v_mov_b32_e32 v81, v2
	v_mov_b32_e32 v82, v2
	v_mov_b32_e32 v83, v2
	v_mov_b32_e32 v84, v2
	v_mov_b32_e32 v85, v2
	v_mov_b32_e32 v86, v2
	v_mov_b32_e32 v87, v2
	v_mov_b32_e32 v88, v2
	v_mov_b32_e32 v89, v2
	v_mov_b32_e32 v90, v2
	v_mov_b32_e32 v91, v2
	v_mov_b32_e32 v92, v2
	v_mov_b32_e32 v93, v2
	v_mov_b32_e32 v94, v2
	v_mov_b32_e32 v95, v2
	v_mov_b32_e32 v96, v2
	v_mov_b32_e32 v97, v2
	v_mov_b32_e32 v98, v2
	v_mov_b32_e32 v99, v2
	v_mov_b32_e32 v100, v2
	v_mov_b32_e32 v101, v2
	v_mov_b32_e32 v102, v2
	v_mov_b32_e32 v103, v2
	v_mov_b32_e32 v104, v2
	v_mov_b32_e32 v105, v2
	v_mov_b32_e32 v106, v2
	v_mov_b32_e32 v107, v2
	v_mov_b32_e32 v108, v2
	v_mov_b32_e32 v109, v2
	v_mov_b32_e32 v110, v2
	v_mov_b32_e32 v111, v2
	v_mov_b32_e32 v112, v2
	v_mov_b32_e32 v113, v2
	v_mov_b32_e32 v114, v2
	v_mov_b32_e32 v115, v2
	v_mov_b32_e32 v116, v2
	v_mov_b32_e32 v117, v2
	v_mov_b32_e32 v118, v2
	v_mov_b32_e32 v119, v2
	v_mov_b32_e32 v120, v2
	v_mov_b32_e32 v121, v2
	v_mov_b32_e32 v122, v2
	v_mov_b32_e32 v123, v2
	v_mov_b32_e32 v124, v2
	v_mov_b32_e32 v125, v2
	v_mov_b32_e32 v126, v2
	v_mov_b32_e32 v127, v2
	v_mov_b32_e32 v128, v2
	v_mov_b32_e32 v129, v2
	s_mov_b32 s38, 0
	v_add3_u32 v0, s38, v153, v151
	v_add3_u32 v159, s38, v153, v158
	v_add3_u32 v209, s38, v152, v167
	v_add3_u32 v240, s38, v152, v165
	v_add3_u32 v242, s38, v152, v163
	v_add3_u32 v208, s38, v152, v150
	v_add3_u32 v231, s38, v152, v166
	v_add3_u32 v241, s38, v152, v164
	v_add3_u32 v243, s38, v152, v162
	ds_read_b128 v[168:171], v0 offset:32768
	ds_read_b128 v[172:175], v0 offset:34816
	ds_read_b128 v[184:187], v159
	ds_read_b128 v[188:191], v208
	ds_read_b128 v[192:195], v209
	ds_read_b128 v[196:199], v231
	ds_read_b128 v[200:203], v240
	ds_read_b128 v[204:207], v241
	ds_read_b128 v[232:235], v242
	ds_read_b128 v[236:239], v243
	ds_read_b128 v[176:179], v0 offset:36864
	ds_read_b128 v[180:183], v0 offset:38912
	v_add_u32_e32 v244, 0x10000, v157
	s_nop 0
	v_readfirstlane_b32 s38, v244
	s_mov_b32 m0, s38
	v_lshl_add_u64 v[160:161], v[144:145], 0, s[0:1]
	global_load_lds_dwordx4 v[160:161], off
	s_add_u32 m0, s38, 0x8000
	v_lshl_add_u64 v[160:161], v[136:137], 0, s[0:1]
	global_load_lds_dwordx4 v[160:161], off
	s_add_u32 m0, s38, 0x2000
	v_lshl_add_u64 v[160:161], v[142:143], 0, s[0:1]
	global_load_lds_dwordx4 v[160:161], off
	s_add_u32 m0, s38, 0xa000
	v_lshl_add_u64 v[160:161], v[134:135], 0, s[0:1]
	global_load_lds_dwordx4 v[160:161], off
	s_add_u32 m0, s38, 0x4000
	v_lshl_add_u64 v[160:161], v[140:141], 0, s[0:1]
	global_load_lds_dwordx4 v[160:161], off
	s_add_u32 m0, s38, 0xc000
	v_lshl_add_u64 v[160:161], v[132:133], 0, s[0:1]
	global_load_lds_dwordx4 v[160:161], off
	s_add_u32 m0, s38, 0x6000
	v_lshl_add_u64 v[160:161], v[138:139], 0, s[0:1]
	global_load_lds_dwordx4 v[160:161], off
	s_add_u32 m0, s38, 0xe000
	v_lshl_add_u64 v[160:161], v[130:131], 0, s[0:1]
	global_load_lds_dwordx4 v[160:161], off
; #define MFMA16(a, b, c) __builtin_amdgcn_mfma_f32_16x16x32_bf16((a), (b), (c), 0, 0, 0)
; template <class Epi>
; DI void gemm8_tile(const bf16_t* __restrict__ Ab, int lda, const bf16_t* __restrict__ Bb, int ldb, int K, int brow, int bcol, const Epi epi,
;                    bool staged, bool has_next, const bf16_t* __restrict__ Abn, const bf16_t* __restrict__ Bbn) {
;     ...
;   for (int t = 0; t < nt; ++t) {
;     const int cur = t & 1;
;     const unsigned char* sa = smem + cur * G8_STAGE_B;
;     const unsigned char* sb = sa + G8_TILE_B;
; #pragma unroll
;     for (int ks = 0; ks < 2; ++ks) {
;       bf16x8 At[8], Bf[4];
;       Bf[0] = *(const bf16x8*)(sb + lds_byte2(wc * 64 + fr, ks * 32 + fq * 8));
;       At[0] = *(const bf16x8*)(sa + lds_byte2(wr * 128 + fr, ks * 32 + fq * 8));
; #pragma unroll
;       for (int n = 1; n < 4; ++n) Bf[n] = *(const bf16x8*)(sb + lds_byte2(wc * 64 + n * 16 + fr, ks * 32 + fq * 8));
; #pragma unroll
;       for (int m = 1; m < 8; ++m) At[m] = *(const bf16x8*)(sa + lds_byte2(wr * 128 + m * 16 + fr, ks * 32 + fq * 8));
;       {
;         __builtin_amdgcn_sched_barrier(0);
;         if (t + 1 < nt) { G8_STAGE_R(cur ^ 1, Ab + (t + 1) * 64, Bb + (t + 1) * 64, 2 * ks, 2 * ks + 2); }
;         else if (has_next) { G8_STAGE_R(0, Abn, Bbn, 2 * ks, 2 * ks + 2); }
;         __builtin_amdgcn_sched_barrier(0);
;       }
; #pragma unroll
;       for (int m = 0; m < 8; ++m)
; #pragma unroll
;         for (int n = 0; n < 4; ++n) acc[m][n] = MFMA16(At[m], Bf[n], acc[m][n]);
;       __builtin_amdgcn_sched_barrier(0);
;     }
;     asm volatile("s_waitcnt vmcnt(0)" ::: "memory");
;     __syncthreads();
;   }
.LBB0_1673:
	s_and_b32 s15, s14, 0x10000
	s_xor_b32 s38, s15, 0x10000
	v_add_u32_e32 v244, s38, v157
	s_nop 0
	v_readfirstlane_b32 s15, v244
	s_waitcnt lgkmcnt(8)
	v_mfma_f32_16x16x32_bf16 v[126:129], v[184:187], v[168:171], v[126:129]
	v_mfma_f32_16x16x32_bf16 v[122:125], v[184:187], v[172:175], v[122:125]
	v_mfma_f32_16x16x32_bf16 v[110:113], v[188:191], v[168:171], v[110:113]
	v_mfma_f32_16x16x32_bf16 v[106:109], v[188:191], v[172:175], v[106:109]
	s_waitcnt lgkmcnt(6)
	v_mfma_f32_16x16x32_bf16 v[94:97], v[192:195], v[168:171], v[94:97]
	v_mfma_f32_16x16x32_bf16 v[90:93], v[192:195], v[172:175], v[90:93]
	v_mfma_f32_16x16x32_bf16 v[78:81], v[196:199], v[168:171], v[78:81]
	v_mfma_f32_16x16x32_bf16 v[74:77], v[196:199], v[172:175], v[74:77]
	s_waitcnt lgkmcnt(4)
	v_mfma_f32_16x16x32_bf16 v[62:65], v[200:203], v[168:171], v[62:65]
	v_mfma_f32_16x16x32_bf16 v[58:61], v[200:203], v[172:175], v[58:61]
	v_mfma_f32_16x16x32_bf16 v[46:49], v[204:207], v[168:171], v[46:49]
	v_mfma_f32_16x16x32_bf16 v[42:45], v[204:207], v[172:175], v[42:45]
	s_waitcnt lgkmcnt(2)
	v_mfma_f32_16x16x32_bf16 v[30:33], v[232:235], v[168:171], v[30:33]
	v_mfma_f32_16x16x32_bf16 v[26:29], v[232:235], v[172:175], v[26:29]
	v_mfma_f32_16x16x32_bf16 v[14:17], v[236:239], v[168:171], v[14:17]
	v_mfma_f32_16x16x32_bf16 v[10:13], v[236:239], v[172:175], v[10:13]
	ds_read_b128 v[168:171], v0 offset:33792
	ds_read_b128 v[172:175], v0 offset:35840
	s_waitcnt lgkmcnt(2)
	v_mfma_f32_16x16x32_bf16 v[118:121], v[184:187], v[176:179], v[118:121]
	v_mfma_f32_16x16x32_bf16 v[114:117], v[184:187], v[180:183], v[114:117]
	ds_read_b128 v[184:187], v159 offset:1024
	v_mfma_f32_16x16x32_bf16 v[102:105], v[188:191], v[176:179], v[102:105]
	v_mfma_f32_16x16x32_bf16 v[98:101], v[188:191], v[180:183], v[98:101]
	ds_read_b128 v[188:191], v208 offset:1024
	v_mfma_f32_16x16x32_bf16 v[86:89], v[192:195], v[176:179], v[86:89]
	v_mfma_f32_16x16x32_bf16 v[82:85], v[192:195], v[180:183], v[82:85]
	ds_read_b128 v[192:195], v209 offset:1024
	v_mfma_f32_16x16x32_bf16 v[70:73], v[196:199], v[176:179], v[70:73]
	v_mfma_f32_16x16x32_bf16 v[66:69], v[196:199], v[180:183], v[66:69]
	ds_read_b128 v[196:199], v231 offset:1024
	v_mfma_f32_16x16x32_bf16 v[54:57], v[200:203], v[176:179], v[54:57]
	v_mfma_f32_16x16x32_bf16 v[50:53], v[200:203], v[180:183], v[50:53]
	ds_read_b128 v[200:203], v240 offset:1024
	v_mfma_f32_16x16x32_bf16 v[38:41], v[204:207], v[176:179], v[38:41]
	v_mfma_f32_16x16x32_bf16 v[34:37], v[204:207], v[180:183], v[34:37]
	ds_read_b128 v[204:207], v241 offset:1024
	v_mfma_f32_16x16x32_bf16 v[22:25], v[232:235], v[176:179], v[22:25]
	v_mfma_f32_16x16x32_bf16 v[18:21], v[232:235], v[180:183], v[18:21]
	ds_read_b128 v[232:235], v242 offset:1024
	v_mfma_f32_16x16x32_bf16 v[6:9], v[236:239], v[176:179], v[6:9]
	v_mfma_f32_16x16x32_bf16 v[2:5], v[236:239], v[180:183], v[2:5]
	ds_read_b128 v[236:239], v243 offset:1024
	ds_read_b128 v[176:179], v0 offset:37888
	ds_read_b128 v[180:183], v0 offset:39936
	s_waitcnt lgkmcnt(8)
	v_mfma_f32_16x16x32_bf16 v[126:129], v[184:187], v[168:171], v[126:129]
	v_mfma_f32_16x16x32_bf16 v[122:125], v[184:187], v[172:175], v[122:125]
	v_add3_u32 v0, s38, v153, v151
	v_mfma_f32_16x16x32_bf16 v[110:113], v[188:191], v[168:171], v[110:113]
	v_mfma_f32_16x16x32_bf16 v[106:109], v[188:191], v[172:175], v[106:109]
	v_add3_u32 v159, s38, v153, v158
	s_waitcnt lgkmcnt(6)
	v_mfma_f32_16x16x32_bf16 v[94:97], v[192:195], v[168:171], v[94:97]
	v_mfma_f32_16x16x32_bf16 v[90:93], v[192:195], v[172:175], v[90:93]
	v_add3_u32 v209, s38, v152, v167
	v_mfma_f32_16x16x32_bf16 v[78:81], v[196:199], v[168:171], v[78:81]
	v_mfma_f32_16x16x32_bf16 v[74:77], v[196:199], v[172:175], v[74:77]
	v_add3_u32 v240, s38, v152, v165
	s_waitcnt lgkmcnt(4)
	v_mfma_f32_16x16x32_bf16 v[62:65], v[200:203], v[168:171], v[62:65]
	v_mfma_f32_16x16x32_bf16 v[58:61], v[200:203], v[172:175], v[58:61]
	v_add3_u32 v242, s38, v152, v163
	v_mfma_f32_16x16x32_bf16 v[46:49], v[204:207], v[168:171], v[46:49]
	v_mfma_f32_16x16x32_bf16 v[42:45], v[204:207], v[172:175], v[42:45]
	v_add3_u32 v208, s38, v152, v150
	s_waitcnt lgkmcnt(2)
	v_mfma_f32_16x16x32_bf16 v[30:33], v[232:235], v[168:171], v[30:33]
	v_mfma_f32_16x16x32_bf16 v[26:29], v[232:235], v[172:175], v[26:29]
	v_add3_u32 v231, s38, v152, v166
	v_mfma_f32_16x16x32_bf16 v[14:17], v[236:239], v[168:171], v[14:17]
	v_mfma_f32_16x16x32_bf16 v[10:13], v[236:239], v[172:175], v[10:13]
	v_add3_u32 v241, s38, v152, v164
	v_add3_u32 v243, s38, v152, v162
	s_waitcnt vmcnt(0) lgkmcnt(0)
	s_barrier
	s_add_u32 s0, s0, 0x80
	s_addc_u32 s1, s1, 0
	s_add_i32 s14, s14, 0x10000
	s_xor_b32 s38, s15, 0x10000
	s_cmpk_eq_i32 s0, 0x780
	s_cbranch_scc1 .Lg80_1673_last
; #define MFMA16(a, b, c) __builtin_amdgcn_mfma_f32_16x16x32_bf16((a), (b), (c), 0, 0, 0)
; template <class Epi>
; DI void gemm8_tile(const bf16_t* __restrict__ Ab, int lda, const bf16_t* __restrict__ Bb, int ldb, int K, int brow, int bcol, const Epi epi,
;                    bool staged, bool has_next, const bf16_t* __restrict__ Abn, const bf16_t* __restrict__ Bbn) {
;     ...
;   for (int t = 0; t < nt; ++t) {
;     const int cur = t & 1;
;     const unsigned char* sa = smem + cur * G8_STAGE_B;
;     const unsigned char* sb = sa + G8_TILE_B;
; #pragma unroll
;     for (int ks = 0; ks < 2; ++ks) {
;       bf16x8 At[8], Bf[4];
;       Bf[0] = *(const bf16x8*)(sb + lds_byte2(wc * 64 + fr, ks * 32 + fq * 8));
;       At[0] = *(const bf16x8*)(sa + lds_byte2(wr * 128 + fr, ks * 32 + fq * 8));
; #pragma unroll
;       for (int n = 1; n < 4; ++n) Bf[n] = *(const bf16x8*)(sb + lds_byte2(wc * 64 + n * 16 + fr, ks * 32 + fq * 8));
; #pragma unroll
;       for (int m = 1; m < 8; ++m) At[m] = *(const bf16x8*)(sa + lds_byte2(wr * 128 + m * 16 + fr, ks * 32 + fq * 8));
;       {
;         __builtin_amdgcn_sched_barrier(0);
;         if (t + 1 < nt) { G8_STAGE_R(cur ^ 1, Ab + (t + 1) * 64, Bb + (t + 1) * 64, 2 * ks, 2 * ks + 2); }
;         else if (has_next) { G8_STAGE_R(0, Abn, Bbn, 2 * ks, 2 * ks + 2); }
;         __builtin_amdgcn_sched_barrier(0);
;       }
; #pragma unroll
;       for (int m = 0; m < 8; ++m)
; #pragma unroll
;         for (int n = 0; n < 4; ++n) acc[m][n] = MFMA16(At[m], Bf[n], acc[m][n]);
;       __builtin_amdgcn_sched_barrier(0);
;     }
;     asm volatile("s_waitcnt vmcnt(0)" ::: "memory");
;     __syncthreads();
;   }
	ds_read_b128 v[168:171], v0 offset:32768
	ds_read_b128 v[172:175], v0 offset:34816
	v_mfma_f32_16x16x32_bf16 v[118:121], v[184:187], v[176:179], v[118:121]
	v_mfma_f32_16x16x32_bf16 v[114:117], v[184:187], v[180:183], v[114:117]
	ds_read_b128 v[184:187], v159
	s_mov_b32 m0, s38
	v_lshl_add_u64 v[160:161], v[144:145], 0, s[0:1]
	global_load_lds_dwordx4 v[160:161], off
	v_mfma_f32_16x16x32_bf16 v[102:105], v[188:191], v[176:179], v[102:105]
	v_mfma_f32_16x16x32_bf16 v[98:101], v[188:191], v[180:183], v[98:101]
	ds_read_b128 v[188:191], v208
	s_add_u32 m0, s38, 0x8000
	v_lshl_add_u64 v[160:161], v[136:137], 0, s[0:1]
	global_load_lds_dwordx4 v[160:161], off
	v_mfma_f32_16x16x32_bf16 v[86:89], v[192:195], v[176:179], v[86:89]
	v_mfma_f32_16x16x32_bf16 v[82:85], v[192:195], v[180:183], v[82:85]
	ds_read_b128 v[192:195], v209
	s_add_u32 m0, s38, 0x2000
	v_lshl_add_u64 v[160:161], v[142:143], 0, s[0:1]
	global_load_lds_dwordx4 v[160:161], off
	v_mfma_f32_16x16x32_bf16 v[70:73], v[196:199], v[176:179], v[70:73]
	v_mfma_f32_16x16x32_bf16 v[66:69], v[196:199], v[180:183], v[66:69]
	ds_read_b128 v[196:199], v231
	s_add_u32 m0, s38, 0xa000
	v_lshl_add_u64 v[160:161], v[134:135], 0, s[0:1]
	global_load_lds_dwordx4 v[160:161], off
	v_mfma_f32_16x16x32_bf16 v[54:57], v[200:203], v[176:179], v[54:57]
	v_mfma_f32_16x16x32_bf16 v[50:53], v[200:203], v[180:183], v[50:53]
	ds_read_b128 v[200:203], v240
	s_add_u32 m0, s38, 0x4000
	v_lshl_add_u64 v[160:161], v[140:141], 0, s[0:1]
	global_load_lds_dwordx4 v[160:161], off
	v_mfma_f32_16x16x32_bf16 v[38:41], v[204:207], v[176:179], v[38:41]
	v_mfma_f32_16x16x32_bf16 v[34:37], v[204:207], v[180:183], v[34:37]
	ds_read_b128 v[204:207], v241
	s_add_u32 m0, s38, 0xc000
	v_lshl_add_u64 v[160:161], v[132:133], 0, s[0:1]
	global_load_lds_dwordx4 v[160:161], off
	v_mfma_f32_16x16x32_bf16 v[22:25], v[232:235], v[176:179], v[22:25]
	v_mfma_f32_16x16x32_bf16 v[18:21], v[232:235], v[180:183], v[18:21]
	ds_read_b128 v[232:235], v242
	s_add_u32 m0, s38, 0x6000
	v_lshl_add_u64 v[160:161], v[138:139], 0, s[0:1]
	global_load_lds_dwordx4 v[160:161], off
	v_mfma_f32_16x16x32_bf16 v[6:9], v[236:239], v[176:179], v[6:9]
	v_mfma_f32_16x16x32_bf16 v[2:5], v[236:239], v[180:183], v[2:5]
	ds_read_b128 v[236:239], v243
	s_add_u32 m0, s38, 0xe000
	v_lshl_add_u64 v[160:161], v[130:131], 0, s[0:1]
	global_load_lds_dwordx4 v[160:161], off
	ds_read_b128 v[176:179], v0 offset:36864
	ds_read_b128 v[180:183], v0 offset:38912
	s_branch .LBB0_1673
.Lg80_1673_last:
	ds_read_b128 v[168:171], v0 offset:32768
	ds_read_b128 v[172:175], v0 offset:34816
	v_mfma_f32_16x16x32_bf16 v[118:121], v[184:187], v[176:179], v[118:121]
	v_mfma_f32_16x16x32_bf16 v[114:117], v[184:187], v[180:183], v[114:117]
	ds_read_b128 v[184:187], v159
	v_mfma_f32_16x16x32_bf16 v[102:105], v[188:191], v[176:179], v[102:105]
	v_mfma_f32_16x16x32_bf16 v[98:101], v[188:191], v[180:183], v[98:101]
	ds_read_b128 v[188:191], v208
	v_mfma_f32_16x16x32_bf16 v[86:89], v[192:195], v[176:179], v[86:89]
	v_mfma_f32_16x16x32_bf16 v[82:85], v[192:195], v[180:183], v[82:85]
	ds_read_b128 v[192:195], v209
	v_mfma_f32_16x16x32_bf16 v[70:73], v[196:199], v[176:179], v[70:73]
	v_mfma_f32_16x16x32_bf16 v[66:69], v[196:199], v[180:183], v[66:69]
	ds_read_b128 v[196:199], v231
	v_mfma_f32_16x16x32_bf16 v[54:57], v[200:203], v[176:179], v[54:57]
	v_mfma_f32_16x16x32_bf16 v[50:53], v[200:203], v[180:183], v[50:53]
	ds_read_b128 v[200:203], v240
	v_mfma_f32_16x16x32_bf16 v[38:41], v[204:207], v[176:179], v[38:41]
	v_mfma_f32_16x16x32_bf16 v[34:37], v[204:207], v[180:183], v[34:37]
	ds_read_b128 v[204:207], v241
	v_mfma_f32_16x16x32_bf16 v[22:25], v[232:235], v[176:179], v[22:25]
	v_mfma_f32_16x16x32_bf16 v[18:21], v[232:235], v[180:183], v[18:21]
	ds_read_b128 v[232:235], v242
	v_mfma_f32_16x16x32_bf16 v[6:9], v[236:239], v[176:179], v[6:9]
	v_mfma_f32_16x16x32_bf16 v[2:5], v[236:239], v[180:183], v[2:5]
	ds_read_b128 v[236:239], v243
	ds_read_b128 v[176:179], v0 offset:36864
	ds_read_b128 v[180:183], v0 offset:38912
	s_waitcnt lgkmcnt(0)
	s_add_i32 s0, 0, 0x18000
	v_add_u32_e32 v0, s0, v153
	v_add_u32_e32 v0, v0, v151
	v_add_u32_e32 v130, s30, v153
	v_add_u32_e32 v206, v130, v158
	ds_read_b128 v[130:133], v0
	ds_read_b128 v[134:137], v0 offset:2048
	ds_read_b128 v[138:141], v0 offset:4096
	ds_read_b128 v[142:145], v0 offset:6144
	v_add_u32_e32 v170, s30, v152
	v_add_u32_e32 v208, v170, v167
	v_add_u32_e32 v231, v170, v165
	v_add_u32_e32 v233, v170, v163
	v_add_u32_e32 v207, v170, v150
	ds_read_b128 v[150:153], v206
	ds_read_b128 v[158:161], v207
	v_add_u32_e32 v209, v170, v166
	ds_read_b128 v[166:169], v208
	ds_read_b128 v[174:177], v209
	v_add_u32_e32 v232, v170, v164
	ds_read_b128 v[182:185], v231
	ds_read_b128 v[190:193], v232
	v_add_u32_e32 v234, v170, v162
	ds_read_b128 v[198:201], v233
	ds_read_b128 v[202:205], v234
	v_cndmask_b32_e64 v162, 0, 1, s[12:13]
	v_cmp_ne_u32_e64 s[0:1], 1, v162
	s_andn2_b64 vcc, exec, s[12:13]
	s_cbranch_vccnz .LBB0_1676
	v_readfirstlane_b32 s12, v157
	v_lshl_add_u64 v[162:163], s[8:9], 0, v[148:149]
	s_mov_b32 m0, s12
	v_readfirstlane_b32 s12, v156
	v_lshl_add_u64 v[148:149], s[10:11], 0, v[148:149]
	global_load_lds_dwordx4 v[162:163], off
	s_mov_b32 m0, s12
	v_readfirstlane_b32 s12, v155
	v_lshl_add_u64 v[164:165], s[8:9], 0, v[146:147]
	global_load_lds_dwordx4 v[148:149], off
	s_mov_b32 m0, s12
	v_readfirstlane_b32 s12, v154
	v_lshl_add_u64 v[146:147], s[10:11], 0, v[146:147]
	global_load_lds_dwordx4 v[164:165], off
	s_mov_b32 m0, s12
	s_nop 0
	global_load_lds_dwordx4 v[146:147], off

; DI int opaque_tid512() { int t = threadIdx.x; asm volatile("" : "+v"(t)); return t; }
; #define G8_STAGE(buf_, ap_, bp_) G8_STAGE_R(buf_, ap_, bp_, 0, 4)
; template <class Epi>
; DI void gemm8_tile(const bf16_t* __restrict__ Ab, int lda, const bf16_t* __restrict__ Bb, int ldb, int K, int brow, int bcol, const Epi epi,
;                    bool staged, bool has_next, const bf16_t* __restrict__ Abn, const bf16_t* __restrict__ Bbn) {
;   const int tid = opaque_tid512(), wid = tid >> 6, lane = tid & 63, wr = wid >> 2, wc = wid & 3, fr = lane & 15, fq = lane >> 4;
;   unsigned aoff[4], boff[4];
; #pragma unroll
;   for (int i = 0; i < 4; ++i) { int R, C; stage_rc2(wid * 1024 + i * 8192 + lane * 16, R, C); aoff[i] = (unsigned)R * (unsigned)lda + (unsigned)C; boff[i] = (unsigned)R * (unsigned)ldb + (unsigned)C; }
;     ...
;   f32x4 acc[8][4];
; #pragma unroll
;   for (int m = 0; m < 8; ++m)
; #pragma unroll
;     for (int n = 0; n < 4; ++n) acc[m][n] = (f32x4){0.f, 0.f, 0.f, 0.f};
;   const int nt = K / 64;
;   if (!staged) {
;     G8_STAGE(0, Ab, Bb);
;     asm volatile("s_waitcnt vmcnt(0)" ::: "memory");
;     __syncthreads();
;   }
.LBB0_1694:
	s_lshl_b32 s0, s79, 3
	s_add_i32 s0, s28, s0
	s_add_i32 s0, s0, s81
	s_lshl_b32 s1, s78, 3
	s_sub_i32 s0, s0, s1
	s_lshl_b32 s1, s0, 8
	s_mul_i32 s0, s0, 0x168000
	s_mul_hi_i32 s1, s1, 0x1680
	s_add_u32 s0, s91, s0
	v_lshlrev_b64 v[178:179], 1, v[4:5]
	s_addc_u32 s1, s72, s1
	v_lshlrev_b64 v[180:181], 1, v[2:3]
	v_lshlrev_b64 v[194:195], 1, v[6:7]
	v_lshlrev_b64 v[196:197], 1, v[0:1]
	v_and_b32_e32 v198, 15, v8
	v_lshl_add_u64 v[130:131], s[0:1], 0, v[178:179]
	v_lshl_add_u64 v[132:133], s[0:1], 0, v[180:181]
	v_lshl_add_u64 v[134:135], s[0:1], 0, v[194:195]
	v_lshl_add_u64 v[136:137], s[0:1], 0, v[196:197]
	v_readlane_b32 s0, v253, 25
	v_and_b32_e32 v206, 63, v8
	v_ashrrev_i32_e32 v10, 8, v8
	v_and_b32_e32 v204, 3, v9
	v_and_b32_e32 v9, 48, v8
	v_lshlrev_b32_e32 v199, 2, v198
	v_lshlrev_b32_e32 v8, 6, v8
	s_add_u32 s0, s0, s84
	v_readlane_b32 s1, v253, 26
	v_lshlrev_b32_e32 v11, 6, v198
	v_and_b32_e32 v12, 32, v199
	v_lshlrev_b32_e32 v156, 14, v10
	v_and_b32_e32 v8, 0x3c0, v8
	s_addc_u32 s1, s1, s85
	v_mov_b32_e32 v2, 0
	v_lshlrev_b32_e32 v153, 13, v204
	v_bitop3_b32 v155, v11, v12, v9 bitop3:0x36
	v_lshlrev_b32_e32 v205, 7, v10
	v_or_b32_e32 v150, 0x800, v156
	v_bitop3_b32 v154, v8, v12, v9 bitop3:0x36
	v_or_b32_e32 v152, 0x1000, v156
	v_or_b32_e32 v151, 0x1800, v156
	v_or_b32_e32 v149, 0x2000, v156
	v_or_b32_e32 v148, 0x2800, v156
	v_or_b32_e32 v147, 0x3000, v156
	v_or_b32_e32 v146, 0x3800, v156
	v_lshl_add_u64 v[138:139], s[0:1], 0, v[178:179]
	v_lshl_add_u64 v[140:141], s[0:1], 0, v[180:181]
	v_lshl_add_u64 v[142:143], s[0:1], 0, v[194:195]
	v_lshl_add_u64 v[144:145], s[0:1], 0, v[196:197]
	s_mov_b64 s[0:1], 0
	s_mov_b32 s58, 0
	v_mov_b32_e32 v3, v2
	v_mov_b32_e32 v4, v2
	v_mov_b32_e32 v5, v2
	v_mov_b32_e32 v6, v2
	v_mov_b32_e32 v7, v2
	v_mov_b32_e32 v8, v2
	v_mov_b32_e32 v9, v2
	v_mov_b32_e32 v10, v2
	v_mov_b32_e32 v11, v2
	v_mov_b32_e32 v12, v2
	v_mov_b32_e32 v13, v2
	v_mov_b32_e32 v14, v2
	v_mov_b32_e32 v15, v2
	v_mov_b32_e32 v16, v2
	v_mov_b32_e32 v17, v2
	v_mov_b32_e32 v18, v2
	v_mov_b32_e32 v19, v2
	v_mov_b32_e32 v20, v2
	v_mov_b32_e32 v21, v2
	v_mov_b32_e32 v22, v2
	v_mov_b32_e32 v23, v2
	v_mov_b32_e32 v24, v2
	v_mov_b32_e32 v25, v2
	v_mov_b32_e32 v26, v2
	v_mov_b32_e32 v27, v2
	v_mov_b32_e32 v28, v2
	v_mov_b32_e32 v29, v2
	v_mov_b32_e32 v30, v2
	v_mov_b32_e32 v31, v2
	v_mov_b32_e32 v32, v2
	v_mov_b32_e32 v33, v2
	v_mov_b32_e32 v34, v2
	v_mov_b32_e32 v35, v2
	v_mov_b32_e32 v36, v2
	v_mov_b32_e32 v37, v2
	v_mov_b32_e32 v38, v2
	v_mov_b32_e32 v39, v2
	v_mov_b32_e32 v40, v2
	v_mov_b32_e32 v41, v2
	v_mov_b32_e32 v42, v2
	v_mov_b32_e32 v43, v2
	v_mov_b32_e32 v44, v2
	v_mov_b32_e32 v45, v2
	v_mov_b32_e32 v46, v2
	v_mov_b32_e32 v47, v2
	v_mov_b32_e32 v48, v2
	v_mov_b32_e32 v49, v2
	v_mov_b32_e32 v50, v2
	v_mov_b32_e32 v51, v2
	v_mov_b32_e32 v52, v2
	v_mov_b32_e32 v53, v2
	v_mov_b32_e32 v54, v2
	v_mov_b32_e32 v55, v2
	v_mov_b32_e32 v56, v2
	v_mov_b32_e32 v57, v2
	v_mov_b32_e32 v58, v2
	v_mov_b32_e32 v59, v2
	v_mov_b32_e32 v60, v2
	v_mov_b32_e32 v61, v2
	v_mov_b32_e32 v62, v2
	v_mov_b32_e32 v63, v2
	v_mov_b32_e32 v64, v2
	v_mov_b32_e32 v65, v2
	s_waitcnt vmcnt(8)
	v_mov_b32_e32 v66, v2
	v_mov_b32_e32 v67, v2
	v_mov_b32_e32 v68, v2
	v_mov_b32_e32 v69, v2
	v_mov_b32_e32 v70, v2
	v_mov_b32_e32 v71, v2
	v_mov_b32_e32 v72, v2
	v_mov_b32_e32 v73, v2
	v_mov_b32_e32 v74, v2
	v_mov_b32_e32 v75, v2
	v_mov_b32_e32 v76, v2
	v_mov_b32_e32 v77, v2
	v_mov_b32_e32 v78, v2
	v_mov_b32_e32 v79, v2
	v_mov_b32_e32 v80, v2
	v_mov_b32_e32 v81, v2
	v_mov_b32_e32 v82, v2
	v_mov_b32_e32 v83, v2
	v_mov_b32_e32 v84, v2
	v_mov_b32_e32 v85, v2
	v_mov_b32_e32 v86, v2
	v_mov_b32_e32 v87, v2
	v_mov_b32_e32 v88, v2
	v_mov_b32_e32 v89, v2
	v_mov_b32_e32 v90, v2
	v_mov_b32_e32 v91, v2
	v_mov_b32_e32 v92, v2
	v_mov_b32_e32 v93, v2
	v_mov_b32_e32 v94, v2
	v_mov_b32_e32 v95, v2
	v_mov_b32_e32 v96, v2
	v_mov_b32_e32 v97, v2
	v_mov_b32_e32 v98, v2
	v_mov_b32_e32 v99, v2
	v_mov_b32_e32 v100, v2
	v_mov_b32_e32 v101, v2
	v_mov_b32_e32 v102, v2
	v_mov_b32_e32 v103, v2
	v_mov_b32_e32 v104, v2
	v_mov_b32_e32 v105, v2
	v_mov_b32_e32 v106, v2
	v_mov_b32_e32 v107, v2
	v_mov_b32_e32 v108, v2
	v_mov_b32_e32 v109, v2
	v_mov_b32_e32 v110, v2
	v_mov_b32_e32 v111, v2
	v_mov_b32_e32 v112, v2
	v_mov_b32_e32 v113, v2
	v_mov_b32_e32 v114, v2
	v_mov_b32_e32 v115, v2
	v_mov_b32_e32 v116, v2
	v_mov_b32_e32 v117, v2
	v_mov_b32_e32 v118, v2
	v_mov_b32_e32 v119, v2
	v_mov_b32_e32 v120, v2
	v_mov_b32_e32 v121, v2
	v_mov_b32_e32 v122, v2
	v_mov_b32_e32 v123, v2
	v_mov_b32_e32 v124, v2
	v_mov_b32_e32 v125, v2
	v_mov_b32_e32 v126, v2
	v_mov_b32_e32 v127, v2
	v_mov_b32_e32 v128, v2
	v_mov_b32_e32 v129, v2
	s_mov_b32 s70, 0
	v_add3_u32 v0, s70, v155, v153
	v_add3_u32 v157, s70, v155, v156
	v_add3_u32 v238, s70, v154, v152
	v_add3_u32 v240, s70, v154, v149
	v_add3_u32 v242, s70, v154, v147
	v_add3_u32 v207, s70, v154, v150
	v_add3_u32 v239, s70, v154, v151
	v_add3_u32 v241, s70, v154, v148
	v_add3_u32 v243, s70, v154, v146
	ds_read_b128 v[158:161], v0 offset:32768
	ds_read_b128 v[162:165], v0 offset:34816
	ds_read_b128 v[174:177], v157
	ds_read_b128 v[186:189], v207
	ds_read_b128 v[190:193], v238
	ds_read_b128 v[212:215], v239
	ds_read_b128 v[222:225], v240
	ds_read_b128 v[226:229], v241
	ds_read_b128 v[230:233], v242
	ds_read_b128 v[234:237], v243
	ds_read_b128 v[166:169], v0 offset:36864
	ds_read_b128 v[170:173], v0 offset:38912
	v_add_u32_e32 v244, 0x10000, v185
	s_nop 0
	v_readfirstlane_b32 s70, v244
	s_mov_b32 m0, s70
	v_lshl_add_u64 v[208:209], v[130:131], 0, s[0:1]
	global_load_lds_dwordx4 v[208:209], off
	s_add_u32 m0, s70, 0x8000
	v_lshl_add_u64 v[208:209], v[138:139], 0, s[0:1]
	global_load_lds_dwordx4 v[208:209], off
	s_add_u32 m0, s70, 0x2000
	v_lshl_add_u64 v[208:209], v[132:133], 0, s[0:1]
	global_load_lds_dwordx4 v[208:209], off
	s_add_u32 m0, s70, 0xa000
	v_lshl_add_u64 v[208:209], v[140:141], 0, s[0:1]
	global_load_lds_dwordx4 v[208:209], off
	s_add_u32 m0, s70, 0x4000
	v_lshl_add_u64 v[208:209], v[134:135], 0, s[0:1]
	global_load_lds_dwordx4 v[208:209], off
	s_add_u32 m0, s70, 0xc000
	v_lshl_add_u64 v[208:209], v[142:143], 0, s[0:1]
	global_load_lds_dwordx4 v[208:209], off
	s_add_u32 m0, s70, 0x6000
	v_lshl_add_u64 v[208:209], v[136:137], 0, s[0:1]
	global_load_lds_dwordx4 v[208:209], off
	s_add_u32 m0, s70, 0xe000
	v_lshl_add_u64 v[208:209], v[144:145], 0, s[0:1]
	global_load_lds_dwordx4 v[208:209], off
; #define MFMA16(a, b, c) __builtin_amdgcn_mfma_f32_16x16x32_bf16((a), (b), (c), 0, 0, 0)
; template <class Epi>
; DI void gemm8_tile(const bf16_t* __restrict__ Ab, int lda, const bf16_t* __restrict__ Bb, int ldb, int K, int brow, int bcol, const Epi epi,
;                    bool staged, bool has_next, const bf16_t* __restrict__ Abn, const bf16_t* __restrict__ Bbn) {
;     ...
;   for (int t = 0; t < nt; ++t) {
;     const int cur = t & 1;
;     const unsigned char* sa = smem + cur * G8_STAGE_B;
;     const unsigned char* sb = sa + G8_TILE_B;
; #pragma unroll
;     for (int ks = 0; ks < 2; ++ks) {
;       bf16x8 At[8], Bf[4];
;       Bf[0] = *(const bf16x8*)(sb + lds_byte2(wc * 64 + fr, ks * 32 + fq * 8));
;       At[0] = *(const bf16x8*)(sa + lds_byte2(wr * 128 + fr, ks * 32 + fq * 8));
; #pragma unroll
;       for (int n = 1; n < 4; ++n) Bf[n] = *(const bf16x8*)(sb + lds_byte2(wc * 64 + n * 16 + fr, ks * 32 + fq * 8));
; #pragma unroll
;       for (int m = 1; m < 8; ++m) At[m] = *(const bf16x8*)(sa + lds_byte2(wr * 128 + m * 16 + fr, ks * 32 + fq * 8));
;       {
;         __builtin_amdgcn_sched_barrier(0);
;         if (t + 1 < nt) { G8_STAGE_R(cur ^ 1, Ab + (t + 1) * 64, Bb + (t + 1) * 64, 2 * ks, 2 * ks + 2); }
;         else if (has_next) { G8_STAGE_R(0, Abn, Bbn, 2 * ks, 2 * ks + 2); }
;         __builtin_amdgcn_sched_barrier(0);
;       }
; #pragma unroll
;       for (int m = 0; m < 8; ++m)
; #pragma unroll
;         for (int n = 0; n < 4; ++n) acc[m][n] = MFMA16(At[m], Bf[n], acc[m][n]);
;       __builtin_amdgcn_sched_barrier(0);
;     }
;     asm volatile("s_waitcnt vmcnt(0)" ::: "memory");
;     __syncthreads();
;   }
.LBB0_1695:
	s_and_b32 s59, s58, 0x10000
	s_xor_b32 s70, s59, 0x10000
	v_add_u32_e32 v244, s70, v185
	s_nop 0
	v_readfirstlane_b32 s59, v244
	s_waitcnt lgkmcnt(8)
	v_mfma_f32_16x16x32_bf16 v[126:129], v[174:177], v[158:161], v[126:129]
	v_mfma_f32_16x16x32_bf16 v[122:125], v[174:177], v[162:165], v[122:125]
	v_mfma_f32_16x16x32_bf16 v[110:113], v[186:189], v[158:161], v[110:113]
	v_mfma_f32_16x16x32_bf16 v[106:109], v[186:189], v[162:165], v[106:109]
	s_waitcnt lgkmcnt(6)
	v_mfma_f32_16x16x32_bf16 v[94:97], v[190:193], v[158:161], v[94:97]
	v_mfma_f32_16x16x32_bf16 v[90:93], v[190:193], v[162:165], v[90:93]
	v_mfma_f32_16x16x32_bf16 v[78:81], v[212:215], v[158:161], v[78:81]
	v_mfma_f32_16x16x32_bf16 v[74:77], v[212:215], v[162:165], v[74:77]
	s_waitcnt lgkmcnt(4)
	v_mfma_f32_16x16x32_bf16 v[62:65], v[222:225], v[158:161], v[62:65]
	v_mfma_f32_16x16x32_bf16 v[58:61], v[222:225], v[162:165], v[58:61]
	v_mfma_f32_16x16x32_bf16 v[46:49], v[226:229], v[158:161], v[46:49]
	v_mfma_f32_16x16x32_bf16 v[42:45], v[226:229], v[162:165], v[42:45]
	s_waitcnt lgkmcnt(2)
	v_mfma_f32_16x16x32_bf16 v[30:33], v[230:233], v[158:161], v[30:33]
	v_mfma_f32_16x16x32_bf16 v[26:29], v[230:233], v[162:165], v[26:29]
	v_mfma_f32_16x16x32_bf16 v[14:17], v[234:237], v[158:161], v[14:17]
	v_mfma_f32_16x16x32_bf16 v[10:13], v[234:237], v[162:165], v[10:13]
	ds_read_b128 v[158:161], v0 offset:33792
	ds_read_b128 v[162:165], v0 offset:35840
	s_waitcnt lgkmcnt(2)
	v_mfma_f32_16x16x32_bf16 v[118:121], v[174:177], v[166:169], v[118:121]
	v_mfma_f32_16x16x32_bf16 v[114:117], v[174:177], v[170:173], v[114:117]
	ds_read_b128 v[174:177], v157 offset:1024
	v_mfma_f32_16x16x32_bf16 v[102:105], v[186:189], v[166:169], v[102:105]
	v_mfma_f32_16x16x32_bf16 v[98:101], v[186:189], v[170:173], v[98:101]
	ds_read_b128 v[186:189], v207 offset:1024
	v_mfma_f32_16x16x32_bf16 v[86:89], v[190:193], v[166:169], v[86:89]
	v_mfma_f32_16x16x32_bf16 v[82:85], v[190:193], v[170:173], v[82:85]
	ds_read_b128 v[190:193], v238 offset:1024
	v_mfma_f32_16x16x32_bf16 v[70:73], v[212:215], v[166:169], v[70:73]
	v_mfma_f32_16x16x32_bf16 v[66:69], v[212:215], v[170:173], v[66:69]
	ds_read_b128 v[212:215], v239 offset:1024
	v_mfma_f32_16x16x32_bf16 v[54:57], v[222:225], v[166:169], v[54:57]
	v_mfma_f32_16x16x32_bf16 v[50:53], v[222:225], v[170:173], v[50:53]
	ds_read_b128 v[222:225], v240 offset:1024
	v_mfma_f32_16x16x32_bf16 v[38:41], v[226:229], v[166:169], v[38:41]
	v_mfma_f32_16x16x32_bf16 v[34:37], v[226:229], v[170:173], v[34:37]
	ds_read_b128 v[226:229], v241 offset:1024
	v_mfma_f32_16x16x32_bf16 v[22:25], v[230:233], v[166:169], v[22:25]
	v_mfma_f32_16x16x32_bf16 v[18:21], v[230:233], v[170:173], v[18:21]
	ds_read_b128 v[230:233], v242 offset:1024
	v_mfma_f32_16x16x32_bf16 v[6:9], v[234:237], v[166:169], v[6:9]
	v_mfma_f32_16x16x32_bf16 v[2:5], v[234:237], v[170:173], v[2:5]
	ds_read_b128 v[234:237], v243 offset:1024
	ds_read_b128 v[166:169], v0 offset:37888
	ds_read_b128 v[170:173], v0 offset:39936
	s_waitcnt lgkmcnt(8)
	v_mfma_f32_16x16x32_bf16 v[126:129], v[174:177], v[158:161], v[126:129]
	v_mfma_f32_16x16x32_bf16 v[122:125], v[174:177], v[162:165], v[122:125]
	v_add3_u32 v0, s70, v155, v153
	v_mfma_f32_16x16x32_bf16 v[110:113], v[186:189], v[158:161], v[110:113]
	v_mfma_f32_16x16x32_bf16 v[106:109], v[186:189], v[162:165], v[106:109]
	v_add3_u32 v157, s70, v155, v156
	s_waitcnt lgkmcnt(6)
	v_mfma_f32_16x16x32_bf16 v[94:97], v[190:193], v[158:161], v[94:97]
	v_mfma_f32_16x16x32_bf16 v[90:93], v[190:193], v[162:165], v[90:93]
	v_add3_u32 v238, s70, v154, v152
	v_mfma_f32_16x16x32_bf16 v[78:81], v[212:215], v[158:161], v[78:81]
	v_mfma_f32_16x16x32_bf16 v[74:77], v[212:215], v[162:165], v[74:77]
	v_add3_u32 v240, s70, v154, v149
	s_waitcnt lgkmcnt(4)
	v_mfma_f32_16x16x32_bf16 v[62:65], v[222:225], v[158:161], v[62:65]
	v_mfma_f32_16x16x32_bf16 v[58:61], v[222:225], v[162:165], v[58:61]
	v_add3_u32 v242, s70, v154, v147
	v_mfma_f32_16x16x32_bf16 v[46:49], v[226:229], v[158:161], v[46:49]
	v_mfma_f32_16x16x32_bf16 v[42:45], v[226:229], v[162:165], v[42:45]
	v_add3_u32 v207, s70, v154, v150
	s_waitcnt lgkmcnt(2)
	v_mfma_f32_16x16x32_bf16 v[30:33], v[230:233], v[158:161], v[30:33]
	v_mfma_f32_16x16x32_bf16 v[26:29], v[230:233], v[162:165], v[26:29]
	v_add3_u32 v239, s70, v154, v151
	v_mfma_f32_16x16x32_bf16 v[14:17], v[234:237], v[158:161], v[14:17]
	v_mfma_f32_16x16x32_bf16 v[10:13], v[234:237], v[162:165], v[10:13]
	v_add3_u32 v241, s70, v154, v148
	v_add3_u32 v243, s70, v154, v146
	s_waitcnt vmcnt(0) lgkmcnt(0)
	s_barrier
	s_add_u32 s0, s0, 0x80
	s_addc_u32 s1, s1, 0
	s_add_i32 s58, s58, 0x10000
	s_xor_b32 s70, s59, 0x10000
	s_cmpk_eq_i32 s0, 0x1580
	s_cbranch_scc1 .Lg80_1695_last
; #define MFMA16(a, b, c) __builtin_amdgcn_mfma_f32_16x16x32_bf16((a), (b), (c), 0, 0, 0)
; template <class Epi>
; DI void gemm8_tile(const bf16_t* __restrict__ Ab, int lda, const bf16_t* __restrict__ Bb, int ldb, int K, int brow, int bcol, const Epi epi,
;                    bool staged, bool has_next, const bf16_t* __restrict__ Abn, const bf16_t* __restrict__ Bbn) {
;     ...
;   for (int t = 0; t < nt; ++t) {
;     const int cur = t & 1;
;     const unsigned char* sa = smem + cur * G8_STAGE_B;
;     const unsigned char* sb = sa + G8_TILE_B;
; #pragma unroll
;     for (int ks = 0; ks < 2; ++ks) {
;       bf16x8 At[8], Bf[4];
;       Bf[0] = *(const bf16x8*)(sb + lds_byte2(wc * 64 + fr, ks * 32 + fq * 8));
;       At[0] = *(const bf16x8*)(sa + lds_byte2(wr * 128 + fr, ks * 32 + fq * 8));
; #pragma unroll
;       for (int n = 1; n < 4; ++n) Bf[n] = *(const bf16x8*)(sb + lds_byte2(wc * 64 + n * 16 + fr, ks * 32 + fq * 8));
; #pragma unroll
;       for (int m = 1; m < 8; ++m) At[m] = *(const bf16x8*)(sa + lds_byte2(wr * 128 + m * 16 + fr, ks * 32 + fq * 8));
;       {
;         __builtin_amdgcn_sched_barrier(0);
;         if (t + 1 < nt) { G8_STAGE_R(cur ^ 1, Ab + (t + 1) * 64, Bb + (t + 1) * 64, 2 * ks, 2 * ks + 2); }
;         else if (has_next) { G8_STAGE_R(0, Abn, Bbn, 2 * ks, 2 * ks + 2); }
;         __builtin_amdgcn_sched_barrier(0);
;       }
; #pragma unroll
;       for (int m = 0; m < 8; ++m)
; #pragma unroll
;         for (int n = 0; n < 4; ++n) acc[m][n] = MFMA16(At[m], Bf[n], acc[m][n]);
;       __builtin_amdgcn_sched_barrier(0);
;     }
;     asm volatile("s_waitcnt vmcnt(0)" ::: "memory");
;     __syncthreads();
;   }
	ds_read_b128 v[158:161], v0 offset:32768
	ds_read_b128 v[162:165], v0 offset:34816
	v_mfma_f32_16x16x32_bf16 v[118:121], v[174:177], v[166:169], v[118:121]
	v_mfma_f32_16x16x32_bf16 v[114:117], v[174:177], v[170:173], v[114:117]
	ds_read_b128 v[174:177], v157
	s_mov_b32 m0, s70
	v_lshl_add_u64 v[208:209], v[130:131], 0, s[0:1]
	global_load_lds_dwordx4 v[208:209], off
	v_mfma_f32_16x16x32_bf16 v[102:105], v[186:189], v[166:169], v[102:105]
	v_mfma_f32_16x16x32_bf16 v[98:101], v[186:189], v[170:173], v[98:101]
	ds_read_b128 v[186:189], v207
	s_add_u32 m0, s70, 0x8000
	v_lshl_add_u64 v[208:209], v[138:139], 0, s[0:1]
	global_load_lds_dwordx4 v[208:209], off
	v_mfma_f32_16x16x32_bf16 v[86:89], v[190:193], v[166:169], v[86:89]
	v_mfma_f32_16x16x32_bf16 v[82:85], v[190:193], v[170:173], v[82:85]
	ds_read_b128 v[190:193], v238
	s_add_u32 m0, s70, 0x2000
	v_lshl_add_u64 v[208:209], v[132:133], 0, s[0:1]
	global_load_lds_dwordx4 v[208:209], off
	v_mfma_f32_16x16x32_bf16 v[70:73], v[212:215], v[166:169], v[70:73]
	v_mfma_f32_16x16x32_bf16 v[66:69], v[212:215], v[170:173], v[66:69]
	ds_read_b128 v[212:215], v239
	s_add_u32 m0, s70, 0xa000
	v_lshl_add_u64 v[208:209], v[140:141], 0, s[0:1]
	global_load_lds_dwordx4 v[208:209], off
	v_mfma_f32_16x16x32_bf16 v[54:57], v[222:225], v[166:169], v[54:57]
	v_mfma_f32_16x16x32_bf16 v[50:53], v[222:225], v[170:173], v[50:53]
	ds_read_b128 v[222:225], v240
	s_add_u32 m0, s70, 0x4000
	v_lshl_add_u64 v[208:209], v[134:135], 0, s[0:1]
	global_load_lds_dwordx4 v[208:209], off
	v_mfma_f32_16x16x32_bf16 v[38:41], v[226:229], v[166:169], v[38:41]
	v_mfma_f32_16x16x32_bf16 v[34:37], v[226:229], v[170:173], v[34:37]
	ds_read_b128 v[226:229], v241
	s_add_u32 m0, s70, 0xc000
	v_lshl_add_u64 v[208:209], v[142:143], 0, s[0:1]
	global_load_lds_dwordx4 v[208:209], off
	v_mfma_f32_16x16x32_bf16 v[22:25], v[230:233], v[166:169], v[22:25]
	v_mfma_f32_16x16x32_bf16 v[18:21], v[230:233], v[170:173], v[18:21]
	ds_read_b128 v[230:233], v242
	s_add_u32 m0, s70, 0x6000
	v_lshl_add_u64 v[208:209], v[136:137], 0, s[0:1]
	global_load_lds_dwordx4 v[208:209], off
	v_mfma_f32_16x16x32_bf16 v[6:9], v[234:237], v[166:169], v[6:9]
	v_mfma_f32_16x16x32_bf16 v[2:5], v[234:237], v[170:173], v[2:5]
	ds_read_b128 v[234:237], v243
	s_add_u32 m0, s70, 0xe000
	v_lshl_add_u64 v[208:209], v[144:145], 0, s[0:1]
	global_load_lds_dwordx4 v[208:209], off
	ds_read_b128 v[166:169], v0 offset:36864
	ds_read_b128 v[170:173], v0 offset:38912
	s_branch .LBB0_1695
.Lg80_1695_last:
	ds_read_b128 v[158:161], v0 offset:32768
	ds_read_b128 v[162:165], v0 offset:34816
	v_mfma_f32_16x16x32_bf16 v[118:121], v[174:177], v[166:169], v[118:121]
	v_mfma_f32_16x16x32_bf16 v[114:117], v[174:177], v[170:173], v[114:117]
	ds_read_b128 v[174:177], v157
	v_mfma_f32_16x16x32_bf16 v[102:105], v[186:189], v[166:169], v[102:105]
	v_mfma_f32_16x16x32_bf16 v[98:101], v[186:189], v[170:173], v[98:101]
	ds_read_b128 v[186:189], v207
	v_mfma_f32_16x16x32_bf16 v[86:89], v[190:193], v[166:169], v[86:89]
	v_mfma_f32_16x16x32_bf16 v[82:85], v[190:193], v[170:173], v[82:85]
	ds_read_b128 v[190:193], v238
	v_mfma_f32_16x16x32_bf16 v[70:73], v[212:215], v[166:169], v[70:73]
	v_mfma_f32_16x16x32_bf16 v[66:69], v[212:215], v[170:173], v[66:69]
	ds_read_b128 v[212:215], v239
	v_mfma_f32_16x16x32_bf16 v[54:57], v[222:225], v[166:169], v[54:57]
	v_mfma_f32_16x16x32_bf16 v[50:53], v[222:225], v[170:173], v[50:53]
	ds_read_b128 v[222:225], v240
	v_mfma_f32_16x16x32_bf16 v[38:41], v[226:229], v[166:169], v[38:41]
	v_mfma_f32_16x16x32_bf16 v[34:37], v[226:229], v[170:173], v[34:37]
	ds_read_b128 v[226:229], v241
	v_mfma_f32_16x16x32_bf16 v[22:25], v[230:233], v[166:169], v[22:25]
	v_mfma_f32_16x16x32_bf16 v[18:21], v[230:233], v[170:173], v[18:21]
	ds_read_b128 v[230:233], v242
	v_mfma_f32_16x16x32_bf16 v[6:9], v[234:237], v[166:169], v[6:9]
	v_mfma_f32_16x16x32_bf16 v[2:5], v[234:237], v[170:173], v[2:5]
	ds_read_b128 v[234:237], v243
	ds_read_b128 v[166:169], v0 offset:36864
	ds_read_b128 v[170:173], v0 offset:38912
	s_waitcnt lgkmcnt(0)
	s_add_i32 s0, 0, 0x18000
	v_add_u32_e32 v0, s0, v155
	v_add_u32_e32 v0, v0, v153
	v_add_u32_e32 v130, s30, v155
	v_add_u32_e32 v190, v130, v156
	ds_read_b128 v[130:133], v0
	ds_read_b128 v[134:137], v0 offset:2048
	ds_read_b128 v[138:141], v0 offset:4096
	ds_read_b128 v[142:145], v0 offset:6144
	v_add_u32_e32 v174, s30, v154
	v_add_u32_e32 v192, v174, v152
	v_add_u32_e32 v207, v174, v149
	v_add_u32_e32 v209, v174, v147
	v_add_u32_e32 v191, v174, v150
	ds_read_b128 v[170:173], v190
	ds_read_b128 v[162:165], v191
	v_add_u32_e32 v193, v174, v151
	ds_read_b128 v[166:169], v192
	ds_read_b128 v[154:157], v193
	v_add_u32_e32 v208, v174, v148
	ds_read_b128 v[158:161], v207
	ds_read_b128 v[150:153], v208
	v_add_u32_e32 v212, v174, v146
	ds_read_b128 v[174:177], v209
	ds_read_b128 v[146:149], v212
	v_cndmask_b32_e64 v186, 0, 1, s[14:15]
	v_cmp_ne_u32_e64 s[0:1], 1, v186
	s_andn2_b64 vcc, exec, s[14:15]
	s_cbranch_vccnz .LBB0_1698
	v_readfirstlane_b32 s14, v185
	v_lshl_add_u64 v[188:189], s[6:7], 0, v[178:179]
	v_lshl_add_u64 v[178:179], s[4:5], 0, v[178:179]
	s_mov_b32 m0, s14
	v_readfirstlane_b32 s14, v184
	global_load_lds_dwordx4 v[178:179], off
	s_mov_b32 m0, s14
	v_readfirstlane_b32 s14, v183
	v_lshl_add_u64 v[186:187], s[6:7], 0, v[180:181]
	v_lshl_add_u64 v[180:181], s[4:5], 0, v[180:181]
	global_load_lds_dwordx4 v[188:189], off
	s_mov_b32 m0, s14
	v_readfirstlane_b32 s14, v182
	global_load_lds_dwordx4 v[180:181], off
	s_mov_b32 m0, s14
	s_nop 0
	global_load_lds_dwordx4 v[186:187], off
